# two LDS-DMA tiles in flight (split barrier) in all GEMM K loops + ctx-tile tails one block per CU
# speedup vs baseline: 1.0837x; 1.0149x over previous
.LBB0_232:
	s_mul_hi_i32 s2, s8, 0x66666667
	s_lshr_b32 s3, s2, 31
	s_ashr_i32 s2, s2, 3
	s_add_i32 s34, s2, s3
	s_ashr_i32 s35, s34, 31
	v_readlane_b32 s36, v210, 50
	v_mov_b32_e32 v36, v133
	s_lshl_b64 s[2:3], s[34:35], 18
	v_readlane_b32 s38, v210, 52
	v_readlane_b32 s39, v210, 53
	v_ashrrev_i32_e32 v34, 3, v36
	s_add_u32 s2, s38, s2
	v_ashrrev_i32_e32 v35, 31, v34
	s_addc_u32 s3, s39, s3
	v_lshlrev_b64 v[2:3], 11, v[34:35]
	s_waitcnt vmcnt(0)
	v_lshlrev_b32_e32 v0, 4, v36
	v_lshl_add_u64 v[2:3], s[2:3], 0, v[2:3]
	v_and_b32_e32 v0, 0x70, v0
	s_mul_i32 s2, s34, 0xa00
	v_lshl_add_u64 v[66:67], v[2:3], 0, v[0:1]
	v_subrev_u32_e32 v2, s2, v34
	v_add_u32_e32 v2, s7, v2
	v_ashrrev_i32_e32 v3, 31, v2
	v_lshlrev_b64 v[2:3], 11, v[2:3]
	v_lshl_add_u64 v[2:3], s[0:1], 0, v[2:3]
	v_add_co_u32_e32 v70, vcc, s56, v66
	v_lshl_add_u64 v[68:69], v[2:3], 0, v[0:1]
	s_nop 0
	v_addc_co_u32_e32 v71, vcc, 0, v67, vcc
	v_add_co_u32_e32 v72, vcc, s56, v68
	v_addc_co_u32_e32 v73, vcc, 0, v69, vcc
	v_add_co_u32_e32 v74, vcc, s57, v66
	s_nop 0
	v_addc_co_u32_e32 v75, vcc, 0, v67, vcc
	v_add_co_u32_e32 v76, vcc, s57, v68
	s_nop 0
	v_addc_co_u32_e32 v77, vcc, 0, v69, vcc
	v_add_co_u32_e32 v78, vcc, s58, v66
	s_nop 0
	v_addc_co_u32_e32 v79, vcc, 0, v67, vcc
	v_add_co_u32_e32 v80, vcc, s58, v68
	v_lshlrev_b32_e32 v0, 7, v34
	s_nop 0
	v_addc_co_u32_e32 v81, vcc, 0, v69, vcc
	v_lshrrev_b32_e32 v216, 4, v133
	v_xor_b32_e32 v216, v216, v133
	v_and_b32_e32 v216, 7, v216
	v_lshlrev_b32_e32 v216, 4, v216
	v_mov_b32_e32 v217, 0x70
	v_lshrrev_b32_e32 v218, 6, v133
	v_lshlrev_b32_e32 v218, 10, v218
	s_nop 0
	v_readfirstlane_b32 s32, v218
	v_bfi_b32 v66, v217, v216, v66
	v_bfi_b32 v70, v217, v216, v70
	v_bfi_b32 v74, v217, v216, v74
	v_bfi_b32 v78, v217, v216, v78
	v_bfi_b32 v68, v217, v216, v68
	v_bfi_b32 v72, v217, v216, v72
	v_bfi_b32 v76, v217, v216, v76
	v_bfi_b32 v80, v217, v216, v80
	s_mov_b64 s[98:99], 0x80
	s_add_u32 m0, s32, 0x0
	s_nop 0
	global_load_lds_dwordx4 v[66:67], off
	s_add_u32 m0, s32, 0x1000
	s_nop 0
	global_load_lds_dwordx4 v[70:71], off
	s_add_u32 m0, s32, 0x2000
	s_nop 0
	global_load_lds_dwordx4 v[74:75], off
	s_add_u32 m0, s32, 0x3000
	s_nop 0
	global_load_lds_dwordx4 v[78:79], off
	s_add_u32 m0, s32, 0x8000
	s_nop 0
	global_load_lds_dwordx4 v[68:69], off
	s_add_u32 m0, s32, 0x9000
	s_nop 0
	global_load_lds_dwordx4 v[72:73], off
	s_add_u32 m0, s32, 0xa000
	s_nop 0
	global_load_lds_dwordx4 v[76:77], off
	s_add_u32 m0, s32, 0xb000
	s_nop 0
	global_load_lds_dwordx4 v[80:81], off
	v_lshl_add_u64 v[66:67], v[66:67], 0, s[98:99]
	v_lshl_add_u64 v[70:71], v[70:71], 0, s[98:99]
	v_lshl_add_u64 v[74:75], v[74:75], 0, s[98:99]
	v_lshl_add_u64 v[78:79], v[78:79], 0, s[98:99]
	v_lshl_add_u64 v[68:69], v[68:69], 0, s[98:99]
	v_lshl_add_u64 v[72:73], v[72:73], 0, s[98:99]
	v_lshl_add_u64 v[76:77], v[76:77], 0, s[98:99]
	v_lshl_add_u64 v[80:81], v[80:81], 0, s[98:99]
	v_lshrrev_b32_e32 v34, 1, v34
	v_xor_b32_e32 v34, v34, v36
	v_lshlrev_b32_e32 v34, 4, v34
	v_and_or_b32 v0, v34, s59, v0
	v_and_b32_e32 v84, 31, v36
	v_bfe_u32 v82, v36, 5, 1
	v_ashrrev_i32_e32 v83, 7, v36
	v_bfe_u32 v85, v36, 6, 1
	v_readlane_b32 s40, v210, 54
	v_readlane_b32 s41, v210, 55
	v_readlane_b32 s37, v210, 51
	v_readlane_b32 s42, v210, 56
	v_readlane_b32 s43, v210, 57
	v_readlane_b32 s44, v210, 58
	v_readlane_b32 s45, v210, 59
	v_readlane_b32 s46, v210, 60
	v_readlane_b32 s47, v210, 61
	v_readlane_b32 s48, v210, 62
	v_readlane_b32 s49, v210, 63
	v_readlane_b32 s50, v209, 0
	v_readlane_b32 s51, v209, 1
	s_waitcnt lgkmcnt(0)
	s_barrier
	s_add_u32 m0, s32, 0x4000
	s_nop 0
	global_load_lds_dwordx4 v[66:67], off
	s_add_u32 m0, s32, 0x5000
	s_nop 0
	global_load_lds_dwordx4 v[70:71], off
	s_add_u32 m0, s32, 0x6000
	s_nop 0
	global_load_lds_dwordx4 v[74:75], off
	s_add_u32 m0, s32, 0x7000
	s_nop 0
	global_load_lds_dwordx4 v[78:79], off
	s_add_u32 m0, s32, 0xc000
	s_nop 0
	global_load_lds_dwordx4 v[68:69], off
	s_add_u32 m0, s32, 0xd000
	s_nop 0
	global_load_lds_dwordx4 v[72:73], off
	s_add_u32 m0, s32, 0xe000
	s_nop 0
	global_load_lds_dwordx4 v[76:77], off
	s_add_u32 m0, s32, 0xf000
	s_nop 0
	global_load_lds_dwordx4 v[80:81], off
	s_waitcnt vmcnt(8)
	s_barrier
	v_lshrrev_b32_e32 v4, 1, v36
	v_lshlrev_b32_e32 v2, 7, v84
	v_bitop3_b32 v4, v4, v82, 7 bitop3:0x6c
	v_lshl_or_b32 v3, v83, 13, v2
	v_bfe_u32 v5, v36, 1, 3
	v_lshlrev_b32_e32 v4, 4, v4
	v_lshl_or_b32 v2, v85, 13, v2
	v_or_b32_e32 v91, v3, v4
	v_or_b32_e32 v92, v2, v4
	v_bitop3_b32 v4, v82, v5, 2 bitop3:0x36
	v_lshlrev_b32_e32 v4, 4, v4
	v_or_b32_e32 v93, v3, v4
	v_or_b32_e32 v90, v2, v4
	v_bitop3_b32 v4, v82, v5, 4 bitop3:0x36
	v_lshlrev_b32_e32 v4, 4, v4
	v_or_b32_e32 v89, v3, v4
	v_or_b32_e32 v88, v2, v4
	v_bitop3_b32 v4, v82, v5, 6 bitop3:0x36
	v_lshlrev_b32_e32 v4, 4, v4
	v_or_b32_e32 v87, v3, v4
	v_or_b32_e32 v86, v2, v4
	ds_read_b128 v[2:5], v91
	ds_read_b128 v[6:9], v92 offset:32768
	ds_read_b128 v[10:13], v91 offset:4096
	ds_read_b128 v[14:17], v92 offset:36864
	ds_read_b128 v[162:165], v93
	ds_read_b128 v[166:169], v90 offset:32768
	ds_read_b128 v[182:185], v93 offset:4096
	ds_read_b128 v[186:189], v90 offset:36864
	s_waitcnt lgkmcnt(6)
	v_mfma_f32_32x32x16_bf16 v[50:65], v[2:5], v[6:9], 0
	s_waitcnt lgkmcnt(4)
	v_mfma_f32_32x32x16_bf16 v[34:49], v[2:5], v[14:17], 0
	v_mfma_f32_32x32x16_bf16 v[18:33], v[10:13], v[6:9], 0
	v_mfma_f32_32x32x16_bf16 v[2:17], v[10:13], v[14:17], 0
	ds_read_b128 v[190:193], v89
	ds_read_b128 v[194:197], v89 offset:4096
	ds_read_b128 v[198:201], v88 offset:32768
	ds_read_b128 v[202:205], v88 offset:36864
	s_waitcnt lgkmcnt(6)
	v_mfma_f32_32x32x16_bf16 v[50:65], v[162:165], v[166:169], v[50:65]
	s_waitcnt lgkmcnt(4)
	v_mfma_f32_32x32x16_bf16 v[34:49], v[162:165], v[186:189], v[34:49]
	v_mfma_f32_32x32x16_bf16 v[18:33], v[182:185], v[166:169], v[18:33]
	v_mfma_f32_32x32x16_bf16 v[2:17], v[182:185], v[186:189], v[2:17]
	ds_read_b128 v[162:165], v87
	ds_read_b128 v[166:169], v87 offset:4096
	ds_read_b128 v[182:185], v86 offset:32768
	ds_read_b128 v[186:189], v86 offset:36864
	v_lshl_add_u64 v[66:67], v[66:67], 0, s[98:99]
	v_lshl_add_u64 v[70:71], v[70:71], 0, s[98:99]
	v_lshl_add_u64 v[74:75], v[74:75], 0, s[98:99]
	v_lshl_add_u64 v[78:79], v[78:79], 0, s[98:99]
	v_lshl_add_u64 v[68:69], v[68:69], 0, s[98:99]
	v_lshl_add_u64 v[72:73], v[72:73], 0, s[98:99]
	v_lshl_add_u64 v[76:77], v[76:77], 0, s[98:99]
	v_lshl_add_u64 v[80:81], v[80:81], 0, s[98:99]
	s_waitcnt lgkmcnt(0)
	s_barrier
	s_add_u32 m0, s32, 0x0
	v_mfma_f32_32x32x16_bf16 v[50:65], v[190:193], v[198:201], v[50:65]
	global_load_lds_dwordx4 v[66:67], off
	s_add_u32 m0, s32, 0x1000
	v_mfma_f32_32x32x16_bf16 v[34:49], v[190:193], v[202:205], v[34:49]
	global_load_lds_dwordx4 v[70:71], off
	s_add_u32 m0, s32, 0x2000
	v_mfma_f32_32x32x16_bf16 v[18:33], v[194:197], v[198:201], v[18:33]
	global_load_lds_dwordx4 v[74:75], off
	s_add_u32 m0, s32, 0x3000
	v_mfma_f32_32x32x16_bf16 v[2:17], v[194:197], v[202:205], v[2:17]
	global_load_lds_dwordx4 v[78:79], off
	s_add_u32 m0, s32, 0x8000
	v_mfma_f32_32x32x16_bf16 v[50:65], v[162:165], v[182:185], v[50:65]
	global_load_lds_dwordx4 v[68:69], off
	s_add_u32 m0, s32, 0x9000
	v_mfma_f32_32x32x16_bf16 v[34:49], v[162:165], v[186:189], v[34:49]
	global_load_lds_dwordx4 v[72:73], off
	s_add_u32 m0, s32, 0xa000
	v_mfma_f32_32x32x16_bf16 v[18:33], v[166:169], v[182:185], v[18:33]
	global_load_lds_dwordx4 v[76:77], off
	s_add_u32 m0, s32, 0xb000
	v_mfma_f32_32x32x16_bf16 v[2:17], v[166:169], v[186:189], v[2:17]
	global_load_lds_dwordx4 v[80:81], off
	s_waitcnt vmcnt(8)
	s_barrier
	ds_read_b128 v[162:165], v91 offset:16384
	ds_read_b128 v[166:169], v92 offset:49152
	ds_read_b128 v[182:185], v91 offset:20480
	ds_read_b128 v[186:189], v92 offset:53248
	ds_read_b128 v[190:193], v93 offset:16384
	ds_read_b128 v[194:197], v90 offset:49152
	ds_read_b128 v[198:201], v93 offset:20480
	ds_read_b128 v[202:205], v90 offset:53248
	s_waitcnt lgkmcnt(6)
	v_mfma_f32_32x32x16_bf16 v[50:65], v[162:165], v[166:169], v[50:65]
	s_waitcnt lgkmcnt(4)
	v_mfma_f32_32x32x16_bf16 v[34:49], v[162:165], v[186:189], v[34:49]
	v_mfma_f32_32x32x16_bf16 v[18:33], v[182:185], v[166:169], v[18:33]
	v_mfma_f32_32x32x16_bf16 v[2:17], v[182:185], v[186:189], v[2:17]
	ds_read_b128 v[162:165], v89 offset:16384
	ds_read_b128 v[166:169], v89 offset:20480
	ds_read_b128 v[182:185], v88 offset:49152
	ds_read_b128 v[186:189], v88 offset:53248
	s_waitcnt lgkmcnt(6)
	v_mfma_f32_32x32x16_bf16 v[50:65], v[190:193], v[194:197], v[50:65]
	s_waitcnt lgkmcnt(4)
	v_mfma_f32_32x32x16_bf16 v[34:49], v[190:193], v[202:205], v[34:49]
	v_mfma_f32_32x32x16_bf16 v[18:33], v[198:201], v[194:197], v[18:33]
	v_mfma_f32_32x32x16_bf16 v[2:17], v[198:201], v[202:205], v[2:17]
	ds_read_b128 v[190:193], v87 offset:16384
	ds_read_b128 v[194:197], v87 offset:20480
	ds_read_b128 v[198:201], v86 offset:49152
	ds_read_b128 v[202:205], v86 offset:53248
	v_lshl_add_u64 v[66:67], v[66:67], 0, s[98:99]
	v_lshl_add_u64 v[70:71], v[70:71], 0, s[98:99]
	v_lshl_add_u64 v[74:75], v[74:75], 0, s[98:99]
	v_lshl_add_u64 v[78:79], v[78:79], 0, s[98:99]
	v_lshl_add_u64 v[68:69], v[68:69], 0, s[98:99]
	v_lshl_add_u64 v[72:73], v[72:73], 0, s[98:99]
	v_lshl_add_u64 v[76:77], v[76:77], 0, s[98:99]
	v_lshl_add_u64 v[80:81], v[80:81], 0, s[98:99]
	s_waitcnt lgkmcnt(0)
	s_barrier
	s_add_u32 m0, s32, 0x4000
	v_mfma_f32_32x32x16_bf16 v[50:65], v[162:165], v[182:185], v[50:65]
	global_load_lds_dwordx4 v[66:67], off
	s_add_u32 m0, s32, 0x5000
	v_mfma_f32_32x32x16_bf16 v[34:49], v[162:165], v[186:189], v[34:49]
	global_load_lds_dwordx4 v[70:71], off
	s_add_u32 m0, s32, 0x6000
	v_mfma_f32_32x32x16_bf16 v[18:33], v[166:169], v[182:185], v[18:33]
	global_load_lds_dwordx4 v[74:75], off
	s_add_u32 m0, s32, 0x7000
	v_mfma_f32_32x32x16_bf16 v[2:17], v[166:169], v[186:189], v[2:17]
	global_load_lds_dwordx4 v[78:79], off
	s_add_u32 m0, s32, 0xc000
	v_mfma_f32_32x32x16_bf16 v[50:65], v[190:193], v[198:201], v[50:65]
	global_load_lds_dwordx4 v[68:69], off
	s_add_u32 m0, s32, 0xd000
	v_mfma_f32_32x32x16_bf16 v[34:49], v[190:193], v[202:205], v[34:49]
	global_load_lds_dwordx4 v[72:73], off
	s_add_u32 m0, s32, 0xe000
	v_mfma_f32_32x32x16_bf16 v[18:33], v[194:197], v[198:201], v[18:33]
	global_load_lds_dwordx4 v[76:77], off
	s_add_u32 m0, s32, 0xf000
	v_mfma_f32_32x32x16_bf16 v[2:17], v[194:197], v[202:205], v[2:17]
	global_load_lds_dwordx4 v[80:81], off
	s_waitcnt vmcnt(8)
	s_barrier
	ds_read_b128 v[162:165], v91
	ds_read_b128 v[166:169], v92 offset:32768
	ds_read_b128 v[182:185], v91 offset:4096
	ds_read_b128 v[186:189], v92 offset:36864
	ds_read_b128 v[190:193], v93
	ds_read_b128 v[194:197], v90 offset:32768
	ds_read_b128 v[198:201], v93 offset:4096
	ds_read_b128 v[202:205], v90 offset:36864
	s_waitcnt lgkmcnt(6)
	v_mfma_f32_32x32x16_bf16 v[50:65], v[162:165], v[166:169], v[50:65]
	s_waitcnt lgkmcnt(4)
	v_mfma_f32_32x32x16_bf16 v[34:49], v[162:165], v[186:189], v[34:49]
	v_mfma_f32_32x32x16_bf16 v[18:33], v[182:185], v[166:169], v[18:33]
	v_mfma_f32_32x32x16_bf16 v[2:17], v[182:185], v[186:189], v[2:17]
	ds_read_b128 v[162:165], v89
	ds_read_b128 v[166:169], v89 offset:4096
	ds_read_b128 v[182:185], v88 offset:32768
	ds_read_b128 v[186:189], v88 offset:36864
	s_waitcnt lgkmcnt(6)
	v_mfma_f32_32x32x16_bf16 v[50:65], v[190:193], v[194:197], v[50:65]
	s_waitcnt lgkmcnt(4)
	v_mfma_f32_32x32x16_bf16 v[34:49], v[190:193], v[202:205], v[34:49]
	v_mfma_f32_32x32x16_bf16 v[18:33], v[198:201], v[194:197], v[18:33]
	v_mfma_f32_32x32x16_bf16 v[2:17], v[198:201], v[202:205], v[2:17]
	ds_read_b128 v[190:193], v87
	ds_read_b128 v[194:197], v87 offset:4096
	ds_read_b128 v[198:201], v86 offset:32768
	ds_read_b128 v[202:205], v86 offset:36864
	v_lshl_add_u64 v[66:67], v[66:67], 0, s[98:99]
	v_lshl_add_u64 v[70:71], v[70:71], 0, s[98:99]
	v_lshl_add_u64 v[74:75], v[74:75], 0, s[98:99]
	v_lshl_add_u64 v[78:79], v[78:79], 0, s[98:99]
	v_lshl_add_u64 v[68:69], v[68:69], 0, s[98:99]
	v_lshl_add_u64 v[72:73], v[72:73], 0, s[98:99]
	v_lshl_add_u64 v[76:77], v[76:77], 0, s[98:99]
	v_lshl_add_u64 v[80:81], v[80:81], 0, s[98:99]
	s_waitcnt lgkmcnt(0)
	s_barrier
	s_add_u32 m0, s32, 0x0
	v_mfma_f32_32x32x16_bf16 v[50:65], v[162:165], v[182:185], v[50:65]
	global_load_lds_dwordx4 v[66:67], off
	s_add_u32 m0, s32, 0x1000
	v_mfma_f32_32x32x16_bf16 v[34:49], v[162:165], v[186:189], v[34:49]
	global_load_lds_dwordx4 v[70:71], off
	s_add_u32 m0, s32, 0x2000
	v_mfma_f32_32x32x16_bf16 v[18:33], v[166:169], v[182:185], v[18:33]
	global_load_lds_dwordx4 v[74:75], off
	s_add_u32 m0, s32, 0x3000
	v_mfma_f32_32x32x16_bf16 v[2:17], v[166:169], v[186:189], v[2:17]
	global_load_lds_dwordx4 v[78:79], off
	s_add_u32 m0, s32, 0x8000
	v_mfma_f32_32x32x16_bf16 v[50:65], v[190:193], v[198:201], v[50:65]
	global_load_lds_dwordx4 v[68:69], off
	s_add_u32 m0, s32, 0x9000
	v_mfma_f32_32x32x16_bf16 v[34:49], v[190:193], v[202:205], v[34:49]
	global_load_lds_dwordx4 v[72:73], off
	s_add_u32 m0, s32, 0xa000
	v_mfma_f32_32x32x16_bf16 v[18:33], v[194:197], v[198:201], v[18:33]
	global_load_lds_dwordx4 v[76:77], off
	s_add_u32 m0, s32, 0xb000
	v_mfma_f32_32x32x16_bf16 v[2:17], v[194:197], v[202:205], v[2:17]
	global_load_lds_dwordx4 v[80:81], off
	s_waitcnt vmcnt(8)
	s_barrier
	ds_read_b128 v[162:165], v91 offset:16384
	ds_read_b128 v[166:169], v92 offset:49152
	ds_read_b128 v[182:185], v91 offset:20480
	ds_read_b128 v[186:189], v92 offset:53248
	ds_read_b128 v[190:193], v93 offset:16384
	ds_read_b128 v[194:197], v90 offset:49152
	ds_read_b128 v[198:201], v93 offset:20480
	ds_read_b128 v[202:205], v90 offset:53248
	s_waitcnt lgkmcnt(6)
	v_mfma_f32_32x32x16_bf16 v[50:65], v[162:165], v[166:169], v[50:65]
	s_waitcnt lgkmcnt(4)
	v_mfma_f32_32x32x16_bf16 v[34:49], v[162:165], v[186:189], v[34:49]
	v_mfma_f32_32x32x16_bf16 v[18:33], v[182:185], v[166:169], v[18:33]
	v_mfma_f32_32x32x16_bf16 v[2:17], v[182:185], v[186:189], v[2:17]
	ds_read_b128 v[162:165], v89 offset:16384
	ds_read_b128 v[166:169], v89 offset:20480
	ds_read_b128 v[182:185], v88 offset:49152
	ds_read_b128 v[186:189], v88 offset:53248
	s_waitcnt lgkmcnt(6)
	v_mfma_f32_32x32x16_bf16 v[50:65], v[190:193], v[194:197], v[50:65]
	s_waitcnt lgkmcnt(4)
	v_mfma_f32_32x32x16_bf16 v[34:49], v[190:193], v[202:205], v[34:49]
	v_mfma_f32_32x32x16_bf16 v[18:33], v[198:201], v[194:197], v[18:33]
	v_mfma_f32_32x32x16_bf16 v[2:17], v[198:201], v[202:205], v[2:17]
	ds_read_b128 v[190:193], v87 offset:16384
	ds_read_b128 v[194:197], v87 offset:20480
	ds_read_b128 v[198:201], v86 offset:49152
	ds_read_b128 v[202:205], v86 offset:53248
	v_lshl_add_u64 v[66:67], v[66:67], 0, s[98:99]
	v_lshl_add_u64 v[70:71], v[70:71], 0, s[98:99]
	v_lshl_add_u64 v[74:75], v[74:75], 0, s[98:99]
	v_lshl_add_u64 v[78:79], v[78:79], 0, s[98:99]
	v_lshl_add_u64 v[68:69], v[68:69], 0, s[98:99]
	v_lshl_add_u64 v[72:73], v[72:73], 0, s[98:99]
	v_lshl_add_u64 v[76:77], v[76:77], 0, s[98:99]
	v_lshl_add_u64 v[80:81], v[80:81], 0, s[98:99]
	s_waitcnt lgkmcnt(0)
	s_barrier
	s_add_u32 m0, s32, 0x4000
	v_mfma_f32_32x32x16_bf16 v[50:65], v[162:165], v[182:185], v[50:65]
	global_load_lds_dwordx4 v[66:67], off
	s_add_u32 m0, s32, 0x5000
	v_mfma_f32_32x32x16_bf16 v[34:49], v[162:165], v[186:189], v[34:49]
	global_load_lds_dwordx4 v[70:71], off
	s_add_u32 m0, s32, 0x6000
	v_mfma_f32_32x32x16_bf16 v[18:33], v[166:169], v[182:185], v[18:33]
	global_load_lds_dwordx4 v[74:75], off
	s_add_u32 m0, s32, 0x7000
	v_mfma_f32_32x32x16_bf16 v[2:17], v[166:169], v[186:189], v[2:17]
	global_load_lds_dwordx4 v[78:79], off
	s_add_u32 m0, s32, 0xc000
	v_mfma_f32_32x32x16_bf16 v[50:65], v[190:193], v[198:201], v[50:65]
	global_load_lds_dwordx4 v[68:69], off
	s_add_u32 m0, s32, 0xd000
	v_mfma_f32_32x32x16_bf16 v[34:49], v[190:193], v[202:205], v[34:49]
	global_load_lds_dwordx4 v[72:73], off
	s_add_u32 m0, s32, 0xe000
	v_mfma_f32_32x32x16_bf16 v[18:33], v[194:197], v[198:201], v[18:33]
	global_load_lds_dwordx4 v[76:77], off
	s_add_u32 m0, s32, 0xf000
	v_mfma_f32_32x32x16_bf16 v[2:17], v[194:197], v[202:205], v[2:17]
	global_load_lds_dwordx4 v[80:81], off
	s_waitcnt vmcnt(8)
	s_barrier
	ds_read_b128 v[162:165], v91
	ds_read_b128 v[166:169], v92 offset:32768
	ds_read_b128 v[182:185], v91 offset:4096
	ds_read_b128 v[186:189], v92 offset:36864
	ds_read_b128 v[190:193], v93
	ds_read_b128 v[194:197], v90 offset:32768
	ds_read_b128 v[198:201], v93 offset:4096
	ds_read_b128 v[202:205], v90 offset:36864
	s_waitcnt lgkmcnt(6)
	v_mfma_f32_32x32x16_bf16 v[50:65], v[162:165], v[166:169], v[50:65]
	s_waitcnt lgkmcnt(4)
	v_mfma_f32_32x32x16_bf16 v[34:49], v[162:165], v[186:189], v[34:49]
	v_mfma_f32_32x32x16_bf16 v[18:33], v[182:185], v[166:169], v[18:33]
	v_mfma_f32_32x32x16_bf16 v[2:17], v[182:185], v[186:189], v[2:17]
	ds_read_b128 v[162:165], v89
	ds_read_b128 v[166:169], v89 offset:4096
	ds_read_b128 v[182:185], v88 offset:32768
	ds_read_b128 v[186:189], v88 offset:36864
	s_waitcnt lgkmcnt(6)
	v_mfma_f32_32x32x16_bf16 v[50:65], v[190:193], v[194:197], v[50:65]
	s_waitcnt lgkmcnt(4)
	v_mfma_f32_32x32x16_bf16 v[34:49], v[190:193], v[202:205], v[34:49]
	v_mfma_f32_32x32x16_bf16 v[18:33], v[198:201], v[194:197], v[18:33]
	v_mfma_f32_32x32x16_bf16 v[2:17], v[198:201], v[202:205], v[2:17]
	ds_read_b128 v[190:193], v87
	ds_read_b128 v[194:197], v87 offset:4096
	ds_read_b128 v[198:201], v86 offset:32768
	ds_read_b128 v[202:205], v86 offset:36864
	v_lshl_add_u64 v[66:67], v[66:67], 0, s[98:99]
	v_lshl_add_u64 v[70:71], v[70:71], 0, s[98:99]
	v_lshl_add_u64 v[74:75], v[74:75], 0, s[98:99]
	v_lshl_add_u64 v[78:79], v[78:79], 0, s[98:99]
	v_lshl_add_u64 v[68:69], v[68:69], 0, s[98:99]
	v_lshl_add_u64 v[72:73], v[72:73], 0, s[98:99]
	v_lshl_add_u64 v[76:77], v[76:77], 0, s[98:99]
	v_lshl_add_u64 v[80:81], v[80:81], 0, s[98:99]
	s_waitcnt lgkmcnt(0)
	s_barrier
	s_add_u32 m0, s32, 0x0
	v_mfma_f32_32x32x16_bf16 v[50:65], v[162:165], v[182:185], v[50:65]
	global_load_lds_dwordx4 v[66:67], off
	s_add_u32 m0, s32, 0x1000
	v_mfma_f32_32x32x16_bf16 v[34:49], v[162:165], v[186:189], v[34:49]
	global_load_lds_dwordx4 v[70:71], off
	s_add_u32 m0, s32, 0x2000
	v_mfma_f32_32x32x16_bf16 v[18:33], v[166:169], v[182:185], v[18:33]
	global_load_lds_dwordx4 v[74:75], off
	s_add_u32 m0, s32, 0x3000
	v_mfma_f32_32x32x16_bf16 v[2:17], v[166:169], v[186:189], v[2:17]
	global_load_lds_dwordx4 v[78:79], off
	s_add_u32 m0, s32, 0x8000
	v_mfma_f32_32x32x16_bf16 v[50:65], v[190:193], v[198:201], v[50:65]
	global_load_lds_dwordx4 v[68:69], off
	s_add_u32 m0, s32, 0x9000
	v_mfma_f32_32x32x16_bf16 v[34:49], v[190:193], v[202:205], v[34:49]
	global_load_lds_dwordx4 v[72:73], off
	s_add_u32 m0, s32, 0xa000
	v_mfma_f32_32x32x16_bf16 v[18:33], v[194:197], v[198:201], v[18:33]
	global_load_lds_dwordx4 v[76:77], off
	s_add_u32 m0, s32, 0xb000
	v_mfma_f32_32x32x16_bf16 v[2:17], v[194:197], v[202:205], v[2:17]
	global_load_lds_dwordx4 v[80:81], off
	s_waitcnt vmcnt(8)
	s_barrier
	ds_read_b128 v[162:165], v91 offset:16384
	ds_read_b128 v[166:169], v92 offset:49152
	ds_read_b128 v[182:185], v91 offset:20480
	ds_read_b128 v[186:189], v92 offset:53248
	ds_read_b128 v[190:193], v93 offset:16384
	ds_read_b128 v[194:197], v90 offset:49152
	ds_read_b128 v[198:201], v93 offset:20480
	ds_read_b128 v[202:205], v90 offset:53248
	s_waitcnt lgkmcnt(6)
	v_mfma_f32_32x32x16_bf16 v[50:65], v[162:165], v[166:169], v[50:65]
	s_waitcnt lgkmcnt(4)
	v_mfma_f32_32x32x16_bf16 v[34:49], v[162:165], v[186:189], v[34:49]
	v_mfma_f32_32x32x16_bf16 v[18:33], v[182:185], v[166:169], v[18:33]
	v_mfma_f32_32x32x16_bf16 v[2:17], v[182:185], v[186:189], v[2:17]
	ds_read_b128 v[162:165], v89 offset:16384
	ds_read_b128 v[166:169], v89 offset:20480
	ds_read_b128 v[182:185], v88 offset:49152
	ds_read_b128 v[186:189], v88 offset:53248
	s_waitcnt lgkmcnt(6)
	v_mfma_f32_32x32x16_bf16 v[50:65], v[190:193], v[194:197], v[50:65]
	s_waitcnt lgkmcnt(4)
	v_mfma_f32_32x32x16_bf16 v[34:49], v[190:193], v[202:205], v[34:49]
	v_mfma_f32_32x32x16_bf16 v[18:33], v[198:201], v[194:197], v[18:33]
	v_mfma_f32_32x32x16_bf16 v[2:17], v[198:201], v[202:205], v[2:17]
	ds_read_b128 v[190:193], v87 offset:16384
	ds_read_b128 v[194:197], v87 offset:20480
	ds_read_b128 v[198:201], v86 offset:49152
	ds_read_b128 v[202:205], v86 offset:53248
	v_lshl_add_u64 v[66:67], v[66:67], 0, s[98:99]
	v_lshl_add_u64 v[70:71], v[70:71], 0, s[98:99]
	v_lshl_add_u64 v[74:75], v[74:75], 0, s[98:99]
	v_lshl_add_u64 v[78:79], v[78:79], 0, s[98:99]
	v_lshl_add_u64 v[68:69], v[68:69], 0, s[98:99]
	v_lshl_add_u64 v[72:73], v[72:73], 0, s[98:99]
	v_lshl_add_u64 v[76:77], v[76:77], 0, s[98:99]
	v_lshl_add_u64 v[80:81], v[80:81], 0, s[98:99]
	s_waitcnt lgkmcnt(0)
	s_barrier
	s_add_u32 m0, s32, 0x4000
	v_mfma_f32_32x32x16_bf16 v[50:65], v[162:165], v[182:185], v[50:65]
	global_load_lds_dwordx4 v[66:67], off
	s_add_u32 m0, s32, 0x5000
	v_mfma_f32_32x32x16_bf16 v[34:49], v[162:165], v[186:189], v[34:49]
	global_load_lds_dwordx4 v[70:71], off
	s_add_u32 m0, s32, 0x6000
	v_mfma_f32_32x32x16_bf16 v[18:33], v[166:169], v[182:185], v[18:33]
	global_load_lds_dwordx4 v[74:75], off
	s_add_u32 m0, s32, 0x7000
	v_mfma_f32_32x32x16_bf16 v[2:17], v[166:169], v[186:189], v[2:17]
	global_load_lds_dwordx4 v[78:79], off
	s_add_u32 m0, s32, 0xc000
	v_mfma_f32_32x32x16_bf16 v[50:65], v[190:193], v[198:201], v[50:65]
	global_load_lds_dwordx4 v[68:69], off
	s_add_u32 m0, s32, 0xd000
	v_mfma_f32_32x32x16_bf16 v[34:49], v[190:193], v[202:205], v[34:49]
	global_load_lds_dwordx4 v[72:73], off
	s_add_u32 m0, s32, 0xe000
	v_mfma_f32_32x32x16_bf16 v[18:33], v[194:197], v[198:201], v[18:33]
	global_load_lds_dwordx4 v[76:77], off
	s_add_u32 m0, s32, 0xf000
	v_mfma_f32_32x32x16_bf16 v[2:17], v[194:197], v[202:205], v[2:17]
	global_load_lds_dwordx4 v[80:81], off
	s_waitcnt vmcnt(8)
	s_barrier
	ds_read_b128 v[162:165], v91
	ds_read_b128 v[166:169], v92 offset:32768
	ds_read_b128 v[182:185], v91 offset:4096
	ds_read_b128 v[186:189], v92 offset:36864
	ds_read_b128 v[190:193], v93
	ds_read_b128 v[194:197], v90 offset:32768
	ds_read_b128 v[198:201], v93 offset:4096
	ds_read_b128 v[202:205], v90 offset:36864
	s_waitcnt lgkmcnt(6)
	v_mfma_f32_32x32x16_bf16 v[50:65], v[162:165], v[166:169], v[50:65]
	s_waitcnt lgkmcnt(4)
	v_mfma_f32_32x32x16_bf16 v[34:49], v[162:165], v[186:189], v[34:49]
	v_mfma_f32_32x32x16_bf16 v[18:33], v[182:185], v[166:169], v[18:33]
	v_mfma_f32_32x32x16_bf16 v[2:17], v[182:185], v[186:189], v[2:17]
	ds_read_b128 v[162:165], v89
	ds_read_b128 v[166:169], v89 offset:4096
	ds_read_b128 v[182:185], v88 offset:32768
	ds_read_b128 v[186:189], v88 offset:36864
	s_waitcnt lgkmcnt(6)
	v_mfma_f32_32x32x16_bf16 v[50:65], v[190:193], v[194:197], v[50:65]
	s_waitcnt lgkmcnt(4)
	v_mfma_f32_32x32x16_bf16 v[34:49], v[190:193], v[202:205], v[34:49]
	v_mfma_f32_32x32x16_bf16 v[18:33], v[198:201], v[194:197], v[18:33]
	v_mfma_f32_32x32x16_bf16 v[2:17], v[198:201], v[202:205], v[2:17]
	ds_read_b128 v[190:193], v87
	ds_read_b128 v[194:197], v87 offset:4096
	ds_read_b128 v[198:201], v86 offset:32768
	ds_read_b128 v[202:205], v86 offset:36864
	v_lshl_add_u64 v[66:67], v[66:67], 0, s[98:99]
	v_lshl_add_u64 v[70:71], v[70:71], 0, s[98:99]
	v_lshl_add_u64 v[74:75], v[74:75], 0, s[98:99]
	v_lshl_add_u64 v[78:79], v[78:79], 0, s[98:99]
	v_lshl_add_u64 v[68:69], v[68:69], 0, s[98:99]
	v_lshl_add_u64 v[72:73], v[72:73], 0, s[98:99]
	v_lshl_add_u64 v[76:77], v[76:77], 0, s[98:99]
	v_lshl_add_u64 v[80:81], v[80:81], 0, s[98:99]
	s_waitcnt lgkmcnt(0)
	s_barrier
	s_add_u32 m0, s32, 0x0
	v_mfma_f32_32x32x16_bf16 v[50:65], v[162:165], v[182:185], v[50:65]
	global_load_lds_dwordx4 v[66:67], off
	s_add_u32 m0, s32, 0x1000
	v_mfma_f32_32x32x16_bf16 v[34:49], v[162:165], v[186:189], v[34:49]
	global_load_lds_dwordx4 v[70:71], off
	s_add_u32 m0, s32, 0x2000
	v_mfma_f32_32x32x16_bf16 v[18:33], v[166:169], v[182:185], v[18:33]
	global_load_lds_dwordx4 v[74:75], off
	s_add_u32 m0, s32, 0x3000
	v_mfma_f32_32x32x16_bf16 v[2:17], v[166:169], v[186:189], v[2:17]
	global_load_lds_dwordx4 v[78:79], off
	s_add_u32 m0, s32, 0x8000
	v_mfma_f32_32x32x16_bf16 v[50:65], v[190:193], v[198:201], v[50:65]
	global_load_lds_dwordx4 v[68:69], off
	s_add_u32 m0, s32, 0x9000
	v_mfma_f32_32x32x16_bf16 v[34:49], v[190:193], v[202:205], v[34:49]
	global_load_lds_dwordx4 v[72:73], off
	s_add_u32 m0, s32, 0xa000
	v_mfma_f32_32x32x16_bf16 v[18:33], v[194:197], v[198:201], v[18:33]
	global_load_lds_dwordx4 v[76:77], off
	s_add_u32 m0, s32, 0xb000
	v_mfma_f32_32x32x16_bf16 v[2:17], v[194:197], v[202:205], v[2:17]
	global_load_lds_dwordx4 v[80:81], off
	s_waitcnt vmcnt(8)
	s_barrier
	ds_read_b128 v[162:165], v91 offset:16384
	ds_read_b128 v[166:169], v92 offset:49152
	ds_read_b128 v[182:185], v91 offset:20480
	ds_read_b128 v[186:189], v92 offset:53248
	ds_read_b128 v[190:193], v93 offset:16384
	ds_read_b128 v[194:197], v90 offset:49152
	ds_read_b128 v[198:201], v93 offset:20480
	ds_read_b128 v[202:205], v90 offset:53248
	s_waitcnt lgkmcnt(6)
	v_mfma_f32_32x32x16_bf16 v[50:65], v[162:165], v[166:169], v[50:65]
	s_waitcnt lgkmcnt(4)
	v_mfma_f32_32x32x16_bf16 v[34:49], v[162:165], v[186:189], v[34:49]
	v_mfma_f32_32x32x16_bf16 v[18:33], v[182:185], v[166:169], v[18:33]
	v_mfma_f32_32x32x16_bf16 v[2:17], v[182:185], v[186:189], v[2:17]
	ds_read_b128 v[162:165], v89 offset:16384
	ds_read_b128 v[166:169], v89 offset:20480
	ds_read_b128 v[182:185], v88 offset:49152
	ds_read_b128 v[186:189], v88 offset:53248
	s_waitcnt lgkmcnt(6)
	v_mfma_f32_32x32x16_bf16 v[50:65], v[190:193], v[194:197], v[50:65]
	s_waitcnt lgkmcnt(4)
	v_mfma_f32_32x32x16_bf16 v[34:49], v[190:193], v[202:205], v[34:49]
	v_mfma_f32_32x32x16_bf16 v[18:33], v[198:201], v[194:197], v[18:33]
	v_mfma_f32_32x32x16_bf16 v[2:17], v[198:201], v[202:205], v[2:17]
	ds_read_b128 v[190:193], v87 offset:16384
	ds_read_b128 v[194:197], v87 offset:20480
	ds_read_b128 v[198:201], v86 offset:49152
	ds_read_b128 v[202:205], v86 offset:53248
	v_lshl_add_u64 v[66:67], v[66:67], 0, s[98:99]
	v_lshl_add_u64 v[70:71], v[70:71], 0, s[98:99]
	v_lshl_add_u64 v[74:75], v[74:75], 0, s[98:99]
	v_lshl_add_u64 v[78:79], v[78:79], 0, s[98:99]
	v_lshl_add_u64 v[68:69], v[68:69], 0, s[98:99]
	v_lshl_add_u64 v[72:73], v[72:73], 0, s[98:99]
	v_lshl_add_u64 v[76:77], v[76:77], 0, s[98:99]
	v_lshl_add_u64 v[80:81], v[80:81], 0, s[98:99]
	s_waitcnt lgkmcnt(0)
	s_barrier
	s_add_u32 m0, s32, 0x4000
	v_mfma_f32_32x32x16_bf16 v[50:65], v[162:165], v[182:185], v[50:65]
	global_load_lds_dwordx4 v[66:67], off
	s_add_u32 m0, s32, 0x5000
	v_mfma_f32_32x32x16_bf16 v[34:49], v[162:165], v[186:189], v[34:49]
	global_load_lds_dwordx4 v[70:71], off
	s_add_u32 m0, s32, 0x6000
	v_mfma_f32_32x32x16_bf16 v[18:33], v[166:169], v[182:185], v[18:33]
	global_load_lds_dwordx4 v[74:75], off
	s_add_u32 m0, s32, 0x7000
	v_mfma_f32_32x32x16_bf16 v[2:17], v[166:169], v[186:189], v[2:17]
	global_load_lds_dwordx4 v[78:79], off
	s_add_u32 m0, s32, 0xc000
	v_mfma_f32_32x32x16_bf16 v[50:65], v[190:193], v[198:201], v[50:65]
	global_load_lds_dwordx4 v[68:69], off
	s_add_u32 m0, s32, 0xd000
	v_mfma_f32_32x32x16_bf16 v[34:49], v[190:193], v[202:205], v[34:49]
	global_load_lds_dwordx4 v[72:73], off
	s_add_u32 m0, s32, 0xe000
	v_mfma_f32_32x32x16_bf16 v[18:33], v[194:197], v[198:201], v[18:33]
	global_load_lds_dwordx4 v[76:77], off
	s_add_u32 m0, s32, 0xf000
	v_mfma_f32_32x32x16_bf16 v[2:17], v[194:197], v[202:205], v[2:17]
	global_load_lds_dwordx4 v[80:81], off
	s_waitcnt vmcnt(8)
	s_barrier
	ds_read_b128 v[162:165], v91
	ds_read_b128 v[166:169], v92 offset:32768
	ds_read_b128 v[182:185], v91 offset:4096
	ds_read_b128 v[186:189], v92 offset:36864
	ds_read_b128 v[190:193], v93
	ds_read_b128 v[194:197], v90 offset:32768
	ds_read_b128 v[198:201], v93 offset:4096
	ds_read_b128 v[202:205], v90 offset:36864
	s_waitcnt lgkmcnt(6)
	v_mfma_f32_32x32x16_bf16 v[50:65], v[162:165], v[166:169], v[50:65]
	s_waitcnt lgkmcnt(4)
	v_mfma_f32_32x32x16_bf16 v[34:49], v[162:165], v[186:189], v[34:49]
	v_mfma_f32_32x32x16_bf16 v[18:33], v[182:185], v[166:169], v[18:33]
	v_mfma_f32_32x32x16_bf16 v[2:17], v[182:185], v[186:189], v[2:17]
	ds_read_b128 v[162:165], v89
	ds_read_b128 v[166:169], v89 offset:4096
	ds_read_b128 v[182:185], v88 offset:32768
	ds_read_b128 v[186:189], v88 offset:36864
	s_waitcnt lgkmcnt(6)
	v_mfma_f32_32x32x16_bf16 v[50:65], v[190:193], v[194:197], v[50:65]
	s_waitcnt lgkmcnt(4)
	v_mfma_f32_32x32x16_bf16 v[34:49], v[190:193], v[202:205], v[34:49]
	v_mfma_f32_32x32x16_bf16 v[18:33], v[198:201], v[194:197], v[18:33]
	v_mfma_f32_32x32x16_bf16 v[2:17], v[198:201], v[202:205], v[2:17]
	ds_read_b128 v[190:193], v87
	ds_read_b128 v[194:197], v87 offset:4096
	ds_read_b128 v[198:201], v86 offset:32768
	ds_read_b128 v[202:205], v86 offset:36864
	v_lshl_add_u64 v[66:67], v[66:67], 0, s[98:99]
	v_lshl_add_u64 v[70:71], v[70:71], 0, s[98:99]
	v_lshl_add_u64 v[74:75], v[74:75], 0, s[98:99]
	v_lshl_add_u64 v[78:79], v[78:79], 0, s[98:99]
	v_lshl_add_u64 v[68:69], v[68:69], 0, s[98:99]
	v_lshl_add_u64 v[72:73], v[72:73], 0, s[98:99]
	v_lshl_add_u64 v[76:77], v[76:77], 0, s[98:99]
	v_lshl_add_u64 v[80:81], v[80:81], 0, s[98:99]
	s_waitcnt lgkmcnt(0)
	s_barrier
	s_add_u32 m0, s32, 0x0
	v_mfma_f32_32x32x16_bf16 v[50:65], v[162:165], v[182:185], v[50:65]
	global_load_lds_dwordx4 v[66:67], off
	s_add_u32 m0, s32, 0x1000
	v_mfma_f32_32x32x16_bf16 v[34:49], v[162:165], v[186:189], v[34:49]
	global_load_lds_dwordx4 v[70:71], off
	s_add_u32 m0, s32, 0x2000
	v_mfma_f32_32x32x16_bf16 v[18:33], v[166:169], v[182:185], v[18:33]
	global_load_lds_dwordx4 v[74:75], off
	s_add_u32 m0, s32, 0x3000
	v_mfma_f32_32x32x16_bf16 v[2:17], v[166:169], v[186:189], v[2:17]
	global_load_lds_dwordx4 v[78:79], off
	s_add_u32 m0, s32, 0x8000
	v_mfma_f32_32x32x16_bf16 v[50:65], v[190:193], v[198:201], v[50:65]
	global_load_lds_dwordx4 v[68:69], off
	s_add_u32 m0, s32, 0x9000
	v_mfma_f32_32x32x16_bf16 v[34:49], v[190:193], v[202:205], v[34:49]
	global_load_lds_dwordx4 v[72:73], off
	s_add_u32 m0, s32, 0xa000
	v_mfma_f32_32x32x16_bf16 v[18:33], v[194:197], v[198:201], v[18:33]
	global_load_lds_dwordx4 v[76:77], off
	s_add_u32 m0, s32, 0xb000
	v_mfma_f32_32x32x16_bf16 v[2:17], v[194:197], v[202:205], v[2:17]
	global_load_lds_dwordx4 v[80:81], off
	s_waitcnt vmcnt(8)
	s_barrier
	ds_read_b128 v[162:165], v91 offset:16384
	ds_read_b128 v[166:169], v92 offset:49152
	ds_read_b128 v[182:185], v91 offset:20480
	ds_read_b128 v[186:189], v92 offset:53248
	ds_read_b128 v[190:193], v93 offset:16384
	ds_read_b128 v[194:197], v90 offset:49152
	ds_read_b128 v[198:201], v93 offset:20480
	ds_read_b128 v[202:205], v90 offset:53248
	s_waitcnt lgkmcnt(6)
	v_mfma_f32_32x32x16_bf16 v[50:65], v[162:165], v[166:169], v[50:65]
	s_waitcnt lgkmcnt(4)
	v_mfma_f32_32x32x16_bf16 v[34:49], v[162:165], v[186:189], v[34:49]
	v_mfma_f32_32x32x16_bf16 v[18:33], v[182:185], v[166:169], v[18:33]
	v_mfma_f32_32x32x16_bf16 v[2:17], v[182:185], v[186:189], v[2:17]
	ds_read_b128 v[162:165], v89 offset:16384
	ds_read_b128 v[166:169], v89 offset:20480
	ds_read_b128 v[182:185], v88 offset:49152
	ds_read_b128 v[186:189], v88 offset:53248
	s_waitcnt lgkmcnt(6)
	v_mfma_f32_32x32x16_bf16 v[50:65], v[190:193], v[194:197], v[50:65]
	s_waitcnt lgkmcnt(4)
	v_mfma_f32_32x32x16_bf16 v[34:49], v[190:193], v[202:205], v[34:49]
	v_mfma_f32_32x32x16_bf16 v[18:33], v[198:201], v[194:197], v[18:33]
	v_mfma_f32_32x32x16_bf16 v[2:17], v[198:201], v[202:205], v[2:17]
	ds_read_b128 v[190:193], v87 offset:16384
	ds_read_b128 v[194:197], v87 offset:20480
	ds_read_b128 v[198:201], v86 offset:49152
	ds_read_b128 v[202:205], v86 offset:53248
	v_lshl_add_u64 v[66:67], v[66:67], 0, s[98:99]
	v_lshl_add_u64 v[70:71], v[70:71], 0, s[98:99]
	v_lshl_add_u64 v[74:75], v[74:75], 0, s[98:99]
	v_lshl_add_u64 v[78:79], v[78:79], 0, s[98:99]
	v_lshl_add_u64 v[68:69], v[68:69], 0, s[98:99]
	v_lshl_add_u64 v[72:73], v[72:73], 0, s[98:99]
	v_lshl_add_u64 v[76:77], v[76:77], 0, s[98:99]
	v_lshl_add_u64 v[80:81], v[80:81], 0, s[98:99]
	s_waitcnt lgkmcnt(0)
	s_barrier
	s_add_u32 m0, s32, 0x4000
	v_mfma_f32_32x32x16_bf16 v[50:65], v[162:165], v[182:185], v[50:65]
	global_load_lds_dwordx4 v[66:67], off
	s_add_u32 m0, s32, 0x5000
	v_mfma_f32_32x32x16_bf16 v[34:49], v[162:165], v[186:189], v[34:49]
	global_load_lds_dwordx4 v[70:71], off
	s_add_u32 m0, s32, 0x6000
	v_mfma_f32_32x32x16_bf16 v[18:33], v[166:169], v[182:185], v[18:33]
	global_load_lds_dwordx4 v[74:75], off
	s_add_u32 m0, s32, 0x7000
	v_mfma_f32_32x32x16_bf16 v[2:17], v[166:169], v[186:189], v[2:17]
	global_load_lds_dwordx4 v[78:79], off
	s_add_u32 m0, s32, 0xc000
	v_mfma_f32_32x32x16_bf16 v[50:65], v[190:193], v[198:201], v[50:65]
	global_load_lds_dwordx4 v[68:69], off
	s_add_u32 m0, s32, 0xd000
	v_mfma_f32_32x32x16_bf16 v[34:49], v[190:193], v[202:205], v[34:49]
	global_load_lds_dwordx4 v[72:73], off
	s_add_u32 m0, s32, 0xe000
	v_mfma_f32_32x32x16_bf16 v[18:33], v[194:197], v[198:201], v[18:33]
	global_load_lds_dwordx4 v[76:77], off
	s_add_u32 m0, s32, 0xf000
	v_mfma_f32_32x32x16_bf16 v[2:17], v[194:197], v[202:205], v[2:17]
	global_load_lds_dwordx4 v[80:81], off
	s_waitcnt vmcnt(8)
	s_barrier
	ds_read_b128 v[162:165], v91
	ds_read_b128 v[166:169], v92 offset:32768
	ds_read_b128 v[182:185], v91 offset:4096
	ds_read_b128 v[186:189], v92 offset:36864
	ds_read_b128 v[190:193], v93
	ds_read_b128 v[194:197], v90 offset:32768
	ds_read_b128 v[198:201], v93 offset:4096
	ds_read_b128 v[202:205], v90 offset:36864
	s_waitcnt lgkmcnt(6)
	v_mfma_f32_32x32x16_bf16 v[50:65], v[162:165], v[166:169], v[50:65]
	s_waitcnt lgkmcnt(4)
	v_mfma_f32_32x32x16_bf16 v[34:49], v[162:165], v[186:189], v[34:49]
	v_mfma_f32_32x32x16_bf16 v[18:33], v[182:185], v[166:169], v[18:33]
	v_mfma_f32_32x32x16_bf16 v[2:17], v[182:185], v[186:189], v[2:17]
	ds_read_b128 v[162:165], v89
	ds_read_b128 v[166:169], v89 offset:4096
	ds_read_b128 v[182:185], v88 offset:32768
	ds_read_b128 v[186:189], v88 offset:36864
	s_waitcnt lgkmcnt(6)
	v_mfma_f32_32x32x16_bf16 v[50:65], v[190:193], v[194:197], v[50:65]
	s_waitcnt lgkmcnt(4)
	v_mfma_f32_32x32x16_bf16 v[34:49], v[190:193], v[202:205], v[34:49]
	v_mfma_f32_32x32x16_bf16 v[18:33], v[198:201], v[194:197], v[18:33]
	v_mfma_f32_32x32x16_bf16 v[2:17], v[198:201], v[202:205], v[2:17]
	ds_read_b128 v[190:193], v87
	ds_read_b128 v[194:197], v87 offset:4096
	ds_read_b128 v[198:201], v86 offset:32768
	ds_read_b128 v[202:205], v86 offset:36864
	v_lshl_add_u64 v[66:67], v[66:67], 0, s[98:99]
	v_lshl_add_u64 v[70:71], v[70:71], 0, s[98:99]
	v_lshl_add_u64 v[74:75], v[74:75], 0, s[98:99]
	v_lshl_add_u64 v[78:79], v[78:79], 0, s[98:99]
	v_lshl_add_u64 v[68:69], v[68:69], 0, s[98:99]
	v_lshl_add_u64 v[72:73], v[72:73], 0, s[98:99]
	v_lshl_add_u64 v[76:77], v[76:77], 0, s[98:99]
	v_lshl_add_u64 v[80:81], v[80:81], 0, s[98:99]
	s_waitcnt lgkmcnt(0)
	s_barrier
	s_add_u32 m0, s32, 0x0
	v_mfma_f32_32x32x16_bf16 v[50:65], v[162:165], v[182:185], v[50:65]
	global_load_lds_dwordx4 v[66:67], off
	s_add_u32 m0, s32, 0x1000
	v_mfma_f32_32x32x16_bf16 v[34:49], v[162:165], v[186:189], v[34:49]
	global_load_lds_dwordx4 v[70:71], off
	s_add_u32 m0, s32, 0x2000
	v_mfma_f32_32x32x16_bf16 v[18:33], v[166:169], v[182:185], v[18:33]
	global_load_lds_dwordx4 v[74:75], off
	s_add_u32 m0, s32, 0x3000
	v_mfma_f32_32x32x16_bf16 v[2:17], v[166:169], v[186:189], v[2:17]
	global_load_lds_dwordx4 v[78:79], off
	s_add_u32 m0, s32, 0x8000
	v_mfma_f32_32x32x16_bf16 v[50:65], v[190:193], v[198:201], v[50:65]
	global_load_lds_dwordx4 v[68:69], off
	s_add_u32 m0, s32, 0x9000
	v_mfma_f32_32x32x16_bf16 v[34:49], v[190:193], v[202:205], v[34:49]
	global_load_lds_dwordx4 v[72:73], off
	s_add_u32 m0, s32, 0xa000
	v_mfma_f32_32x32x16_bf16 v[18:33], v[194:197], v[198:201], v[18:33]
	global_load_lds_dwordx4 v[76:77], off
	s_add_u32 m0, s32, 0xb000
	v_mfma_f32_32x32x16_bf16 v[2:17], v[194:197], v[202:205], v[2:17]
	global_load_lds_dwordx4 v[80:81], off
	s_waitcnt vmcnt(8)
	s_barrier
	ds_read_b128 v[162:165], v91 offset:16384
	ds_read_b128 v[166:169], v92 offset:49152
	ds_read_b128 v[182:185], v91 offset:20480
	ds_read_b128 v[186:189], v92 offset:53248
	ds_read_b128 v[190:193], v93 offset:16384
	ds_read_b128 v[194:197], v90 offset:49152
	ds_read_b128 v[198:201], v93 offset:20480
	ds_read_b128 v[202:205], v90 offset:53248
	s_waitcnt lgkmcnt(6)
	v_mfma_f32_32x32x16_bf16 v[50:65], v[162:165], v[166:169], v[50:65]
	s_waitcnt lgkmcnt(4)
	v_mfma_f32_32x32x16_bf16 v[34:49], v[162:165], v[186:189], v[34:49]
	v_mfma_f32_32x32x16_bf16 v[18:33], v[182:185], v[166:169], v[18:33]
	v_mfma_f32_32x32x16_bf16 v[2:17], v[182:185], v[186:189], v[2:17]
	ds_read_b128 v[162:165], v89 offset:16384
	ds_read_b128 v[166:169], v89 offset:20480
	ds_read_b128 v[182:185], v88 offset:49152
	ds_read_b128 v[186:189], v88 offset:53248
	s_waitcnt lgkmcnt(6)
	v_mfma_f32_32x32x16_bf16 v[50:65], v[190:193], v[194:197], v[50:65]
	s_waitcnt lgkmcnt(4)
	v_mfma_f32_32x32x16_bf16 v[34:49], v[190:193], v[202:205], v[34:49]
	v_mfma_f32_32x32x16_bf16 v[18:33], v[198:201], v[194:197], v[18:33]
	v_mfma_f32_32x32x16_bf16 v[2:17], v[198:201], v[202:205], v[2:17]
	ds_read_b128 v[190:193], v87 offset:16384
	ds_read_b128 v[194:197], v87 offset:20480
	ds_read_b128 v[198:201], v86 offset:49152
	ds_read_b128 v[202:205], v86 offset:53248
	v_lshl_add_u64 v[66:67], v[66:67], 0, s[98:99]
	v_lshl_add_u64 v[70:71], v[70:71], 0, s[98:99]
	v_lshl_add_u64 v[74:75], v[74:75], 0, s[98:99]
	v_lshl_add_u64 v[78:79], v[78:79], 0, s[98:99]
	v_lshl_add_u64 v[68:69], v[68:69], 0, s[98:99]
	v_lshl_add_u64 v[72:73], v[72:73], 0, s[98:99]
	v_lshl_add_u64 v[76:77], v[76:77], 0, s[98:99]
	v_lshl_add_u64 v[80:81], v[80:81], 0, s[98:99]
	s_waitcnt lgkmcnt(0)
	s_barrier
	s_add_u32 m0, s32, 0x4000
	v_mfma_f32_32x32x16_bf16 v[50:65], v[162:165], v[182:185], v[50:65]
	global_load_lds_dwordx4 v[66:67], off
	s_add_u32 m0, s32, 0x5000
	v_mfma_f32_32x32x16_bf16 v[34:49], v[162:165], v[186:189], v[34:49]
	global_load_lds_dwordx4 v[70:71], off
	s_add_u32 m0, s32, 0x6000
	v_mfma_f32_32x32x16_bf16 v[18:33], v[166:169], v[182:185], v[18:33]
	global_load_lds_dwordx4 v[74:75], off
	s_add_u32 m0, s32, 0x7000
	v_mfma_f32_32x32x16_bf16 v[2:17], v[166:169], v[186:189], v[2:17]
	global_load_lds_dwordx4 v[78:79], off
	s_add_u32 m0, s32, 0xc000
	v_mfma_f32_32x32x16_bf16 v[50:65], v[190:193], v[198:201], v[50:65]
	global_load_lds_dwordx4 v[68:69], off
	s_add_u32 m0, s32, 0xd000
	v_mfma_f32_32x32x16_bf16 v[34:49], v[190:193], v[202:205], v[34:49]
	global_load_lds_dwordx4 v[72:73], off
	s_add_u32 m0, s32, 0xe000
	v_mfma_f32_32x32x16_bf16 v[18:33], v[194:197], v[198:201], v[18:33]
	global_load_lds_dwordx4 v[76:77], off
	s_add_u32 m0, s32, 0xf000
	v_mfma_f32_32x32x16_bf16 v[2:17], v[194:197], v[202:205], v[2:17]
	global_load_lds_dwordx4 v[80:81], off
	s_waitcnt vmcnt(8)
	s_barrier
	ds_read_b128 v[162:165], v91
	ds_read_b128 v[166:169], v92 offset:32768
	ds_read_b128 v[182:185], v91 offset:4096
	ds_read_b128 v[186:189], v92 offset:36864
	ds_read_b128 v[190:193], v93
	ds_read_b128 v[194:197], v90 offset:32768
	ds_read_b128 v[198:201], v93 offset:4096
	ds_read_b128 v[202:205], v90 offset:36864
	s_waitcnt lgkmcnt(6)
	v_mfma_f32_32x32x16_bf16 v[50:65], v[162:165], v[166:169], v[50:65]
	s_waitcnt lgkmcnt(4)
	v_mfma_f32_32x32x16_bf16 v[34:49], v[162:165], v[186:189], v[34:49]
	v_mfma_f32_32x32x16_bf16 v[18:33], v[182:185], v[166:169], v[18:33]
	v_mfma_f32_32x32x16_bf16 v[2:17], v[182:185], v[186:189], v[2:17]
	ds_read_b128 v[162:165], v89
	ds_read_b128 v[166:169], v89 offset:4096
	ds_read_b128 v[182:185], v88 offset:32768
	ds_read_b128 v[186:189], v88 offset:36864
	s_waitcnt lgkmcnt(6)
	v_mfma_f32_32x32x16_bf16 v[50:65], v[190:193], v[194:197], v[50:65]
	s_waitcnt lgkmcnt(4)
	v_mfma_f32_32x32x16_bf16 v[34:49], v[190:193], v[202:205], v[34:49]
	v_mfma_f32_32x32x16_bf16 v[18:33], v[198:201], v[194:197], v[18:33]
	v_mfma_f32_32x32x16_bf16 v[2:17], v[198:201], v[202:205], v[2:17]
	ds_read_b128 v[190:193], v87
	ds_read_b128 v[194:197], v87 offset:4096
	ds_read_b128 v[198:201], v86 offset:32768
	ds_read_b128 v[202:205], v86 offset:36864
	v_lshl_add_u64 v[66:67], v[66:67], 0, s[98:99]
	v_lshl_add_u64 v[70:71], v[70:71], 0, s[98:99]
	v_lshl_add_u64 v[74:75], v[74:75], 0, s[98:99]
	v_lshl_add_u64 v[78:79], v[78:79], 0, s[98:99]
	v_lshl_add_u64 v[68:69], v[68:69], 0, s[98:99]
	v_lshl_add_u64 v[72:73], v[72:73], 0, s[98:99]
	v_lshl_add_u64 v[76:77], v[76:77], 0, s[98:99]
	v_lshl_add_u64 v[80:81], v[80:81], 0, s[98:99]
	s_waitcnt lgkmcnt(0)
	s_barrier
	s_add_u32 m0, s32, 0x0
	s_nop 0
	global_load_lds_dwordx4 v[66:67], off
	s_add_u32 m0, s32, 0x1000
	s_nop 0
	global_load_lds_dwordx4 v[70:71], off
	s_add_u32 m0, s32, 0x2000
	s_nop 0
	global_load_lds_dwordx4 v[74:75], off
	s_add_u32 m0, s32, 0x3000
	s_nop 0
	global_load_lds_dwordx4 v[78:79], off
	s_add_u32 m0, s32, 0x8000
	s_nop 0
	global_load_lds_dwordx4 v[68:69], off
	s_add_u32 m0, s32, 0x9000
	s_nop 0
	global_load_lds_dwordx4 v[72:73], off
	s_add_u32 m0, s32, 0xa000
	s_nop 0
	global_load_lds_dwordx4 v[76:77], off
	s_add_u32 m0, s32, 0xb000
	s_nop 0
	global_load_lds_dwordx4 v[80:81], off
	s_waitcnt vmcnt(8)
	s_barrier
	s_nop 0
	s_nop 0
	s_nop 0
	s_nop 0
	s_nop 0
	s_nop 0
	s_nop 0
	v_mfma_f32_32x32x16_bf16 v[50:65], v[162:165], v[182:185], v[50:65]
	v_mfma_f32_32x32x16_bf16 v[34:49], v[162:165], v[186:189], v[34:49]
	v_mfma_f32_32x32x16_bf16 v[18:33], v[166:169], v[182:185], v[18:33]
	v_mfma_f32_32x32x16_bf16 v[2:17], v[166:169], v[186:189], v[2:17]
	ds_read_b128 v[110:113], v91 offset:16384
	ds_read_b128 v[114:117], v91 offset:20480
	ds_read_b128 v[118:121], v92 offset:49152
	ds_read_b128 v[122:125], v92 offset:53248
	ds_read_b128 v[162:165], v93 offset:16384
	ds_read_b128 v[166:169], v93 offset:20480
	ds_read_b128 v[182:185], v90 offset:49152
	ds_read_b128 v[186:189], v90 offset:53248
	v_mfma_f32_32x32x16_bf16 v[50:65], v[190:193], v[198:201], v[50:65]
	v_mfma_f32_32x32x16_bf16 v[34:49], v[190:193], v[202:205], v[34:49]
	v_mfma_f32_32x32x16_bf16 v[18:33], v[194:197], v[198:201], v[18:33]
	v_mfma_f32_32x32x16_bf16 v[2:17], v[194:197], v[202:205], v[2:17]
	s_waitcnt lgkmcnt(5)
	v_mfma_f32_32x32x16_bf16 v[50:65], v[110:113], v[118:121], v[50:65]
	s_waitcnt lgkmcnt(4)
	v_mfma_f32_32x32x16_bf16 v[34:49], v[110:113], v[122:125], v[34:49]
	v_mfma_f32_32x32x16_bf16 v[18:33], v[114:117], v[118:121], v[18:33]
	v_mfma_f32_32x32x16_bf16 v[2:17], v[114:117], v[122:125], v[2:17]
	ds_read_b128 v[110:113], v89 offset:16384
	ds_read_b128 v[114:117], v89 offset:20480
	ds_read_b128 v[118:121], v88 offset:49152
	ds_read_b128 v[122:125], v88 offset:53248
	s_waitcnt lgkmcnt(5)
	v_mfma_f32_32x32x16_bf16 v[50:65], v[162:165], v[182:185], v[50:65]
	s_waitcnt lgkmcnt(4)
	v_mfma_f32_32x32x16_bf16 v[34:49], v[162:165], v[186:189], v[34:49]
	v_mfma_f32_32x32x16_bf16 v[18:33], v[166:169], v[182:185], v[18:33]
	v_mfma_f32_32x32x16_bf16 v[2:17], v[166:169], v[186:189], v[2:17]
	ds_read_b128 v[162:165], v87 offset:16384
	ds_read_b128 v[166:169], v87 offset:20480
	ds_read_b128 v[182:185], v86 offset:49152
	ds_read_b128 v[186:189], v86 offset:53248
	s_waitcnt lgkmcnt(5)
	v_mfma_f32_32x32x16_bf16 v[50:65], v[110:113], v[118:121], v[50:65]
	v_lshl_add_u64 v[66:67], v[66:67], 0, s[98:99]
	v_lshl_add_u64 v[70:71], v[70:71], 0, s[98:99]
	v_lshl_add_u64 v[74:75], v[74:75], 0, s[98:99]
	v_lshl_add_u64 v[78:79], v[78:79], 0, s[98:99]
	v_lshl_add_u64 v[68:69], v[68:69], 0, s[98:99]
	v_lshl_add_u64 v[72:73], v[72:73], 0, s[98:99]
	v_lshl_add_u64 v[76:77], v[76:77], 0, s[98:99]
	v_lshl_add_u64 v[80:81], v[80:81], 0, s[98:99]
	s_waitcnt lgkmcnt(0)
	s_barrier
	s_add_u32 m0, s32, 0x4000
	s_nop 0
	global_load_lds_dwordx4 v[66:67], off
	s_add_u32 m0, s32, 0x5000
	s_nop 0
	global_load_lds_dwordx4 v[70:71], off
	s_add_u32 m0, s32, 0x6000
	s_nop 0
	global_load_lds_dwordx4 v[74:75], off
	s_add_u32 m0, s32, 0x7000
	s_nop 0
	global_load_lds_dwordx4 v[78:79], off
	s_add_u32 m0, s32, 0xc000
	s_nop 0
	global_load_lds_dwordx4 v[68:69], off
	s_add_u32 m0, s32, 0xd000
	s_nop 0
	global_load_lds_dwordx4 v[72:73], off
	s_add_u32 m0, s32, 0xe000
	s_nop 0
	global_load_lds_dwordx4 v[76:77], off
	s_add_u32 m0, s32, 0xf000
	s_nop 0
	global_load_lds_dwordx4 v[80:81], off
	s_waitcnt vmcnt(8)
	s_barrier
	v_mfma_f32_32x32x16_bf16 v[34:49], v[110:113], v[122:125], v[34:49]
	v_mfma_f32_32x32x16_bf16 v[18:33], v[114:117], v[118:121], v[18:33]
	v_mfma_f32_32x32x16_bf16 v[2:17], v[114:117], v[122:125], v[2:17]
	ds_read_b128 v[110:113], v91
	ds_read_b128 v[114:117], v91 offset:4096
	ds_read_b128 v[118:121], v92 offset:32768
	ds_read_b128 v[122:125], v92 offset:36864
	ds_read_b128 v[126:129], v93
	ds_read_b128 v[134:137], v93 offset:4096
	ds_read_b128 v[138:141], v90 offset:32768
	ds_read_b128 v[142:145], v90 offset:36864
	v_mfma_f32_32x32x16_bf16 v[50:65], v[162:165], v[182:185], v[50:65]
	v_mfma_f32_32x32x16_bf16 v[34:49], v[162:165], v[186:189], v[34:49]
	v_mfma_f32_32x32x16_bf16 v[18:33], v[166:169], v[182:185], v[18:33]
	v_mfma_f32_32x32x16_bf16 v[2:17], v[166:169], v[186:189], v[2:17]
	s_waitcnt lgkmcnt(5)
	v_mfma_f32_32x32x16_bf16 v[50:65], v[110:113], v[118:121], v[50:65]
	s_waitcnt lgkmcnt(4)
	v_mfma_f32_32x32x16_bf16 v[34:49], v[110:113], v[122:125], v[34:49]
	v_mfma_f32_32x32x16_bf16 v[18:33], v[114:117], v[118:121], v[18:33]
	v_mfma_f32_32x32x16_bf16 v[2:17], v[114:117], v[122:125], v[2:17]
	ds_read_b128 v[110:113], v89
	ds_read_b128 v[114:117], v89 offset:4096
	ds_read_b128 v[118:121], v88 offset:32768
	ds_read_b128 v[122:125], v88 offset:36864
	s_waitcnt lgkmcnt(5)
	v_mfma_f32_32x32x16_bf16 v[50:65], v[126:129], v[138:141], v[50:65]
	s_waitcnt lgkmcnt(4)
	v_mfma_f32_32x32x16_bf16 v[34:49], v[126:129], v[142:145], v[34:49]
	v_mfma_f32_32x32x16_bf16 v[18:33], v[134:137], v[138:141], v[18:33]
	v_mfma_f32_32x32x16_bf16 v[2:17], v[134:137], v[142:145], v[2:17]
	ds_read_b128 v[126:129], v87
	ds_read_b128 v[134:137], v87 offset:4096
	ds_read_b128 v[138:141], v86 offset:32768
	ds_read_b128 v[142:145], v86 offset:36864
	s_waitcnt lgkmcnt(5)
	v_mfma_f32_32x32x16_bf16 v[50:65], v[110:113], v[118:121], v[50:65]
	s_waitcnt vmcnt(0)
	s_waitcnt lgkmcnt(0)
	s_barrier
	ds_read_b128 v[66:69], v91 offset:16384
	ds_read_b128 v[70:73], v91 offset:20480
	ds_read_b128 v[74:77], v92 offset:49152
	ds_read_b128 v[78:81], v92 offset:53248
	ds_read_b128 v[94:97], v93 offset:16384
	ds_read_b128 v[98:101], v93 offset:20480
	ds_read_b128 v[102:105], v90 offset:49152
	ds_read_b128 v[90:93], v90 offset:53248
	v_mfma_f32_32x32x16_bf16 v[34:49], v[110:113], v[122:125], v[34:49]
	v_mfma_f32_32x32x16_bf16 v[18:33], v[114:117], v[118:121], v[18:33]
	v_mfma_f32_32x32x16_bf16 v[2:17], v[114:117], v[122:125], v[2:17]
	v_mfma_f32_32x32x16_bf16 v[50:65], v[126:129], v[138:141], v[50:65]
	v_mfma_f32_32x32x16_bf16 v[34:49], v[126:129], v[142:145], v[34:49]
	v_mfma_f32_32x32x16_bf16 v[18:33], v[134:137], v[138:141], v[18:33]
	v_mfma_f32_32x32x16_bf16 v[2:17], v[134:137], v[142:145], v[2:17]
	s_waitcnt lgkmcnt(5)
	v_mfma_f32_32x32x16_bf16 v[50:65], v[66:69], v[74:77], v[50:65]
	s_waitcnt lgkmcnt(4)
	v_mfma_f32_32x32x16_bf16 v[34:49], v[66:69], v[78:81], v[34:49]
	v_mfma_f32_32x32x16_bf16 v[18:33], v[70:73], v[74:77], v[18:33]
	v_mfma_f32_32x32x16_bf16 v[2:17], v[70:73], v[78:81], v[2:17]
	ds_read_b128 v[66:69], v89 offset:16384
	ds_read_b128 v[70:73], v89 offset:20480
	ds_read_b128 v[74:77], v88 offset:49152
	ds_read_b128 v[78:81], v88 offset:53248
	s_waitcnt lgkmcnt(5)
	v_mfma_f32_32x32x16_bf16 v[50:65], v[94:97], v[102:105], v[50:65]
	s_waitcnt lgkmcnt(4)
	v_mfma_f32_32x32x16_bf16 v[34:49], v[94:97], v[90:93], v[34:49]
	v_mfma_f32_32x32x16_bf16 v[18:33], v[98:101], v[102:105], v[18:33]
	v_mfma_f32_32x32x16_bf16 v[2:17], v[98:101], v[90:93], v[2:17]
	ds_read_b128 v[88:91], v87 offset:16384
	ds_read_b128 v[92:95], v87 offset:20480
	ds_read_b128 v[96:99], v86 offset:49152
	ds_read_b128 v[100:103], v86 offset:53248
	s_waitcnt lgkmcnt(5)
	v_mfma_f32_32x32x16_bf16 v[50:65], v[66:69], v[74:77], v[50:65]
	v_lshlrev_b32_e32 v0, 6, v85
	v_subrev_u32_e32 v0, s2, v0
	s_lshl_b32 s3, s34, 7
	s_movk_i32 s2, 0x9c0
	s_waitcnt lgkmcnt(0)
	s_barrier
	v_mfma_f32_32x32x16_bf16 v[34:49], v[66:69], v[78:81], v[34:49]
	v_add_u32_e32 v66, s7, v0
	v_lshl_add_u32 v68, v83, 6, s3
	v_add_u32_e32 v0, v66, v84
	v_cmp_lt_i32_e64 s[40:41], s63, v0
	v_cmp_gt_u32_e32 vcc, s2, v66
	v_lshl_add_u64 v[66:67], v[0:1], 1, s[48:49]
	v_mfma_f32_32x32x16_bf16 v[18:33], v[70:73], v[74:77], v[18:33]
	v_mfma_f32_32x32x16_bf16 v[2:17], v[70:73], v[78:81], v[2:17]
	v_lshl_or_b32 v70, v82, 2, v68
	v_mfma_f32_32x32x16_bf16 v[50:65], v[88:91], v[96:99], v[50:65]
	v_mfma_f32_32x32x16_bf16 v[34:49], v[88:91], v[100:103], v[34:49]
	v_mfma_f32_32x32x16_bf16 v[18:33], v[92:95], v[96:99], v[18:33]
	v_mfma_f32_32x32x16_bf16 v[2:17], v[92:95], v[100:103], v[2:17]
	s_and_saveexec_b64 s[2:3], s[40:41]
	s_xor_b64 s[2:3], exec, s[2:3]
	s_cbranch_execz .LBB0_236
	s_and_saveexec_b64 s[4:5], vcc
	s_cbranch_execz .LBB0_235
	s_nop 3
	v_cvt_pk_bf16_f32 v71, v50, s0
	v_mad_i64_i32 v[68:69], s[34:35], v70, s68, v[66:67]
	global_store_short v[68:69], v71, off offset:-1920

.LBB0_1186:
	s_ashr_i32 s5, s4, 31
	s_lshr_b32 s5, s5, 29
	s_add_i32 s5, s4, s5
	s_ashr_i32 s34, s5, 3
	s_ashr_i32 s35, s34, 31
	v_readlane_b32 s36, v210, 50
	v_mov_b32_e32 v36, v133
	s_lshl_b64 s[6:7], s[34:35], 18
	v_readlane_b32 s38, v210, 52
	v_readlane_b32 s39, v210, 53
	v_ashrrev_i32_e32 v34, 3, v36
	s_add_u32 s6, s38, s6
	v_ashrrev_i32_e32 v35, 31, v34
	s_addc_u32 s7, s39, s7
	v_lshlrev_b64 v[2:3], 11, v[34:35]
	v_lshlrev_b32_e32 v0, 4, v36
	v_lshl_add_u64 v[2:3], s[6:7], 0, v[2:3]
	v_and_b32_e32 v0, 0x70, v0
	s_lshl_b32 s5, s34, 10
	v_lshl_add_u64 v[66:67], v[2:3], 0, v[0:1]
	v_subrev_u32_e32 v2, s5, v34
	v_add_u32_e32 v2, s3, v2
	v_ashrrev_i32_e32 v3, 31, v2
	v_lshlrev_b64 v[2:3], 11, v[2:3]
	v_lshl_add_u64 v[2:3], s[0:1], 0, v[2:3]
	v_add_co_u32_e32 v70, vcc, s10, v66
	v_lshl_add_u64 v[68:69], v[2:3], 0, v[0:1]
	s_nop 0
	v_addc_co_u32_e32 v71, vcc, 0, v67, vcc
	v_add_co_u32_e32 v72, vcc, s10, v68
	v_addc_co_u32_e32 v73, vcc, 0, v69, vcc
	v_add_co_u32_e32 v74, vcc, s63, v66
	s_nop 0
	v_addc_co_u32_e32 v75, vcc, 0, v67, vcc
	v_add_co_u32_e32 v76, vcc, s63, v68
	s_nop 0
	v_addc_co_u32_e32 v77, vcc, 0, v69, vcc
	v_add_co_u32_e32 v78, vcc, s61, v66
	s_nop 0
	v_addc_co_u32_e32 v79, vcc, 0, v67, vcc
	v_add_co_u32_e32 v80, vcc, s61, v68
	v_lshlrev_b32_e32 v0, 7, v34
	s_nop 0
	v_addc_co_u32_e32 v81, vcc, 0, v69, vcc
	v_lshrrev_b32_e32 v216, 4, v133
	v_xor_b32_e32 v216, v216, v133
	v_and_b32_e32 v216, 7, v216
	v_lshlrev_b32_e32 v216, 4, v216
	v_mov_b32_e32 v217, 0x70
	v_lshrrev_b32_e32 v218, 6, v133
	v_lshlrev_b32_e32 v218, 10, v218
	s_nop 0
	v_readfirstlane_b32 s32, v218
	v_bfi_b32 v66, v217, v216, v66
	v_bfi_b32 v70, v217, v216, v70
	v_bfi_b32 v74, v217, v216, v74
	v_bfi_b32 v78, v217, v216, v78
	v_bfi_b32 v68, v217, v216, v68
	v_bfi_b32 v72, v217, v216, v72
	v_bfi_b32 v76, v217, v216, v76
	v_bfi_b32 v80, v217, v216, v80
	s_mov_b64 s[98:99], 0x80
	s_add_u32 m0, s32, 0x0
	s_nop 0
	global_load_lds_dwordx4 v[66:67], off
	s_add_u32 m0, s32, 0x1000
	s_nop 0
	global_load_lds_dwordx4 v[70:71], off
	s_add_u32 m0, s32, 0x2000
	s_nop 0
	global_load_lds_dwordx4 v[74:75], off
	s_add_u32 m0, s32, 0x3000
	s_nop 0
	global_load_lds_dwordx4 v[78:79], off
	s_add_u32 m0, s32, 0x8000
	s_nop 0
	global_load_lds_dwordx4 v[68:69], off
	s_add_u32 m0, s32, 0x9000
	s_nop 0
	global_load_lds_dwordx4 v[72:73], off
	s_add_u32 m0, s32, 0xa000
	s_nop 0
	global_load_lds_dwordx4 v[76:77], off
	s_add_u32 m0, s32, 0xb000
	s_nop 0
	global_load_lds_dwordx4 v[80:81], off
	v_lshl_add_u64 v[66:67], v[66:67], 0, s[98:99]
	v_lshl_add_u64 v[70:71], v[70:71], 0, s[98:99]
	v_lshl_add_u64 v[74:75], v[74:75], 0, s[98:99]
	v_lshl_add_u64 v[78:79], v[78:79], 0, s[98:99]
	v_lshl_add_u64 v[68:69], v[68:69], 0, s[98:99]
	v_lshl_add_u64 v[72:73], v[72:73], 0, s[98:99]
	v_lshl_add_u64 v[76:77], v[76:77], 0, s[98:99]
	v_lshl_add_u64 v[80:81], v[80:81], 0, s[98:99]
	v_lshrrev_b32_e32 v34, 1, v34
	v_xor_b32_e32 v34, v34, v36
	v_lshlrev_b32_e32 v34, 4, v34
	s_movk_i32 s6, 0x70
	v_and_or_b32 v0, v34, s6, v0
	s_waitcnt vmcnt(26)
	v_and_b32_e32 v82, 31, v36
	v_bfe_u32 v85, v36, 5, 1
	v_ashrrev_i32_e32 v84, 7, v36
	v_bfe_u32 v83, v36, 6, 1
	v_readlane_b32 s37, v210, 51
	v_readlane_b32 s40, v210, 54
	v_readlane_b32 s41, v210, 55
	v_readlane_b32 s42, v210, 56
	v_readlane_b32 s43, v210, 57
	v_readlane_b32 s44, v210, 58
	v_readlane_b32 s45, v210, 59
	v_readlane_b32 s46, v210, 60
	v_readlane_b32 s47, v210, 61
	v_readlane_b32 s48, v210, 62
	v_readlane_b32 s49, v210, 63
	v_readlane_b32 s50, v209, 0
	v_readlane_b32 s51, v209, 1
	s_waitcnt lgkmcnt(0)
	s_barrier
	s_add_u32 m0, s32, 0x4000
	s_nop 0
	global_load_lds_dwordx4 v[66:67], off
	s_add_u32 m0, s32, 0x5000
	s_nop 0
	global_load_lds_dwordx4 v[70:71], off
	s_add_u32 m0, s32, 0x6000
	s_nop 0
	global_load_lds_dwordx4 v[74:75], off
	s_add_u32 m0, s32, 0x7000
	s_nop 0
	global_load_lds_dwordx4 v[78:79], off
	s_add_u32 m0, s32, 0xc000
	s_nop 0
	global_load_lds_dwordx4 v[68:69], off
	s_add_u32 m0, s32, 0xd000
	s_nop 0
	global_load_lds_dwordx4 v[72:73], off
	s_add_u32 m0, s32, 0xe000
	s_nop 0
	global_load_lds_dwordx4 v[76:77], off
	s_add_u32 m0, s32, 0xf000
	s_nop 0
	global_load_lds_dwordx4 v[80:81], off
	s_waitcnt vmcnt(8)
	s_barrier
	v_lshrrev_b32_e32 v4, 1, v36
	v_lshlrev_b32_e32 v2, 7, v82
	v_bitop3_b32 v4, v4, v85, 7 bitop3:0x6c
	v_lshl_or_b32 v3, v84, 13, v2
	v_bfe_u32 v5, v36, 1, 3
	v_lshlrev_b32_e32 v4, 4, v4
	v_lshl_or_b32 v2, v83, 13, v2
	v_or_b32_e32 v91, v3, v4
	v_or_b32_e32 v92, v2, v4
	v_bitop3_b32 v4, v85, v5, 2 bitop3:0x36
	v_lshlrev_b32_e32 v4, 4, v4
	v_or_b32_e32 v93, v3, v4
	v_or_b32_e32 v90, v2, v4
	v_bitop3_b32 v4, v85, v5, 4 bitop3:0x36
	v_lshlrev_b32_e32 v4, 4, v4
	v_or_b32_e32 v89, v3, v4
	v_or_b32_e32 v88, v2, v4
	v_bitop3_b32 v4, v85, v5, 6 bitop3:0x36
	v_lshlrev_b32_e32 v4, 4, v4
	v_or_b32_e32 v87, v3, v4
	v_or_b32_e32 v86, v2, v4
	ds_read_b128 v[2:5], v91
	ds_read_b128 v[6:9], v92 offset:32768
	ds_read_b128 v[10:13], v91 offset:4096
	ds_read_b128 v[14:17], v92 offset:36864
	ds_read_b128 v[162:165], v93
	ds_read_b128 v[166:169], v90 offset:32768
	ds_read_b128 v[182:185], v93 offset:4096
	ds_read_b128 v[186:189], v90 offset:36864
	s_waitcnt lgkmcnt(6)
	v_mfma_f32_32x32x16_bf16 v[50:65], v[2:5], v[6:9], 0
	s_waitcnt lgkmcnt(4)
	v_mfma_f32_32x32x16_bf16 v[18:33], v[2:5], v[14:17], 0
	v_mfma_f32_32x32x16_bf16 v[34:49], v[10:13], v[6:9], 0
	v_mfma_f32_32x32x16_bf16 v[2:17], v[10:13], v[14:17], 0
	ds_read_b128 v[190:193], v89
	ds_read_b128 v[194:197], v89 offset:4096
	ds_read_b128 v[198:201], v88 offset:32768
	ds_read_b128 v[202:205], v88 offset:36864
	s_waitcnt lgkmcnt(6)
	v_mfma_f32_32x32x16_bf16 v[50:65], v[162:165], v[166:169], v[50:65]
	s_waitcnt lgkmcnt(4)
	v_mfma_f32_32x32x16_bf16 v[18:33], v[162:165], v[186:189], v[18:33]
	v_mfma_f32_32x32x16_bf16 v[34:49], v[182:185], v[166:169], v[34:49]
	v_mfma_f32_32x32x16_bf16 v[2:17], v[182:185], v[186:189], v[2:17]
	ds_read_b128 v[162:165], v87
	ds_read_b128 v[166:169], v87 offset:4096
	ds_read_b128 v[182:185], v86 offset:32768
	ds_read_b128 v[186:189], v86 offset:36864
	v_lshl_add_u64 v[66:67], v[66:67], 0, s[98:99]
	v_lshl_add_u64 v[70:71], v[70:71], 0, s[98:99]
	v_lshl_add_u64 v[74:75], v[74:75], 0, s[98:99]
	v_lshl_add_u64 v[78:79], v[78:79], 0, s[98:99]
	v_lshl_add_u64 v[68:69], v[68:69], 0, s[98:99]
	v_lshl_add_u64 v[72:73], v[72:73], 0, s[98:99]
	v_lshl_add_u64 v[76:77], v[76:77], 0, s[98:99]
	v_lshl_add_u64 v[80:81], v[80:81], 0, s[98:99]
	s_waitcnt lgkmcnt(0)
	s_barrier
	s_add_u32 m0, s32, 0x0
	v_mfma_f32_32x32x16_bf16 v[50:65], v[190:193], v[198:201], v[50:65]
	global_load_lds_dwordx4 v[66:67], off
	s_add_u32 m0, s32, 0x1000
	v_mfma_f32_32x32x16_bf16 v[18:33], v[190:193], v[202:205], v[18:33]
	global_load_lds_dwordx4 v[70:71], off
	s_add_u32 m0, s32, 0x2000
	v_mfma_f32_32x32x16_bf16 v[34:49], v[194:197], v[198:201], v[34:49]
	global_load_lds_dwordx4 v[74:75], off
	s_add_u32 m0, s32, 0x3000
	v_mfma_f32_32x32x16_bf16 v[2:17], v[194:197], v[202:205], v[2:17]
	global_load_lds_dwordx4 v[78:79], off
	s_add_u32 m0, s32, 0x8000
	v_mfma_f32_32x32x16_bf16 v[50:65], v[162:165], v[182:185], v[50:65]
	global_load_lds_dwordx4 v[68:69], off
	s_add_u32 m0, s32, 0x9000
	v_mfma_f32_32x32x16_bf16 v[18:33], v[162:165], v[186:189], v[18:33]
	global_load_lds_dwordx4 v[72:73], off
	s_add_u32 m0, s32, 0xa000
	v_mfma_f32_32x32x16_bf16 v[34:49], v[166:169], v[182:185], v[34:49]
	global_load_lds_dwordx4 v[76:77], off
	s_add_u32 m0, s32, 0xb000
	v_mfma_f32_32x32x16_bf16 v[2:17], v[166:169], v[186:189], v[2:17]
	global_load_lds_dwordx4 v[80:81], off
	s_waitcnt vmcnt(8)
	s_barrier
	ds_read_b128 v[162:165], v91 offset:16384
	ds_read_b128 v[166:169], v92 offset:49152
	ds_read_b128 v[182:185], v91 offset:20480
	ds_read_b128 v[186:189], v92 offset:53248
	ds_read_b128 v[190:193], v93 offset:16384
	ds_read_b128 v[194:197], v90 offset:49152
	ds_read_b128 v[198:201], v93 offset:20480
	ds_read_b128 v[202:205], v90 offset:53248
	s_waitcnt lgkmcnt(6)
	v_mfma_f32_32x32x16_bf16 v[50:65], v[162:165], v[166:169], v[50:65]
	s_waitcnt lgkmcnt(4)
	v_mfma_f32_32x32x16_bf16 v[18:33], v[162:165], v[186:189], v[18:33]
	v_mfma_f32_32x32x16_bf16 v[34:49], v[182:185], v[166:169], v[34:49]
	v_mfma_f32_32x32x16_bf16 v[2:17], v[182:185], v[186:189], v[2:17]
	ds_read_b128 v[162:165], v89 offset:16384
	ds_read_b128 v[166:169], v89 offset:20480
	ds_read_b128 v[182:185], v88 offset:49152
	ds_read_b128 v[186:189], v88 offset:53248
	s_waitcnt lgkmcnt(6)
	v_mfma_f32_32x32x16_bf16 v[50:65], v[190:193], v[194:197], v[50:65]
	s_waitcnt lgkmcnt(4)
	v_mfma_f32_32x32x16_bf16 v[18:33], v[190:193], v[202:205], v[18:33]
	v_mfma_f32_32x32x16_bf16 v[34:49], v[198:201], v[194:197], v[34:49]
	v_mfma_f32_32x32x16_bf16 v[2:17], v[198:201], v[202:205], v[2:17]
	ds_read_b128 v[190:193], v87 offset:16384
	ds_read_b128 v[194:197], v87 offset:20480
	ds_read_b128 v[198:201], v86 offset:49152
	ds_read_b128 v[202:205], v86 offset:53248
	v_lshl_add_u64 v[66:67], v[66:67], 0, s[98:99]
	v_lshl_add_u64 v[70:71], v[70:71], 0, s[98:99]
	v_lshl_add_u64 v[74:75], v[74:75], 0, s[98:99]
	v_lshl_add_u64 v[78:79], v[78:79], 0, s[98:99]
	v_lshl_add_u64 v[68:69], v[68:69], 0, s[98:99]
	v_lshl_add_u64 v[72:73], v[72:73], 0, s[98:99]
	v_lshl_add_u64 v[76:77], v[76:77], 0, s[98:99]
	v_lshl_add_u64 v[80:81], v[80:81], 0, s[98:99]
	s_waitcnt lgkmcnt(0)
	s_barrier
	s_add_u32 m0, s32, 0x4000
	v_mfma_f32_32x32x16_bf16 v[50:65], v[162:165], v[182:185], v[50:65]
	global_load_lds_dwordx4 v[66:67], off
	s_add_u32 m0, s32, 0x5000
	v_mfma_f32_32x32x16_bf16 v[18:33], v[162:165], v[186:189], v[18:33]
	global_load_lds_dwordx4 v[70:71], off
	s_add_u32 m0, s32, 0x6000
	v_mfma_f32_32x32x16_bf16 v[34:49], v[166:169], v[182:185], v[34:49]
	global_load_lds_dwordx4 v[74:75], off
	s_add_u32 m0, s32, 0x7000
	v_mfma_f32_32x32x16_bf16 v[2:17], v[166:169], v[186:189], v[2:17]
	global_load_lds_dwordx4 v[78:79], off
	s_add_u32 m0, s32, 0xc000
	v_mfma_f32_32x32x16_bf16 v[50:65], v[190:193], v[198:201], v[50:65]
	global_load_lds_dwordx4 v[68:69], off
	s_add_u32 m0, s32, 0xd000
	v_mfma_f32_32x32x16_bf16 v[18:33], v[190:193], v[202:205], v[18:33]
	global_load_lds_dwordx4 v[72:73], off
	s_add_u32 m0, s32, 0xe000
	v_mfma_f32_32x32x16_bf16 v[34:49], v[194:197], v[198:201], v[34:49]
	global_load_lds_dwordx4 v[76:77], off
	s_add_u32 m0, s32, 0xf000
	v_mfma_f32_32x32x16_bf16 v[2:17], v[194:197], v[202:205], v[2:17]
	global_load_lds_dwordx4 v[80:81], off
	s_waitcnt vmcnt(8)
	s_barrier
	ds_read_b128 v[162:165], v91
	ds_read_b128 v[166:169], v92 offset:32768
	ds_read_b128 v[182:185], v91 offset:4096
	ds_read_b128 v[186:189], v92 offset:36864
	ds_read_b128 v[190:193], v93
	ds_read_b128 v[194:197], v90 offset:32768
	ds_read_b128 v[198:201], v93 offset:4096
	ds_read_b128 v[202:205], v90 offset:36864
	s_waitcnt lgkmcnt(6)
	v_mfma_f32_32x32x16_bf16 v[50:65], v[162:165], v[166:169], v[50:65]
	s_waitcnt lgkmcnt(4)
	v_mfma_f32_32x32x16_bf16 v[18:33], v[162:165], v[186:189], v[18:33]
	v_mfma_f32_32x32x16_bf16 v[34:49], v[182:185], v[166:169], v[34:49]
	v_mfma_f32_32x32x16_bf16 v[2:17], v[182:185], v[186:189], v[2:17]
	ds_read_b128 v[162:165], v89
	ds_read_b128 v[166:169], v89 offset:4096
	ds_read_b128 v[182:185], v88 offset:32768
	ds_read_b128 v[186:189], v88 offset:36864
	s_waitcnt lgkmcnt(6)
	v_mfma_f32_32x32x16_bf16 v[50:65], v[190:193], v[194:197], v[50:65]
	s_waitcnt lgkmcnt(4)
	v_mfma_f32_32x32x16_bf16 v[18:33], v[190:193], v[202:205], v[18:33]
	v_mfma_f32_32x32x16_bf16 v[34:49], v[198:201], v[194:197], v[34:49]
	v_mfma_f32_32x32x16_bf16 v[2:17], v[198:201], v[202:205], v[2:17]
	ds_read_b128 v[190:193], v87
	ds_read_b128 v[194:197], v87 offset:4096
	ds_read_b128 v[198:201], v86 offset:32768
	ds_read_b128 v[202:205], v86 offset:36864
	v_lshl_add_u64 v[66:67], v[66:67], 0, s[98:99]
	v_lshl_add_u64 v[70:71], v[70:71], 0, s[98:99]
	v_lshl_add_u64 v[74:75], v[74:75], 0, s[98:99]
	v_lshl_add_u64 v[78:79], v[78:79], 0, s[98:99]
	v_lshl_add_u64 v[68:69], v[68:69], 0, s[98:99]
	v_lshl_add_u64 v[72:73], v[72:73], 0, s[98:99]
	v_lshl_add_u64 v[76:77], v[76:77], 0, s[98:99]
	v_lshl_add_u64 v[80:81], v[80:81], 0, s[98:99]
	s_waitcnt lgkmcnt(0)
	s_barrier
	s_add_u32 m0, s32, 0x0
	v_mfma_f32_32x32x16_bf16 v[50:65], v[162:165], v[182:185], v[50:65]
	global_load_lds_dwordx4 v[66:67], off
	s_add_u32 m0, s32, 0x1000
	v_mfma_f32_32x32x16_bf16 v[18:33], v[162:165], v[186:189], v[18:33]
	global_load_lds_dwordx4 v[70:71], off
	s_add_u32 m0, s32, 0x2000
	v_mfma_f32_32x32x16_bf16 v[34:49], v[166:169], v[182:185], v[34:49]
	global_load_lds_dwordx4 v[74:75], off
	s_add_u32 m0, s32, 0x3000
	v_mfma_f32_32x32x16_bf16 v[2:17], v[166:169], v[186:189], v[2:17]
	global_load_lds_dwordx4 v[78:79], off
	s_add_u32 m0, s32, 0x8000
	v_mfma_f32_32x32x16_bf16 v[50:65], v[190:193], v[198:201], v[50:65]
	global_load_lds_dwordx4 v[68:69], off
	s_add_u32 m0, s32, 0x9000
	v_mfma_f32_32x32x16_bf16 v[18:33], v[190:193], v[202:205], v[18:33]
	global_load_lds_dwordx4 v[72:73], off
	s_add_u32 m0, s32, 0xa000
	v_mfma_f32_32x32x16_bf16 v[34:49], v[194:197], v[198:201], v[34:49]
	global_load_lds_dwordx4 v[76:77], off
	s_add_u32 m0, s32, 0xb000
	v_mfma_f32_32x32x16_bf16 v[2:17], v[194:197], v[202:205], v[2:17]
	global_load_lds_dwordx4 v[80:81], off
	s_waitcnt vmcnt(8)
	s_barrier
	ds_read_b128 v[162:165], v91 offset:16384
	ds_read_b128 v[166:169], v92 offset:49152
	ds_read_b128 v[182:185], v91 offset:20480
	ds_read_b128 v[186:189], v92 offset:53248
	ds_read_b128 v[190:193], v93 offset:16384
	ds_read_b128 v[194:197], v90 offset:49152
	ds_read_b128 v[198:201], v93 offset:20480
	ds_read_b128 v[202:205], v90 offset:53248
	s_waitcnt lgkmcnt(6)
	v_mfma_f32_32x32x16_bf16 v[50:65], v[162:165], v[166:169], v[50:65]
	s_waitcnt lgkmcnt(4)
	v_mfma_f32_32x32x16_bf16 v[18:33], v[162:165], v[186:189], v[18:33]
	v_mfma_f32_32x32x16_bf16 v[34:49], v[182:185], v[166:169], v[34:49]
	v_mfma_f32_32x32x16_bf16 v[2:17], v[182:185], v[186:189], v[2:17]
	ds_read_b128 v[162:165], v89 offset:16384
	ds_read_b128 v[166:169], v89 offset:20480
	ds_read_b128 v[182:185], v88 offset:49152
	ds_read_b128 v[186:189], v88 offset:53248
	s_waitcnt lgkmcnt(6)
	v_mfma_f32_32x32x16_bf16 v[50:65], v[190:193], v[194:197], v[50:65]
	s_waitcnt lgkmcnt(4)
	v_mfma_f32_32x32x16_bf16 v[18:33], v[190:193], v[202:205], v[18:33]
	v_mfma_f32_32x32x16_bf16 v[34:49], v[198:201], v[194:197], v[34:49]
	v_mfma_f32_32x32x16_bf16 v[2:17], v[198:201], v[202:205], v[2:17]
	ds_read_b128 v[190:193], v87 offset:16384
	ds_read_b128 v[194:197], v87 offset:20480
	ds_read_b128 v[198:201], v86 offset:49152
	ds_read_b128 v[202:205], v86 offset:53248
	v_lshl_add_u64 v[66:67], v[66:67], 0, s[98:99]
	v_lshl_add_u64 v[70:71], v[70:71], 0, s[98:99]
	v_lshl_add_u64 v[74:75], v[74:75], 0, s[98:99]
	v_lshl_add_u64 v[78:79], v[78:79], 0, s[98:99]
	v_lshl_add_u64 v[68:69], v[68:69], 0, s[98:99]
	v_lshl_add_u64 v[72:73], v[72:73], 0, s[98:99]
	v_lshl_add_u64 v[76:77], v[76:77], 0, s[98:99]
	v_lshl_add_u64 v[80:81], v[80:81], 0, s[98:99]
	s_waitcnt lgkmcnt(0)
	s_barrier
	s_add_u32 m0, s32, 0x4000
	v_mfma_f32_32x32x16_bf16 v[50:65], v[162:165], v[182:185], v[50:65]
	global_load_lds_dwordx4 v[66:67], off
	s_add_u32 m0, s32, 0x5000
	v_mfma_f32_32x32x16_bf16 v[18:33], v[162:165], v[186:189], v[18:33]
	global_load_lds_dwordx4 v[70:71], off
	s_add_u32 m0, s32, 0x6000
	v_mfma_f32_32x32x16_bf16 v[34:49], v[166:169], v[182:185], v[34:49]
	global_load_lds_dwordx4 v[74:75], off
	s_add_u32 m0, s32, 0x7000
	v_mfma_f32_32x32x16_bf16 v[2:17], v[166:169], v[186:189], v[2:17]
	global_load_lds_dwordx4 v[78:79], off
	s_add_u32 m0, s32, 0xc000
	v_mfma_f32_32x32x16_bf16 v[50:65], v[190:193], v[198:201], v[50:65]
	global_load_lds_dwordx4 v[68:69], off
	s_add_u32 m0, s32, 0xd000
	v_mfma_f32_32x32x16_bf16 v[18:33], v[190:193], v[202:205], v[18:33]
	global_load_lds_dwordx4 v[72:73], off
	s_add_u32 m0, s32, 0xe000
	v_mfma_f32_32x32x16_bf16 v[34:49], v[194:197], v[198:201], v[34:49]
	global_load_lds_dwordx4 v[76:77], off
	s_add_u32 m0, s32, 0xf000
	v_mfma_f32_32x32x16_bf16 v[2:17], v[194:197], v[202:205], v[2:17]
	global_load_lds_dwordx4 v[80:81], off
	s_waitcnt vmcnt(8)
	s_barrier
	ds_read_b128 v[162:165], v91
	ds_read_b128 v[166:169], v92 offset:32768
	ds_read_b128 v[182:185], v91 offset:4096
	ds_read_b128 v[186:189], v92 offset:36864
	ds_read_b128 v[190:193], v93
	ds_read_b128 v[194:197], v90 offset:32768
	ds_read_b128 v[198:201], v93 offset:4096
	ds_read_b128 v[202:205], v90 offset:36864
	s_waitcnt lgkmcnt(6)
	v_mfma_f32_32x32x16_bf16 v[50:65], v[162:165], v[166:169], v[50:65]
	s_waitcnt lgkmcnt(4)
	v_mfma_f32_32x32x16_bf16 v[18:33], v[162:165], v[186:189], v[18:33]
	v_mfma_f32_32x32x16_bf16 v[34:49], v[182:185], v[166:169], v[34:49]
	v_mfma_f32_32x32x16_bf16 v[2:17], v[182:185], v[186:189], v[2:17]
	ds_read_b128 v[162:165], v89
	ds_read_b128 v[166:169], v89 offset:4096
	ds_read_b128 v[182:185], v88 offset:32768
	ds_read_b128 v[186:189], v88 offset:36864
	s_waitcnt lgkmcnt(6)
	v_mfma_f32_32x32x16_bf16 v[50:65], v[190:193], v[194:197], v[50:65]
	s_waitcnt lgkmcnt(4)
	v_mfma_f32_32x32x16_bf16 v[18:33], v[190:193], v[202:205], v[18:33]
	v_mfma_f32_32x32x16_bf16 v[34:49], v[198:201], v[194:197], v[34:49]
	v_mfma_f32_32x32x16_bf16 v[2:17], v[198:201], v[202:205], v[2:17]
	ds_read_b128 v[190:193], v87
	ds_read_b128 v[194:197], v87 offset:4096
	ds_read_b128 v[198:201], v86 offset:32768
	ds_read_b128 v[202:205], v86 offset:36864
	v_lshl_add_u64 v[66:67], v[66:67], 0, s[98:99]
	v_lshl_add_u64 v[70:71], v[70:71], 0, s[98:99]
	v_lshl_add_u64 v[74:75], v[74:75], 0, s[98:99]
	v_lshl_add_u64 v[78:79], v[78:79], 0, s[98:99]
	v_lshl_add_u64 v[68:69], v[68:69], 0, s[98:99]
	v_lshl_add_u64 v[72:73], v[72:73], 0, s[98:99]
	v_lshl_add_u64 v[76:77], v[76:77], 0, s[98:99]
	v_lshl_add_u64 v[80:81], v[80:81], 0, s[98:99]
	s_waitcnt lgkmcnt(0)
	s_barrier
	s_add_u32 m0, s32, 0x0
	v_mfma_f32_32x32x16_bf16 v[50:65], v[162:165], v[182:185], v[50:65]
	global_load_lds_dwordx4 v[66:67], off
	s_add_u32 m0, s32, 0x1000
	v_mfma_f32_32x32x16_bf16 v[18:33], v[162:165], v[186:189], v[18:33]
	global_load_lds_dwordx4 v[70:71], off
	s_add_u32 m0, s32, 0x2000
	v_mfma_f32_32x32x16_bf16 v[34:49], v[166:169], v[182:185], v[34:49]
	global_load_lds_dwordx4 v[74:75], off
	s_add_u32 m0, s32, 0x3000
	v_mfma_f32_32x32x16_bf16 v[2:17], v[166:169], v[186:189], v[2:17]
	global_load_lds_dwordx4 v[78:79], off
	s_add_u32 m0, s32, 0x8000
	v_mfma_f32_32x32x16_bf16 v[50:65], v[190:193], v[198:201], v[50:65]
	global_load_lds_dwordx4 v[68:69], off
	s_add_u32 m0, s32, 0x9000
	v_mfma_f32_32x32x16_bf16 v[18:33], v[190:193], v[202:205], v[18:33]
	global_load_lds_dwordx4 v[72:73], off
	s_add_u32 m0, s32, 0xa000
	v_mfma_f32_32x32x16_bf16 v[34:49], v[194:197], v[198:201], v[34:49]
	global_load_lds_dwordx4 v[76:77], off
	s_add_u32 m0, s32, 0xb000
	v_mfma_f32_32x32x16_bf16 v[2:17], v[194:197], v[202:205], v[2:17]
	global_load_lds_dwordx4 v[80:81], off
	s_waitcnt vmcnt(8)
	s_barrier
	ds_read_b128 v[162:165], v91 offset:16384
	ds_read_b128 v[166:169], v92 offset:49152
	ds_read_b128 v[182:185], v91 offset:20480
	ds_read_b128 v[186:189], v92 offset:53248
	ds_read_b128 v[190:193], v93 offset:16384
	ds_read_b128 v[194:197], v90 offset:49152
	ds_read_b128 v[198:201], v93 offset:20480
	ds_read_b128 v[202:205], v90 offset:53248
	s_waitcnt lgkmcnt(6)
	v_mfma_f32_32x32x16_bf16 v[50:65], v[162:165], v[166:169], v[50:65]
	s_waitcnt lgkmcnt(4)
	v_mfma_f32_32x32x16_bf16 v[18:33], v[162:165], v[186:189], v[18:33]
	v_mfma_f32_32x32x16_bf16 v[34:49], v[182:185], v[166:169], v[34:49]
	v_mfma_f32_32x32x16_bf16 v[2:17], v[182:185], v[186:189], v[2:17]
	ds_read_b128 v[162:165], v89 offset:16384
	ds_read_b128 v[166:169], v89 offset:20480
	ds_read_b128 v[182:185], v88 offset:49152
	ds_read_b128 v[186:189], v88 offset:53248
	s_waitcnt lgkmcnt(6)
	v_mfma_f32_32x32x16_bf16 v[50:65], v[190:193], v[194:197], v[50:65]
	s_waitcnt lgkmcnt(4)
	v_mfma_f32_32x32x16_bf16 v[18:33], v[190:193], v[202:205], v[18:33]
	v_mfma_f32_32x32x16_bf16 v[34:49], v[198:201], v[194:197], v[34:49]
	v_mfma_f32_32x32x16_bf16 v[2:17], v[198:201], v[202:205], v[2:17]
	ds_read_b128 v[190:193], v87 offset:16384
	ds_read_b128 v[194:197], v87 offset:20480
	ds_read_b128 v[198:201], v86 offset:49152
	ds_read_b128 v[202:205], v86 offset:53248
	v_lshl_add_u64 v[66:67], v[66:67], 0, s[98:99]
	v_lshl_add_u64 v[70:71], v[70:71], 0, s[98:99]
	v_lshl_add_u64 v[74:75], v[74:75], 0, s[98:99]
	v_lshl_add_u64 v[78:79], v[78:79], 0, s[98:99]
	v_lshl_add_u64 v[68:69], v[68:69], 0, s[98:99]
	v_lshl_add_u64 v[72:73], v[72:73], 0, s[98:99]
	v_lshl_add_u64 v[76:77], v[76:77], 0, s[98:99]
	v_lshl_add_u64 v[80:81], v[80:81], 0, s[98:99]
	s_waitcnt lgkmcnt(0)
	s_barrier
	s_add_u32 m0, s32, 0x4000
	v_mfma_f32_32x32x16_bf16 v[50:65], v[162:165], v[182:185], v[50:65]
	global_load_lds_dwordx4 v[66:67], off
	s_add_u32 m0, s32, 0x5000
	v_mfma_f32_32x32x16_bf16 v[18:33], v[162:165], v[186:189], v[18:33]
	global_load_lds_dwordx4 v[70:71], off
	s_add_u32 m0, s32, 0x6000
	v_mfma_f32_32x32x16_bf16 v[34:49], v[166:169], v[182:185], v[34:49]
	global_load_lds_dwordx4 v[74:75], off
	s_add_u32 m0, s32, 0x7000
	v_mfma_f32_32x32x16_bf16 v[2:17], v[166:169], v[186:189], v[2:17]
	global_load_lds_dwordx4 v[78:79], off
	s_add_u32 m0, s32, 0xc000
	v_mfma_f32_32x32x16_bf16 v[50:65], v[190:193], v[198:201], v[50:65]
	global_load_lds_dwordx4 v[68:69], off
	s_add_u32 m0, s32, 0xd000
	v_mfma_f32_32x32x16_bf16 v[18:33], v[190:193], v[202:205], v[18:33]
	global_load_lds_dwordx4 v[72:73], off
	s_add_u32 m0, s32, 0xe000
	v_mfma_f32_32x32x16_bf16 v[34:49], v[194:197], v[198:201], v[34:49]
	global_load_lds_dwordx4 v[76:77], off
	s_add_u32 m0, s32, 0xf000
	v_mfma_f32_32x32x16_bf16 v[2:17], v[194:197], v[202:205], v[2:17]
	global_load_lds_dwordx4 v[80:81], off
	s_waitcnt vmcnt(8)
	s_barrier
	ds_read_b128 v[162:165], v91
	ds_read_b128 v[166:169], v92 offset:32768
	ds_read_b128 v[182:185], v91 offset:4096
	ds_read_b128 v[186:189], v92 offset:36864
	ds_read_b128 v[190:193], v93
	ds_read_b128 v[194:197], v90 offset:32768
	ds_read_b128 v[198:201], v93 offset:4096
	ds_read_b128 v[202:205], v90 offset:36864
	s_waitcnt lgkmcnt(6)
	v_mfma_f32_32x32x16_bf16 v[50:65], v[162:165], v[166:169], v[50:65]
	s_waitcnt lgkmcnt(4)
	v_mfma_f32_32x32x16_bf16 v[18:33], v[162:165], v[186:189], v[18:33]
	v_mfma_f32_32x32x16_bf16 v[34:49], v[182:185], v[166:169], v[34:49]
	v_mfma_f32_32x32x16_bf16 v[2:17], v[182:185], v[186:189], v[2:17]
	ds_read_b128 v[162:165], v89
	ds_read_b128 v[166:169], v89 offset:4096
	ds_read_b128 v[182:185], v88 offset:32768
	ds_read_b128 v[186:189], v88 offset:36864
	s_waitcnt lgkmcnt(6)
	v_mfma_f32_32x32x16_bf16 v[50:65], v[190:193], v[194:197], v[50:65]
	s_waitcnt lgkmcnt(4)
	v_mfma_f32_32x32x16_bf16 v[18:33], v[190:193], v[202:205], v[18:33]
	v_mfma_f32_32x32x16_bf16 v[34:49], v[198:201], v[194:197], v[34:49]
	v_mfma_f32_32x32x16_bf16 v[2:17], v[198:201], v[202:205], v[2:17]
	ds_read_b128 v[190:193], v87
	ds_read_b128 v[194:197], v87 offset:4096
	ds_read_b128 v[198:201], v86 offset:32768
	ds_read_b128 v[202:205], v86 offset:36864
	v_lshl_add_u64 v[66:67], v[66:67], 0, s[98:99]
	v_lshl_add_u64 v[70:71], v[70:71], 0, s[98:99]
	v_lshl_add_u64 v[74:75], v[74:75], 0, s[98:99]
	v_lshl_add_u64 v[78:79], v[78:79], 0, s[98:99]
	v_lshl_add_u64 v[68:69], v[68:69], 0, s[98:99]
	v_lshl_add_u64 v[72:73], v[72:73], 0, s[98:99]
	v_lshl_add_u64 v[76:77], v[76:77], 0, s[98:99]
	v_lshl_add_u64 v[80:81], v[80:81], 0, s[98:99]
	s_waitcnt lgkmcnt(0)
	s_barrier
	s_add_u32 m0, s32, 0x0
	v_mfma_f32_32x32x16_bf16 v[50:65], v[162:165], v[182:185], v[50:65]
	global_load_lds_dwordx4 v[66:67], off
	s_add_u32 m0, s32, 0x1000
	v_mfma_f32_32x32x16_bf16 v[18:33], v[162:165], v[186:189], v[18:33]
	global_load_lds_dwordx4 v[70:71], off
	s_add_u32 m0, s32, 0x2000
	v_mfma_f32_32x32x16_bf16 v[34:49], v[166:169], v[182:185], v[34:49]
	global_load_lds_dwordx4 v[74:75], off
	s_add_u32 m0, s32, 0x3000
	v_mfma_f32_32x32x16_bf16 v[2:17], v[166:169], v[186:189], v[2:17]
	global_load_lds_dwordx4 v[78:79], off
	s_add_u32 m0, s32, 0x8000
	v_mfma_f32_32x32x16_bf16 v[50:65], v[190:193], v[198:201], v[50:65]
	global_load_lds_dwordx4 v[68:69], off
	s_add_u32 m0, s32, 0x9000
	v_mfma_f32_32x32x16_bf16 v[18:33], v[190:193], v[202:205], v[18:33]
	global_load_lds_dwordx4 v[72:73], off
	s_add_u32 m0, s32, 0xa000
	v_mfma_f32_32x32x16_bf16 v[34:49], v[194:197], v[198:201], v[34:49]
	global_load_lds_dwordx4 v[76:77], off
	s_add_u32 m0, s32, 0xb000
	v_mfma_f32_32x32x16_bf16 v[2:17], v[194:197], v[202:205], v[2:17]
	global_load_lds_dwordx4 v[80:81], off
	s_waitcnt vmcnt(8)
	s_barrier
	ds_read_b128 v[162:165], v91 offset:16384
	ds_read_b128 v[166:169], v92 offset:49152
	ds_read_b128 v[182:185], v91 offset:20480
	ds_read_b128 v[186:189], v92 offset:53248
	ds_read_b128 v[190:193], v93 offset:16384
	ds_read_b128 v[194:197], v90 offset:49152
	ds_read_b128 v[198:201], v93 offset:20480
	ds_read_b128 v[202:205], v90 offset:53248
	s_waitcnt lgkmcnt(6)
	v_mfma_f32_32x32x16_bf16 v[50:65], v[162:165], v[166:169], v[50:65]
	s_waitcnt lgkmcnt(4)
	v_mfma_f32_32x32x16_bf16 v[18:33], v[162:165], v[186:189], v[18:33]
	v_mfma_f32_32x32x16_bf16 v[34:49], v[182:185], v[166:169], v[34:49]
	v_mfma_f32_32x32x16_bf16 v[2:17], v[182:185], v[186:189], v[2:17]
	ds_read_b128 v[162:165], v89 offset:16384
	ds_read_b128 v[166:169], v89 offset:20480
	ds_read_b128 v[182:185], v88 offset:49152
	ds_read_b128 v[186:189], v88 offset:53248
	s_waitcnt lgkmcnt(6)
	v_mfma_f32_32x32x16_bf16 v[50:65], v[190:193], v[194:197], v[50:65]
	s_waitcnt lgkmcnt(4)
	v_mfma_f32_32x32x16_bf16 v[18:33], v[190:193], v[202:205], v[18:33]
	v_mfma_f32_32x32x16_bf16 v[34:49], v[198:201], v[194:197], v[34:49]
	v_mfma_f32_32x32x16_bf16 v[2:17], v[198:201], v[202:205], v[2:17]
	ds_read_b128 v[190:193], v87 offset:16384
	ds_read_b128 v[194:197], v87 offset:20480
	ds_read_b128 v[198:201], v86 offset:49152
	ds_read_b128 v[202:205], v86 offset:53248
	v_lshl_add_u64 v[66:67], v[66:67], 0, s[98:99]
	v_lshl_add_u64 v[70:71], v[70:71], 0, s[98:99]
	v_lshl_add_u64 v[74:75], v[74:75], 0, s[98:99]
	v_lshl_add_u64 v[78:79], v[78:79], 0, s[98:99]
	v_lshl_add_u64 v[68:69], v[68:69], 0, s[98:99]
	v_lshl_add_u64 v[72:73], v[72:73], 0, s[98:99]
	v_lshl_add_u64 v[76:77], v[76:77], 0, s[98:99]
	v_lshl_add_u64 v[80:81], v[80:81], 0, s[98:99]
	s_waitcnt lgkmcnt(0)
	s_barrier
	s_add_u32 m0, s32, 0x4000
	v_mfma_f32_32x32x16_bf16 v[50:65], v[162:165], v[182:185], v[50:65]
	global_load_lds_dwordx4 v[66:67], off
	s_add_u32 m0, s32, 0x5000
	v_mfma_f32_32x32x16_bf16 v[18:33], v[162:165], v[186:189], v[18:33]
	global_load_lds_dwordx4 v[70:71], off
	s_add_u32 m0, s32, 0x6000
	v_mfma_f32_32x32x16_bf16 v[34:49], v[166:169], v[182:185], v[34:49]
	global_load_lds_dwordx4 v[74:75], off
	s_add_u32 m0, s32, 0x7000
	v_mfma_f32_32x32x16_bf16 v[2:17], v[166:169], v[186:189], v[2:17]
	global_load_lds_dwordx4 v[78:79], off
	s_add_u32 m0, s32, 0xc000
	v_mfma_f32_32x32x16_bf16 v[50:65], v[190:193], v[198:201], v[50:65]
	global_load_lds_dwordx4 v[68:69], off
	s_add_u32 m0, s32, 0xd000
	v_mfma_f32_32x32x16_bf16 v[18:33], v[190:193], v[202:205], v[18:33]
	global_load_lds_dwordx4 v[72:73], off
	s_add_u32 m0, s32, 0xe000
	v_mfma_f32_32x32x16_bf16 v[34:49], v[194:197], v[198:201], v[34:49]
	global_load_lds_dwordx4 v[76:77], off
	s_add_u32 m0, s32, 0xf000
	v_mfma_f32_32x32x16_bf16 v[2:17], v[194:197], v[202:205], v[2:17]
	global_load_lds_dwordx4 v[80:81], off
	s_waitcnt vmcnt(8)
	s_barrier
	ds_read_b128 v[162:165], v91
	ds_read_b128 v[166:169], v92 offset:32768
	ds_read_b128 v[182:185], v91 offset:4096
	ds_read_b128 v[186:189], v92 offset:36864
	ds_read_b128 v[190:193], v93
	ds_read_b128 v[194:197], v90 offset:32768
	ds_read_b128 v[198:201], v93 offset:4096
	ds_read_b128 v[202:205], v90 offset:36864
	s_waitcnt lgkmcnt(6)
	v_mfma_f32_32x32x16_bf16 v[50:65], v[162:165], v[166:169], v[50:65]
	s_waitcnt lgkmcnt(4)
	v_mfma_f32_32x32x16_bf16 v[18:33], v[162:165], v[186:189], v[18:33]
	v_mfma_f32_32x32x16_bf16 v[34:49], v[182:185], v[166:169], v[34:49]
	v_mfma_f32_32x32x16_bf16 v[2:17], v[182:185], v[186:189], v[2:17]
	ds_read_b128 v[162:165], v89
	ds_read_b128 v[166:169], v89 offset:4096
	ds_read_b128 v[182:185], v88 offset:32768
	ds_read_b128 v[186:189], v88 offset:36864
	s_waitcnt lgkmcnt(6)
	v_mfma_f32_32x32x16_bf16 v[50:65], v[190:193], v[194:197], v[50:65]
	s_waitcnt lgkmcnt(4)
	v_mfma_f32_32x32x16_bf16 v[18:33], v[190:193], v[202:205], v[18:33]
	v_mfma_f32_32x32x16_bf16 v[34:49], v[198:201], v[194:197], v[34:49]
	v_mfma_f32_32x32x16_bf16 v[2:17], v[198:201], v[202:205], v[2:17]
	ds_read_b128 v[190:193], v87
	ds_read_b128 v[194:197], v87 offset:4096
	ds_read_b128 v[198:201], v86 offset:32768
	ds_read_b128 v[202:205], v86 offset:36864
	v_lshl_add_u64 v[66:67], v[66:67], 0, s[98:99]
	v_lshl_add_u64 v[70:71], v[70:71], 0, s[98:99]
	v_lshl_add_u64 v[74:75], v[74:75], 0, s[98:99]
	v_lshl_add_u64 v[78:79], v[78:79], 0, s[98:99]
	v_lshl_add_u64 v[68:69], v[68:69], 0, s[98:99]
	v_lshl_add_u64 v[72:73], v[72:73], 0, s[98:99]
	v_lshl_add_u64 v[76:77], v[76:77], 0, s[98:99]
	v_lshl_add_u64 v[80:81], v[80:81], 0, s[98:99]
	s_waitcnt lgkmcnt(0)
	s_barrier
	s_add_u32 m0, s32, 0x0
	v_mfma_f32_32x32x16_bf16 v[50:65], v[162:165], v[182:185], v[50:65]
	global_load_lds_dwordx4 v[66:67], off
	s_add_u32 m0, s32, 0x1000
	v_mfma_f32_32x32x16_bf16 v[18:33], v[162:165], v[186:189], v[18:33]
	global_load_lds_dwordx4 v[70:71], off
	s_add_u32 m0, s32, 0x2000
	v_mfma_f32_32x32x16_bf16 v[34:49], v[166:169], v[182:185], v[34:49]
	global_load_lds_dwordx4 v[74:75], off
	s_add_u32 m0, s32, 0x3000
	v_mfma_f32_32x32x16_bf16 v[2:17], v[166:169], v[186:189], v[2:17]
	global_load_lds_dwordx4 v[78:79], off
	s_add_u32 m0, s32, 0x8000
	v_mfma_f32_32x32x16_bf16 v[50:65], v[190:193], v[198:201], v[50:65]
	global_load_lds_dwordx4 v[68:69], off
	s_add_u32 m0, s32, 0x9000
	v_mfma_f32_32x32x16_bf16 v[18:33], v[190:193], v[202:205], v[18:33]
	global_load_lds_dwordx4 v[72:73], off
	s_add_u32 m0, s32, 0xa000
	v_mfma_f32_32x32x16_bf16 v[34:49], v[194:197], v[198:201], v[34:49]
	global_load_lds_dwordx4 v[76:77], off
	s_add_u32 m0, s32, 0xb000
	v_mfma_f32_32x32x16_bf16 v[2:17], v[194:197], v[202:205], v[2:17]
	global_load_lds_dwordx4 v[80:81], off
	s_waitcnt vmcnt(8)
	s_barrier
	ds_read_b128 v[162:165], v91 offset:16384
	ds_read_b128 v[166:169], v92 offset:49152
	ds_read_b128 v[182:185], v91 offset:20480
	ds_read_b128 v[186:189], v92 offset:53248
	ds_read_b128 v[190:193], v93 offset:16384
	ds_read_b128 v[194:197], v90 offset:49152
	ds_read_b128 v[198:201], v93 offset:20480
	ds_read_b128 v[202:205], v90 offset:53248
	s_waitcnt lgkmcnt(6)
	v_mfma_f32_32x32x16_bf16 v[50:65], v[162:165], v[166:169], v[50:65]
	s_waitcnt lgkmcnt(4)
	v_mfma_f32_32x32x16_bf16 v[18:33], v[162:165], v[186:189], v[18:33]
	v_mfma_f32_32x32x16_bf16 v[34:49], v[182:185], v[166:169], v[34:49]
	v_mfma_f32_32x32x16_bf16 v[2:17], v[182:185], v[186:189], v[2:17]
	ds_read_b128 v[162:165], v89 offset:16384
	ds_read_b128 v[166:169], v89 offset:20480
	ds_read_b128 v[182:185], v88 offset:49152
	ds_read_b128 v[186:189], v88 offset:53248
	s_waitcnt lgkmcnt(6)
	v_mfma_f32_32x32x16_bf16 v[50:65], v[190:193], v[194:197], v[50:65]
	s_waitcnt lgkmcnt(4)
	v_mfma_f32_32x32x16_bf16 v[18:33], v[190:193], v[202:205], v[18:33]
	v_mfma_f32_32x32x16_bf16 v[34:49], v[198:201], v[194:197], v[34:49]
	v_mfma_f32_32x32x16_bf16 v[2:17], v[198:201], v[202:205], v[2:17]
	ds_read_b128 v[190:193], v87 offset:16384
	ds_read_b128 v[194:197], v87 offset:20480
	ds_read_b128 v[198:201], v86 offset:49152
	ds_read_b128 v[202:205], v86 offset:53248
	v_lshl_add_u64 v[66:67], v[66:67], 0, s[98:99]
	v_lshl_add_u64 v[70:71], v[70:71], 0, s[98:99]
	v_lshl_add_u64 v[74:75], v[74:75], 0, s[98:99]
	v_lshl_add_u64 v[78:79], v[78:79], 0, s[98:99]
	v_lshl_add_u64 v[68:69], v[68:69], 0, s[98:99]
	v_lshl_add_u64 v[72:73], v[72:73], 0, s[98:99]
	v_lshl_add_u64 v[76:77], v[76:77], 0, s[98:99]
	v_lshl_add_u64 v[80:81], v[80:81], 0, s[98:99]
	s_waitcnt lgkmcnt(0)
	s_barrier
	s_add_u32 m0, s32, 0x4000
	v_mfma_f32_32x32x16_bf16 v[50:65], v[162:165], v[182:185], v[50:65]
	global_load_lds_dwordx4 v[66:67], off
	s_add_u32 m0, s32, 0x5000
	v_mfma_f32_32x32x16_bf16 v[18:33], v[162:165], v[186:189], v[18:33]
	global_load_lds_dwordx4 v[70:71], off
	s_add_u32 m0, s32, 0x6000
	v_mfma_f32_32x32x16_bf16 v[34:49], v[166:169], v[182:185], v[34:49]
	global_load_lds_dwordx4 v[74:75], off
	s_add_u32 m0, s32, 0x7000
	v_mfma_f32_32x32x16_bf16 v[2:17], v[166:169], v[186:189], v[2:17]
	global_load_lds_dwordx4 v[78:79], off
	s_add_u32 m0, s32, 0xc000
	v_mfma_f32_32x32x16_bf16 v[50:65], v[190:193], v[198:201], v[50:65]
	global_load_lds_dwordx4 v[68:69], off
	s_add_u32 m0, s32, 0xd000
	v_mfma_f32_32x32x16_bf16 v[18:33], v[190:193], v[202:205], v[18:33]
	global_load_lds_dwordx4 v[72:73], off
	s_add_u32 m0, s32, 0xe000
	v_mfma_f32_32x32x16_bf16 v[34:49], v[194:197], v[198:201], v[34:49]
	global_load_lds_dwordx4 v[76:77], off
	s_add_u32 m0, s32, 0xf000
	v_mfma_f32_32x32x16_bf16 v[2:17], v[194:197], v[202:205], v[2:17]
	global_load_lds_dwordx4 v[80:81], off
	s_waitcnt vmcnt(8)
	s_barrier
	ds_read_b128 v[162:165], v91
	ds_read_b128 v[166:169], v92 offset:32768
	ds_read_b128 v[182:185], v91 offset:4096
	ds_read_b128 v[186:189], v92 offset:36864
	ds_read_b128 v[190:193], v93
	ds_read_b128 v[194:197], v90 offset:32768
	ds_read_b128 v[198:201], v93 offset:4096
	ds_read_b128 v[202:205], v90 offset:36864
	s_waitcnt lgkmcnt(6)
	v_mfma_f32_32x32x16_bf16 v[50:65], v[162:165], v[166:169], v[50:65]
	s_waitcnt lgkmcnt(4)
	v_mfma_f32_32x32x16_bf16 v[18:33], v[162:165], v[186:189], v[18:33]
	v_mfma_f32_32x32x16_bf16 v[34:49], v[182:185], v[166:169], v[34:49]
	v_mfma_f32_32x32x16_bf16 v[2:17], v[182:185], v[186:189], v[2:17]
	ds_read_b128 v[162:165], v89
	ds_read_b128 v[166:169], v89 offset:4096
	ds_read_b128 v[182:185], v88 offset:32768
	ds_read_b128 v[186:189], v88 offset:36864
	s_waitcnt lgkmcnt(6)
	v_mfma_f32_32x32x16_bf16 v[50:65], v[190:193], v[194:197], v[50:65]
	s_waitcnt lgkmcnt(4)
	v_mfma_f32_32x32x16_bf16 v[18:33], v[190:193], v[202:205], v[18:33]
	v_mfma_f32_32x32x16_bf16 v[34:49], v[198:201], v[194:197], v[34:49]
	v_mfma_f32_32x32x16_bf16 v[2:17], v[198:201], v[202:205], v[2:17]
	ds_read_b128 v[190:193], v87
	ds_read_b128 v[194:197], v87 offset:4096
	ds_read_b128 v[198:201], v86 offset:32768
	ds_read_b128 v[202:205], v86 offset:36864
	v_lshl_add_u64 v[66:67], v[66:67], 0, s[98:99]
	v_lshl_add_u64 v[70:71], v[70:71], 0, s[98:99]
	v_lshl_add_u64 v[74:75], v[74:75], 0, s[98:99]
	v_lshl_add_u64 v[78:79], v[78:79], 0, s[98:99]
	v_lshl_add_u64 v[68:69], v[68:69], 0, s[98:99]
	v_lshl_add_u64 v[72:73], v[72:73], 0, s[98:99]
	v_lshl_add_u64 v[76:77], v[76:77], 0, s[98:99]
	v_lshl_add_u64 v[80:81], v[80:81], 0, s[98:99]
	s_waitcnt lgkmcnt(0)
	s_barrier
	s_add_u32 m0, s32, 0x0
	v_mfma_f32_32x32x16_bf16 v[50:65], v[162:165], v[182:185], v[50:65]
	global_load_lds_dwordx4 v[66:67], off
	s_add_u32 m0, s32, 0x1000
	v_mfma_f32_32x32x16_bf16 v[18:33], v[162:165], v[186:189], v[18:33]
	global_load_lds_dwordx4 v[70:71], off
	s_add_u32 m0, s32, 0x2000
	v_mfma_f32_32x32x16_bf16 v[34:49], v[166:169], v[182:185], v[34:49]
	global_load_lds_dwordx4 v[74:75], off
	s_add_u32 m0, s32, 0x3000
	v_mfma_f32_32x32x16_bf16 v[2:17], v[166:169], v[186:189], v[2:17]
	global_load_lds_dwordx4 v[78:79], off
	s_add_u32 m0, s32, 0x8000
	v_mfma_f32_32x32x16_bf16 v[50:65], v[190:193], v[198:201], v[50:65]
	global_load_lds_dwordx4 v[68:69], off
	s_add_u32 m0, s32, 0x9000
	v_mfma_f32_32x32x16_bf16 v[18:33], v[190:193], v[202:205], v[18:33]
	global_load_lds_dwordx4 v[72:73], off
	s_add_u32 m0, s32, 0xa000
	v_mfma_f32_32x32x16_bf16 v[34:49], v[194:197], v[198:201], v[34:49]
	global_load_lds_dwordx4 v[76:77], off
	s_add_u32 m0, s32, 0xb000
	v_mfma_f32_32x32x16_bf16 v[2:17], v[194:197], v[202:205], v[2:17]
	global_load_lds_dwordx4 v[80:81], off
	s_waitcnt vmcnt(8)
	s_barrier
	ds_read_b128 v[162:165], v91 offset:16384
	ds_read_b128 v[166:169], v92 offset:49152
	ds_read_b128 v[182:185], v91 offset:20480
	ds_read_b128 v[186:189], v92 offset:53248
	ds_read_b128 v[190:193], v93 offset:16384
	ds_read_b128 v[194:197], v90 offset:49152
	ds_read_b128 v[198:201], v93 offset:20480
	ds_read_b128 v[202:205], v90 offset:53248
	s_waitcnt lgkmcnt(6)
	v_mfma_f32_32x32x16_bf16 v[50:65], v[162:165], v[166:169], v[50:65]
	s_waitcnt lgkmcnt(4)
	v_mfma_f32_32x32x16_bf16 v[18:33], v[162:165], v[186:189], v[18:33]
	v_mfma_f32_32x32x16_bf16 v[34:49], v[182:185], v[166:169], v[34:49]
	v_mfma_f32_32x32x16_bf16 v[2:17], v[182:185], v[186:189], v[2:17]
	ds_read_b128 v[162:165], v89 offset:16384
	ds_read_b128 v[166:169], v89 offset:20480
	ds_read_b128 v[182:185], v88 offset:49152
	ds_read_b128 v[186:189], v88 offset:53248
	s_waitcnt lgkmcnt(6)
	v_mfma_f32_32x32x16_bf16 v[50:65], v[190:193], v[194:197], v[50:65]
	s_waitcnt lgkmcnt(4)
	v_mfma_f32_32x32x16_bf16 v[18:33], v[190:193], v[202:205], v[18:33]
	v_mfma_f32_32x32x16_bf16 v[34:49], v[198:201], v[194:197], v[34:49]
	v_mfma_f32_32x32x16_bf16 v[2:17], v[198:201], v[202:205], v[2:17]
	ds_read_b128 v[190:193], v87 offset:16384
	ds_read_b128 v[194:197], v87 offset:20480
	ds_read_b128 v[198:201], v86 offset:49152
	ds_read_b128 v[202:205], v86 offset:53248
	v_lshl_add_u64 v[66:67], v[66:67], 0, s[98:99]
	v_lshl_add_u64 v[70:71], v[70:71], 0, s[98:99]
	v_lshl_add_u64 v[74:75], v[74:75], 0, s[98:99]
	v_lshl_add_u64 v[78:79], v[78:79], 0, s[98:99]
	v_lshl_add_u64 v[68:69], v[68:69], 0, s[98:99]
	v_lshl_add_u64 v[72:73], v[72:73], 0, s[98:99]
	v_lshl_add_u64 v[76:77], v[76:77], 0, s[98:99]
	v_lshl_add_u64 v[80:81], v[80:81], 0, s[98:99]
	s_waitcnt lgkmcnt(0)
	s_barrier
	s_add_u32 m0, s32, 0x4000
	v_mfma_f32_32x32x16_bf16 v[50:65], v[162:165], v[182:185], v[50:65]
	global_load_lds_dwordx4 v[66:67], off
	s_add_u32 m0, s32, 0x5000
	v_mfma_f32_32x32x16_bf16 v[18:33], v[162:165], v[186:189], v[18:33]
	global_load_lds_dwordx4 v[70:71], off
	s_add_u32 m0, s32, 0x6000
	v_mfma_f32_32x32x16_bf16 v[34:49], v[166:169], v[182:185], v[34:49]
	global_load_lds_dwordx4 v[74:75], off
	s_add_u32 m0, s32, 0x7000
	v_mfma_f32_32x32x16_bf16 v[2:17], v[166:169], v[186:189], v[2:17]
	global_load_lds_dwordx4 v[78:79], off
	s_add_u32 m0, s32, 0xc000
	v_mfma_f32_32x32x16_bf16 v[50:65], v[190:193], v[198:201], v[50:65]
	global_load_lds_dwordx4 v[68:69], off
	s_add_u32 m0, s32, 0xd000
	v_mfma_f32_32x32x16_bf16 v[18:33], v[190:193], v[202:205], v[18:33]
	global_load_lds_dwordx4 v[72:73], off
	s_add_u32 m0, s32, 0xe000
	v_mfma_f32_32x32x16_bf16 v[34:49], v[194:197], v[198:201], v[34:49]
	global_load_lds_dwordx4 v[76:77], off
	s_add_u32 m0, s32, 0xf000
	v_mfma_f32_32x32x16_bf16 v[2:17], v[194:197], v[202:205], v[2:17]
	global_load_lds_dwordx4 v[80:81], off
	s_waitcnt vmcnt(8)
	s_barrier
	ds_read_b128 v[162:165], v91
	ds_read_b128 v[166:169], v92 offset:32768
	ds_read_b128 v[182:185], v91 offset:4096
	ds_read_b128 v[186:189], v92 offset:36864
	ds_read_b128 v[190:193], v93
	ds_read_b128 v[194:197], v90 offset:32768
	ds_read_b128 v[198:201], v93 offset:4096
	ds_read_b128 v[202:205], v90 offset:36864
	s_waitcnt lgkmcnt(6)
	v_mfma_f32_32x32x16_bf16 v[50:65], v[162:165], v[166:169], v[50:65]
	s_waitcnt lgkmcnt(4)
	v_mfma_f32_32x32x16_bf16 v[18:33], v[162:165], v[186:189], v[18:33]
	v_mfma_f32_32x32x16_bf16 v[34:49], v[182:185], v[166:169], v[34:49]
	v_mfma_f32_32x32x16_bf16 v[2:17], v[182:185], v[186:189], v[2:17]
	ds_read_b128 v[162:165], v89
	ds_read_b128 v[166:169], v89 offset:4096
	ds_read_b128 v[182:185], v88 offset:32768
	ds_read_b128 v[186:189], v88 offset:36864
	s_waitcnt lgkmcnt(6)
	v_mfma_f32_32x32x16_bf16 v[50:65], v[190:193], v[194:197], v[50:65]
	s_waitcnt lgkmcnt(4)
	v_mfma_f32_32x32x16_bf16 v[18:33], v[190:193], v[202:205], v[18:33]
	v_mfma_f32_32x32x16_bf16 v[34:49], v[198:201], v[194:197], v[34:49]
	v_mfma_f32_32x32x16_bf16 v[2:17], v[198:201], v[202:205], v[2:17]
	ds_read_b128 v[190:193], v87
	ds_read_b128 v[194:197], v87 offset:4096
	ds_read_b128 v[198:201], v86 offset:32768
	ds_read_b128 v[202:205], v86 offset:36864
	v_lshl_add_u64 v[66:67], v[66:67], 0, s[98:99]
	v_lshl_add_u64 v[70:71], v[70:71], 0, s[98:99]
	v_lshl_add_u64 v[74:75], v[74:75], 0, s[98:99]
	v_lshl_add_u64 v[78:79], v[78:79], 0, s[98:99]
	v_lshl_add_u64 v[68:69], v[68:69], 0, s[98:99]
	v_lshl_add_u64 v[72:73], v[72:73], 0, s[98:99]
	v_lshl_add_u64 v[76:77], v[76:77], 0, s[98:99]
	v_lshl_add_u64 v[80:81], v[80:81], 0, s[98:99]
	s_waitcnt lgkmcnt(0)
	s_barrier
	s_add_u32 m0, s32, 0x0
	s_nop 0
	global_load_lds_dwordx4 v[66:67], off
	s_add_u32 m0, s32, 0x1000
	s_nop 0
	global_load_lds_dwordx4 v[70:71], off
	s_add_u32 m0, s32, 0x2000
	s_nop 0
	global_load_lds_dwordx4 v[74:75], off
	s_add_u32 m0, s32, 0x3000
	s_nop 0
	global_load_lds_dwordx4 v[78:79], off
	s_add_u32 m0, s32, 0x8000
	s_nop 0
	global_load_lds_dwordx4 v[68:69], off
	s_add_u32 m0, s32, 0x9000
	s_nop 0
	global_load_lds_dwordx4 v[72:73], off
	s_add_u32 m0, s32, 0xa000
	s_nop 0
	global_load_lds_dwordx4 v[76:77], off
	s_add_u32 m0, s32, 0xb000
	s_nop 0
	global_load_lds_dwordx4 v[80:81], off
	s_waitcnt vmcnt(8)
	s_barrier
	s_nop 0
	s_nop 0
	s_nop 0
	s_nop 0
	s_nop 0
	s_nop 0
	s_nop 0
	v_mfma_f32_32x32x16_bf16 v[50:65], v[162:165], v[182:185], v[50:65]
	v_mfma_f32_32x32x16_bf16 v[18:33], v[162:165], v[186:189], v[18:33]
	v_mfma_f32_32x32x16_bf16 v[34:49], v[166:169], v[182:185], v[34:49]
	v_mfma_f32_32x32x16_bf16 v[2:17], v[166:169], v[186:189], v[2:17]
	ds_read_b128 v[110:113], v91 offset:16384
	ds_read_b128 v[114:117], v91 offset:20480
	ds_read_b128 v[118:121], v92 offset:49152
	ds_read_b128 v[122:125], v92 offset:53248
	ds_read_b128 v[162:165], v93 offset:16384
	ds_read_b128 v[166:169], v93 offset:20480
	ds_read_b128 v[182:185], v90 offset:49152
	ds_read_b128 v[186:189], v90 offset:53248
	v_mfma_f32_32x32x16_bf16 v[50:65], v[190:193], v[198:201], v[50:65]
	v_mfma_f32_32x32x16_bf16 v[18:33], v[190:193], v[202:205], v[18:33]
	v_mfma_f32_32x32x16_bf16 v[34:49], v[194:197], v[198:201], v[34:49]
	v_mfma_f32_32x32x16_bf16 v[2:17], v[194:197], v[202:205], v[2:17]
	s_waitcnt lgkmcnt(5)
	v_mfma_f32_32x32x16_bf16 v[50:65], v[110:113], v[118:121], v[50:65]
	s_waitcnt lgkmcnt(4)
	v_mfma_f32_32x32x16_bf16 v[18:33], v[110:113], v[122:125], v[18:33]
	v_mfma_f32_32x32x16_bf16 v[34:49], v[114:117], v[118:121], v[34:49]
	v_mfma_f32_32x32x16_bf16 v[2:17], v[114:117], v[122:125], v[2:17]
	ds_read_b128 v[110:113], v89 offset:16384
	ds_read_b128 v[114:117], v89 offset:20480
	ds_read_b128 v[118:121], v88 offset:49152
	ds_read_b128 v[122:125], v88 offset:53248
	s_waitcnt lgkmcnt(5)
	v_mfma_f32_32x32x16_bf16 v[50:65], v[162:165], v[182:185], v[50:65]
	s_waitcnt lgkmcnt(4)
	v_mfma_f32_32x32x16_bf16 v[18:33], v[162:165], v[186:189], v[18:33]
	v_mfma_f32_32x32x16_bf16 v[34:49], v[166:169], v[182:185], v[34:49]
	v_mfma_f32_32x32x16_bf16 v[2:17], v[166:169], v[186:189], v[2:17]
	ds_read_b128 v[162:165], v87 offset:16384
	ds_read_b128 v[166:169], v87 offset:20480
	ds_read_b128 v[182:185], v86 offset:49152
	ds_read_b128 v[186:189], v86 offset:53248
	s_waitcnt lgkmcnt(5)
	v_mfma_f32_32x32x16_bf16 v[50:65], v[110:113], v[118:121], v[50:65]
	v_lshl_add_u64 v[66:67], v[66:67], 0, s[98:99]
	v_lshl_add_u64 v[70:71], v[70:71], 0, s[98:99]
	v_lshl_add_u64 v[74:75], v[74:75], 0, s[98:99]
	v_lshl_add_u64 v[78:79], v[78:79], 0, s[98:99]
	v_lshl_add_u64 v[68:69], v[68:69], 0, s[98:99]
	v_lshl_add_u64 v[72:73], v[72:73], 0, s[98:99]
	v_lshl_add_u64 v[76:77], v[76:77], 0, s[98:99]
	v_lshl_add_u64 v[80:81], v[80:81], 0, s[98:99]
	s_waitcnt lgkmcnt(0)
	s_barrier
	s_add_u32 m0, s32, 0x4000
	s_nop 0
	global_load_lds_dwordx4 v[66:67], off
	s_add_u32 m0, s32, 0x5000
	s_nop 0
	global_load_lds_dwordx4 v[70:71], off
	s_add_u32 m0, s32, 0x6000
	s_nop 0
	global_load_lds_dwordx4 v[74:75], off
	s_add_u32 m0, s32, 0x7000
	s_nop 0
	global_load_lds_dwordx4 v[78:79], off
	s_add_u32 m0, s32, 0xc000
	s_nop 0
	global_load_lds_dwordx4 v[68:69], off
	s_add_u32 m0, s32, 0xd000
	s_nop 0
	global_load_lds_dwordx4 v[72:73], off
	s_add_u32 m0, s32, 0xe000
	s_nop 0
	global_load_lds_dwordx4 v[76:77], off
	s_add_u32 m0, s32, 0xf000
	s_nop 0
	global_load_lds_dwordx4 v[80:81], off
	s_waitcnt vmcnt(8)
	s_barrier
	v_mfma_f32_32x32x16_bf16 v[18:33], v[110:113], v[122:125], v[18:33]
	v_mfma_f32_32x32x16_bf16 v[34:49], v[114:117], v[118:121], v[34:49]
	v_mfma_f32_32x32x16_bf16 v[2:17], v[114:117], v[122:125], v[2:17]
	ds_read_b128 v[110:113], v91
	ds_read_b128 v[114:117], v91 offset:4096
	ds_read_b128 v[118:121], v92 offset:32768
	ds_read_b128 v[122:125], v92 offset:36864
	ds_read_b128 v[126:129], v93
	ds_read_b128 v[134:137], v93 offset:4096
	ds_read_b128 v[138:141], v90 offset:32768
	ds_read_b128 v[142:145], v90 offset:36864
	v_mfma_f32_32x32x16_bf16 v[50:65], v[162:165], v[182:185], v[50:65]
	v_mfma_f32_32x32x16_bf16 v[18:33], v[162:165], v[186:189], v[18:33]
	v_mfma_f32_32x32x16_bf16 v[34:49], v[166:169], v[182:185], v[34:49]
	v_mfma_f32_32x32x16_bf16 v[2:17], v[166:169], v[186:189], v[2:17]
	s_waitcnt lgkmcnt(5)
	v_mfma_f32_32x32x16_bf16 v[50:65], v[110:113], v[118:121], v[50:65]
	s_waitcnt lgkmcnt(4)
	v_mfma_f32_32x32x16_bf16 v[18:33], v[110:113], v[122:125], v[18:33]
	v_mfma_f32_32x32x16_bf16 v[34:49], v[114:117], v[118:121], v[34:49]
	v_mfma_f32_32x32x16_bf16 v[2:17], v[114:117], v[122:125], v[2:17]
	ds_read_b128 v[110:113], v89
	ds_read_b128 v[114:117], v89 offset:4096
	ds_read_b128 v[118:121], v88 offset:32768
	ds_read_b128 v[122:125], v88 offset:36864
	s_waitcnt lgkmcnt(5)
	v_mfma_f32_32x32x16_bf16 v[50:65], v[126:129], v[138:141], v[50:65]
	s_waitcnt lgkmcnt(4)
	v_mfma_f32_32x32x16_bf16 v[18:33], v[126:129], v[142:145], v[18:33]
	v_mfma_f32_32x32x16_bf16 v[34:49], v[134:137], v[138:141], v[34:49]
	v_mfma_f32_32x32x16_bf16 v[2:17], v[134:137], v[142:145], v[2:17]
	ds_read_b128 v[126:129], v87
	ds_read_b128 v[134:137], v87 offset:4096
	ds_read_b128 v[138:141], v86 offset:32768
	ds_read_b128 v[142:145], v86 offset:36864
	s_waitcnt vmcnt(0)
	s_waitcnt lgkmcnt(0)
	s_barrier
	ds_read_b128 v[66:69], v91 offset:16384
	ds_read_b128 v[70:73], v91 offset:20480
	ds_read_b128 v[74:77], v92 offset:49152
	ds_read_b128 v[78:81], v92 offset:53248
	ds_read_b128 v[94:97], v93 offset:16384
	ds_read_b128 v[98:101], v93 offset:20480
	ds_read_b128 v[102:105], v90 offset:49152
	ds_read_b128 v[90:93], v90 offset:53248
	v_mfma_f32_32x32x16_bf16 v[50:65], v[110:113], v[118:121], v[50:65]
	v_mfma_f32_32x32x16_bf16 v[18:33], v[110:113], v[122:125], v[18:33]
	v_mfma_f32_32x32x16_bf16 v[34:49], v[114:117], v[118:121], v[34:49]
	v_mfma_f32_32x32x16_bf16 v[2:17], v[114:117], v[122:125], v[2:17]
	v_mfma_f32_32x32x16_bf16 v[50:65], v[126:129], v[138:141], v[50:65]
	v_mfma_f32_32x32x16_bf16 v[18:33], v[126:129], v[142:145], v[18:33]
	v_mfma_f32_32x32x16_bf16 v[34:49], v[134:137], v[138:141], v[34:49]
	v_mfma_f32_32x32x16_bf16 v[2:17], v[134:137], v[142:145], v[2:17]
	s_waitcnt lgkmcnt(5)
	v_mfma_f32_32x32x16_bf16 v[50:65], v[66:69], v[74:77], v[50:65]
	s_waitcnt lgkmcnt(4)
	v_mfma_f32_32x32x16_bf16 v[18:33], v[66:69], v[78:81], v[18:33]
	v_mfma_f32_32x32x16_bf16 v[34:49], v[70:73], v[74:77], v[34:49]
	v_mfma_f32_32x32x16_bf16 v[2:17], v[70:73], v[78:81], v[2:17]
	ds_read_b128 v[66:69], v89 offset:16384
	ds_read_b128 v[70:73], v89 offset:20480
	ds_read_b128 v[74:77], v88 offset:49152
	ds_read_b128 v[78:81], v88 offset:53248
	s_waitcnt lgkmcnt(5)
	v_mfma_f32_32x32x16_bf16 v[50:65], v[94:97], v[102:105], v[50:65]
	s_waitcnt lgkmcnt(4)
	v_mfma_f32_32x32x16_bf16 v[18:33], v[94:97], v[90:93], v[18:33]
	v_mfma_f32_32x32x16_bf16 v[34:49], v[98:101], v[102:105], v[34:49]
	v_mfma_f32_32x32x16_bf16 v[2:17], v[98:101], v[90:93], v[2:17]
	ds_read_b128 v[88:91], v87 offset:16384
	ds_read_b128 v[92:95], v87 offset:20480
	ds_read_b128 v[96:99], v86 offset:49152
	ds_read_b128 v[100:103], v86 offset:53248
	s_lshl_b32 s6, s34, 7
	v_lshl_add_u32 v0, v84, 6, s6
	s_min_i32 s7, s6, 0x4000
	v_lshl_or_b32 v0, v85, 2, v0
	s_movk_i32 s6, 0x4000
	s_waitcnt lgkmcnt(5)
	v_mfma_f32_32x32x16_bf16 v[50:65], v[66:69], v[74:77], v[50:65]
	v_cmp_gt_i32_e32 vcc, s6, v0
	v_readlane_b32 s36, v210, 2
	v_readlane_b32 s40, v210, 6
	s_ashr_i32 s7, s7, 12
	s_add_i32 s7, s7, s70
	s_mul_hi_i32 s8, s7, 0x6000
	s_mulk_i32 s7, 0x6000
	s_waitcnt lgkmcnt(4)
	v_mfma_f32_32x32x16_bf16 v[18:33], v[66:69], v[78:81], v[18:33]
	v_add_u32_e32 v66, 0xffffc000, v0
	v_ashrrev_i32_e32 v67, 31, v0
	v_cndmask_b32_e32 v66, v66, v0, vcc
	v_mov_b32_e32 v0, s95
	v_mov_b32_e32 v68, s89
	v_cndmask_b32_e32 v69, v0, v68, vcc
	v_mov_b32_e32 v0, s94
	v_mov_b32_e32 v68, s88
	v_mfma_f32_32x32x16_bf16 v[34:49], v[70:73], v[74:77], v[34:49]
	v_cndmask_b32_e32 v67, 0, v67, vcc
	v_cndmask_b32_e32 v68, v0, v68, vcc
	v_mov_b32_e32 v0, s40
	v_lshlrev_b64 v[66:67], 12, v[66:67]
	v_lshl_add_u64 v[134:135], v[68:69], 0, v[66:67]
	v_readlane_b32 s37, v210, 3
	v_readlane_b32 s41, v210, 7
	v_mfma_f32_32x32x16_bf16 v[2:17], v[70:73], v[78:81], v[2:17]
	v_mov_b32_e32 v70, s36
	v_cndmask_b32_e32 v0, v0, v70, vcc
	v_cndmask_b32_e64 v68, v68, v0, s[52:53]
	v_lshl_or_b32 v0, v83, 6, v82
	s_add_u32 s7, s90, s7
	v_mov_b32_e32 v70, s41
	v_mov_b32_e32 v71, s37
	v_subrev_u32_e32 v0, s5, v0
	s_addc_u32 s8, s91, s8
	v_cndmask_b32_e32 v70, v70, v71, vcc
	v_add_u32_e32 v168, s3, v0
	s_add_u32 s34, s7, 0x2000
	v_cndmask_b32_e64 v69, v69, v70, s[52:53]
	v_ashrrev_i32_e32 v169, 31, v168
	s_addc_u32 s35, s8, 0
	v_lshl_add_u64 v[66:67], v[68:69], 0, v[66:67]
	v_lshlrev_b64 v[136:137], 2, v[168:169]
	v_lshl_add_u64 v[68:69], s[34:35], 0, v[136:137]
	v_lshl_add_u64 v[66:67], v[66:67], 0, v[136:137]
	s_movk_i32 s8, 0x1000
	s_waitcnt lgkmcnt(0)
	s_barrier
	global_load_dword v0, v[68:69], off
	v_add_co_u32_e32 v68, vcc, s8, v66
	s_movk_i32 s6, 0x2000
	s_nop 0
	v_addc_co_u32_e32 v69, vcc, 0, v67, vcc
	global_load_dword v138, v[66:67], off
	v_add_co_u32_e32 v70, vcc, s6, v66
	v_readlane_b32 s38, v210, 4
	s_nop 0
	v_addc_co_u32_e32 v71, vcc, 0, v67, vcc
	global_load_dword v139, v[70:71], off offset:-4096
	global_load_dword v140, v[70:71], off
	s_movk_i32 s38, 0x3000
	v_add_co_u32_e32 v72, vcc, s38, v66
	s_mov_b32 s7, 0x8000
	s_nop 0
	v_addc_co_u32_e32 v73, vcc, 0, v67, vcc
	global_load_dword v141, v[72:73], off
	v_add_co_u32_e32 v74, vcc, s7, v66
	s_mov_b32 s36, 0x9000
	s_nop 0
	v_addc_co_u32_e32 v75, vcc, 0, v67, vcc
	v_add_co_u32_e32 v76, vcc, s36, v66
	s_mov_b32 s37, 0xa000
	s_nop 0
	v_addc_co_u32_e32 v77, vcc, 0, v67, vcc
	v_add_co_u32_e32 v78, vcc, s37, v66
	s_mov_b32 s5, 0xb000
	s_nop 0
	v_addc_co_u32_e32 v79, vcc, 0, v67, vcc
	global_load_dword v142, v[76:77], off offset:-4096
	global_load_dword v143, v[76:77], off
	v_add_co_u32_e32 v80, vcc, s5, v66
	v_readlane_b32 s39, v210, 5
	s_nop 0
	v_addc_co_u32_e32 v81, vcc, 0, v67, vcc
	v_add_co_u32_e32 v82, vcc, s10, v66
	s_mov_b32 s39, 0x11000
	s_nop 0
	v_addc_co_u32_e32 v83, vcc, 0, v67, vcc
	global_load_dword v144, v[80:81], off offset:-4096
	global_load_dword v145, v[80:81], off
	v_add_co_u32_e32 v84, vcc, s39, v66
	v_mfma_f32_32x32x16_bf16 v[50:65], v[88:91], v[96:99], v[50:65]
	s_nop 0
	v_addc_co_u32_e32 v85, vcc, 0, v67, vcc
	v_add_co_u32_e32 v86, vcc, s62, v66
	global_load_dword v146, v[84:85], off offset:-4096
	global_load_dword v147, v[84:85], off
	v_addc_co_u32_e32 v87, vcc, 0, v67, vcc
	v_mfma_f32_32x32x16_bf16 v[18:33], v[88:91], v[100:103], v[18:33]
	v_add_co_u32_e32 v88, vcc, s57, v66
	v_lshl_add_u64 v[134:135], v[134:135], 0, v[136:137]
	s_nop 0
	v_addc_co_u32_e32 v89, vcc, 0, v67, vcc
	v_add_co_u32_e32 v90, vcc, s54, v66
	v_mfma_f32_32x32x16_bf16 v[34:49], v[92:95], v[96:99], v[34:49]
	s_nop 0
	v_addc_co_u32_e32 v91, vcc, 0, v67, vcc
	global_load_dword v148, v[88:89], off offset:-4096
	global_load_dword v149, v[88:89], off
	s_add_i32 s4, s4, s66
	s_add_i32 s3, s3, s2
	s_cmp_lt_i32 s4, s59
	v_readlane_b32 s42, v210, 8
	v_mfma_f32_32x32x16_bf16 v[2:17], v[92:95], v[100:103], v[2:17]
	v_add_co_u32_e32 v92, vcc, s55, v66
	v_readlane_b32 s43, v210, 9
	s_nop 0
	v_addc_co_u32_e32 v93, vcc, 0, v67, vcc
	v_add_co_u32_e32 v94, vcc, s72, v66
	global_load_dword v150, v[92:93], off offset:-4096
	global_load_dword v151, v[92:93], off
	v_addc_co_u32_e32 v95, vcc, 0, v67, vcc
	v_add_co_u32_e32 v96, vcc, s73, v66
	s_waitcnt vmcnt(13)
	v_fmac_f32_e32 v138, v50, v0
	v_addc_co_u32_e32 v97, vcc, 0, v67, vcc
	v_add_co_u32_e32 v98, vcc, s63, v66
	global_load_dword v152, v[96:97], off offset:-4096
	global_load_dword v153, v[96:97], off
	v_addc_co_u32_e32 v99, vcc, 0, v67, vcc
	v_add_co_u32_e32 v100, vcc, s74, v66
	s_waitcnt vmcnt(14)
	v_fmac_f32_e32 v139, v51, v0
	v_addc_co_u32_e32 v101, vcc, 0, v67, vcc
	v_add_co_u32_e32 v102, vcc, s75, v66
	global_load_dword v154, v[100:101], off offset:-4096
	global_load_dword v155, v[100:101], off
	v_addc_co_u32_e32 v103, vcc, 0, v67, vcc
	v_add_co_u32_e32 v104, vcc, s76, v66
	s_waitcnt vmcnt(15)
	v_fmac_f32_e32 v140, v52, v0
	v_addc_co_u32_e32 v105, vcc, 0, v67, vcc
	v_add_co_u32_e32 v106, vcc, s77, v66
	global_load_dword v156, v[104:105], off offset:-4096
	global_load_dword v157, v[104:105], off
	v_addc_co_u32_e32 v107, vcc, 0, v67, vcc
	v_add_co_u32_e32 v108, vcc, s78, v66
	s_waitcnt vmcnt(16)
	v_fmac_f32_e32 v141, v53, v0
	v_addc_co_u32_e32 v109, vcc, 0, v67, vcc
	v_add_co_u32_e32 v110, vcc, s79, v66
	global_load_dword v158, v[108:109], off offset:-4096
	global_load_dword v159, v[108:109], off
	v_addc_co_u32_e32 v111, vcc, 0, v67, vcc
	v_add_co_u32_e32 v112, vcc, s58, v66
	s_waitcnt vmcnt(17)
	v_fmac_f32_e32 v142, v54, v0
	v_addc_co_u32_e32 v113, vcc, 0, v67, vcc
	v_add_co_u32_e32 v114, vcc, s61, v66
	global_load_dword v160, v[112:113], off offset:-4096
	global_load_dword v161, v[112:113], off
	v_addc_co_u32_e32 v115, vcc, 0, v67, vcc
	v_add_co_u32_e32 v116, vcc, s56, v66
	s_waitcnt vmcnt(18)
	v_fmac_f32_e32 v143, v55, v0
	v_addc_co_u32_e32 v117, vcc, 0, v67, vcc
	v_add_co_u32_e32 v118, vcc, s97, v66
	global_load_dword v162, v[116:117], off offset:-4096
	global_load_dword v163, v[116:117], off
	v_addc_co_u32_e32 v119, vcc, 0, v67, vcc
	v_add_co_u32_e32 v120, vcc, s9, v66
	s_waitcnt vmcnt(19)
	v_fmac_f32_e32 v144, v56, v0
	v_addc_co_u32_e32 v121, vcc, 0, v67, vcc
	v_add_co_u32_e32 v122, vcc, s69, v66
	global_load_dword v164, v[120:121], off offset:-4096
	global_load_dword v165, v[120:121], off
	v_addc_co_u32_e32 v123, vcc, 0, v67, vcc
	v_add_co_u32_e32 v124, vcc, s67, v66
	s_waitcnt vmcnt(20)
	v_fmac_f32_e32 v145, v57, v0
	v_addc_co_u32_e32 v125, vcc, 0, v67, vcc
	v_add_co_u32_e32 v126, vcc, s60, v66
	global_load_dword v166, v[124:125], off offset:-4096
	global_load_dword v167, v[124:125], off
	v_addc_co_u32_e32 v127, vcc, 0, v67, vcc
	v_add_co_u32_e32 v128, vcc, s33, v66
	s_waitcnt vmcnt(21)
	v_fmac_f32_e32 v146, v58, v0
	v_addc_co_u32_e32 v129, vcc, 0, v67, vcc
	global_load_dword v169, v[128:129], off offset:-4096
	global_load_dword v181, v[128:129], off
	v_add_co_u32_e32 v50, vcc, s8, v134
	global_store_dword v[134:135], v138, off
	s_nop 0
	v_addc_co_u32_e32 v51, vcc, 0, v135, vcc
	v_add_co_u32_e32 v136, vcc, s6, v134
	s_waitcnt vmcnt(23)
	v_fmac_f32_e32 v147, v59, v0
	v_addc_co_u32_e32 v137, vcc, 0, v135, vcc
	v_add_co_u32_e32 v52, vcc, s38, v134
	global_store_dword v[136:137], v139, off offset:-4096
	s_nop 0
	v_addc_co_u32_e32 v53, vcc, 0, v135, vcc
	v_add_co_u32_e32 v138, vcc, s7, v134
	global_store_dword v[136:137], v140, off
	s_nop 0
	v_addc_co_u32_e32 v139, vcc, 0, v135, vcc
	v_add_co_u32_e32 v140, vcc, s36, v134
	global_store_dword v[52:53], v141, off
	s_nop 0
	v_addc_co_u32_e32 v141, vcc, 0, v135, vcc
	v_add_co_u32_e32 v54, vcc, s37, v134
	global_store_dword v[140:141], v142, off offset:-4096
	s_nop 0
	v_addc_co_u32_e32 v55, vcc, 0, v135, vcc
	v_add_co_u32_e32 v142, vcc, s5, v134
	global_store_dword v[140:141], v143, off
	s_nop 0
	v_addc_co_u32_e32 v143, vcc, 0, v135, vcc
	v_add_co_u32_e32 v56, vcc, s10, v134
	global_store_dword v[142:143], v144, off offset:-4096
	s_nop 0
	v_addc_co_u32_e32 v57, vcc, 0, v135, vcc
	v_add_co_u32_e32 v144, vcc, s39, v134
	global_store_dword v[142:143], v145, off
	s_nop 0
	v_addc_co_u32_e32 v145, vcc, 0, v135, vcc
	v_add_co_u32_e32 v58, vcc, s62, v134
	global_store_dword v[144:145], v146, off offset:-4096
	s_nop 0
	v_addc_co_u32_e32 v59, vcc, 0, v135, vcc
	v_add_co_u32_e32 v146, vcc, s57, v134
	global_store_dword v[144:145], v147, off
	s_nop 0
	v_addc_co_u32_e32 v147, vcc, 0, v135, vcc
	s_waitcnt vmcnt(31)
	v_fmac_f32_e32 v148, v60, v0
	v_add_co_u32_e32 v60, vcc, s54, v134
	s_waitcnt vmcnt(30)
	v_fmac_f32_e32 v149, v61, v0
	v_addc_co_u32_e32 v61, vcc, 0, v135, vcc
	global_store_dword v[146:147], v148, off offset:-4096
	v_add_co_u32_e32 v148, vcc, s55, v134
	global_store_dword v[146:147], v149, off
	s_nop 0
	v_addc_co_u32_e32 v149, vcc, 0, v135, vcc
	s_waitcnt vmcnt(31)
	v_fmac_f32_e32 v150, v62, v0
	v_add_co_u32_e32 v62, vcc, s72, v134
	s_waitcnt vmcnt(30)
	v_fmac_f32_e32 v151, v63, v0
	v_addc_co_u32_e32 v63, vcc, 0, v135, vcc
	global_store_dword v[148:149], v150, off offset:-4096
	v_add_co_u32_e32 v150, vcc, s73, v134
	global_store_dword v[148:149], v151, off
	s_nop 0
	v_addc_co_u32_e32 v151, vcc, 0, v135, vcc
	s_waitcnt vmcnt(31)
	v_fmac_f32_e32 v152, v64, v0
	v_add_co_u32_e32 v64, vcc, s63, v134
	s_waitcnt vmcnt(30)
	v_fmac_f32_e32 v153, v65, v0
	v_addc_co_u32_e32 v65, vcc, 0, v135, vcc
	global_store_dword v[150:151], v152, off offset:-4096
	v_add_co_u32_e32 v152, vcc, s74, v134
	global_store_dword v[150:151], v153, off
	s_nop 0
	v_addc_co_u32_e32 v153, vcc, 0, v135, vcc
	s_waitcnt vmcnt(31)
	v_fmac_f32_e32 v154, v34, v0
	v_add_co_u32_e32 v34, vcc, s75, v134
	s_waitcnt vmcnt(30)
	v_fmac_f32_e32 v155, v35, v0
	v_addc_co_u32_e32 v35, vcc, 0, v135, vcc
	global_store_dword v[152:153], v154, off offset:-4096
	v_add_co_u32_e32 v154, vcc, s76, v134
	global_store_dword v[152:153], v155, off
	s_nop 0
	v_addc_co_u32_e32 v155, vcc, 0, v135, vcc
	s_waitcnt vmcnt(31)
	v_fmac_f32_e32 v156, v36, v0
	v_add_co_u32_e32 v36, vcc, s77, v134
	s_waitcnt vmcnt(30)
	v_fmac_f32_e32 v157, v37, v0
	v_addc_co_u32_e32 v37, vcc, 0, v135, vcc
	global_store_dword v[154:155], v156, off offset:-4096
	v_add_co_u32_e32 v156, vcc, s78, v134
	global_store_dword v[154:155], v157, off
	s_nop 0
	v_addc_co_u32_e32 v157, vcc, 0, v135, vcc
	s_waitcnt vmcnt(31)
	v_fmac_f32_e32 v158, v38, v0
	v_add_co_u32_e32 v38, vcc, s79, v134
	s_waitcnt vmcnt(30)
	v_fmac_f32_e32 v159, v39, v0
	v_addc_co_u32_e32 v39, vcc, 0, v135, vcc
	global_store_dword v[156:157], v158, off offset:-4096
	v_add_co_u32_e32 v158, vcc, s58, v134
	global_store_dword v[156:157], v159, off
	s_nop 0
	v_addc_co_u32_e32 v159, vcc, 0, v135, vcc
	s_waitcnt vmcnt(31)
	v_fmac_f32_e32 v160, v40, v0
	v_add_co_u32_e32 v40, vcc, s61, v134
	s_waitcnt vmcnt(30)
	v_fmac_f32_e32 v161, v41, v0
	v_addc_co_u32_e32 v41, vcc, 0, v135, vcc
	global_store_dword v[158:159], v160, off offset:-4096
	v_add_co_u32_e32 v160, vcc, s56, v134
	global_store_dword v[158:159], v161, off
	s_nop 0
	v_addc_co_u32_e32 v161, vcc, 0, v135, vcc
	s_waitcnt vmcnt(31)
	v_fmac_f32_e32 v162, v42, v0
	v_add_co_u32_e32 v42, vcc, s97, v134
	s_waitcnt vmcnt(30)
	v_fmac_f32_e32 v163, v43, v0
	v_addc_co_u32_e32 v43, vcc, 0, v135, vcc
	global_store_dword v[160:161], v162, off offset:-4096
	v_add_co_u32_e32 v162, vcc, s9, v134
	global_store_dword v[160:161], v163, off
	s_nop 0
	v_addc_co_u32_e32 v163, vcc, 0, v135, vcc
	s_waitcnt vmcnt(31)
	v_fmac_f32_e32 v164, v44, v0
	v_add_co_u32_e32 v44, vcc, s69, v134
	s_waitcnt vmcnt(30)
	v_fmac_f32_e32 v165, v45, v0
	v_addc_co_u32_e32 v45, vcc, 0, v135, vcc
	global_store_dword v[162:163], v164, off offset:-4096
	v_add_co_u32_e32 v164, vcc, s67, v134
	global_store_dword v[162:163], v165, off
	s_nop 0
	v_addc_co_u32_e32 v165, vcc, 0, v135, vcc
	s_waitcnt vmcnt(31)
	v_fmac_f32_e32 v166, v46, v0
	v_add_co_u32_e32 v46, vcc, s60, v134
	s_waitcnt vmcnt(30)
	v_fmac_f32_e32 v167, v47, v0
	v_addc_co_u32_e32 v47, vcc, 0, v135, vcc
	global_store_dword v[164:165], v166, off offset:-4096
	s_waitcnt vmcnt(30)
	v_fmac_f32_e32 v169, v48, v0
	v_add_co_u32_e32 v166, vcc, s33, v134
	v_add_u32_e32 v48, 32, v168
	global_store_dword v[164:165], v167, off
	v_addc_co_u32_e32 v167, vcc, 0, v135, vcc
	s_waitcnt vmcnt(30)
	v_fmac_f32_e32 v181, v49, v0
	v_ashrrev_i32_e32 v49, 31, v48
	global_store_dword v[166:167], v169, off offset:-4096
	global_store_dword v[166:167], v181, off
	v_lshl_add_u64 v[48:49], v[48:49], 2, s[34:35]
	global_load_dword v0, v[48:49], off
	s_nop 0
	global_load_dword v48, v[66:67], off offset:128
	global_load_dword v49, v[68:69], off offset:128
	s_nop 0
	global_load_dword v66, v[70:71], off offset:128
	global_load_dword v67, v[72:73], off offset:128
	global_load_dword v68, v[74:75], off offset:128
	global_load_dword v69, v[76:77], off offset:128
	s_nop 0
	global_load_dword v70, v[78:79], off offset:128
	global_load_dword v71, v[80:81], off offset:128
	global_load_dword v72, v[82:83], off offset:128
	global_load_dword v73, v[84:85], off offset:128
	global_load_dword v74, v[86:87], off offset:128
	global_load_dword v75, v[88:89], off offset:128
	global_load_dword v76, v[90:91], off offset:128
	global_load_dword v77, v[92:93], off offset:128
	global_load_dword v78, v[94:95], off offset:128
	global_load_dword v79, v[96:97], off offset:128
	global_load_dword v80, v[98:99], off offset:128
	global_load_dword v81, v[100:101], off offset:128
	global_load_dword v82, v[102:103], off offset:128
	global_load_dword v83, v[104:105], off offset:128
	global_load_dword v84, v[106:107], off offset:128
	global_load_dword v85, v[108:109], off offset:128
	global_load_dword v86, v[110:111], off offset:128
	global_load_dword v87, v[112:113], off offset:128
	global_load_dword v88, v[114:115], off offset:128
	global_load_dword v89, v[116:117], off offset:128
	global_load_dword v90, v[118:119], off offset:128
	global_load_dword v91, v[120:121], off offset:128
	global_load_dword v92, v[122:123], off offset:128
	global_load_dword v93, v[124:125], off offset:128
	global_load_dword v94, v[126:127], off offset:128
	global_load_dword v95, v[128:129], off offset:128
	v_readlane_b32 s44, v210, 10
	v_readlane_b32 s45, v210, 11
	v_readlane_b32 s46, v210, 12
	v_readlane_b32 s47, v210, 13
	v_readlane_b32 s48, v210, 14
	v_readlane_b32 s49, v210, 15
	v_readlane_b32 s50, v210, 16
	v_readlane_b32 s51, v210, 17
	s_waitcnt vmcnt(31)
	v_fmac_f32_e32 v48, v18, v0
	s_waitcnt vmcnt(30)
	v_fmac_f32_e32 v49, v19, v0
	s_waitcnt vmcnt(29)
	v_fmac_f32_e32 v66, v20, v0
	s_waitcnt vmcnt(28)
	v_fmac_f32_e32 v67, v21, v0
	s_waitcnt vmcnt(27)
	v_fmac_f32_e32 v68, v22, v0
	s_waitcnt vmcnt(26)
	v_fmac_f32_e32 v69, v23, v0
	s_waitcnt vmcnt(25)
	v_fmac_f32_e32 v70, v24, v0
	s_waitcnt vmcnt(24)
	v_fmac_f32_e32 v71, v25, v0
	s_waitcnt vmcnt(23)
	v_fmac_f32_e32 v72, v26, v0
	s_waitcnt vmcnt(22)
	v_fmac_f32_e32 v73, v27, v0
	s_waitcnt vmcnt(21)
	v_fmac_f32_e32 v74, v28, v0
	s_waitcnt vmcnt(20)
	v_fmac_f32_e32 v75, v29, v0
	s_waitcnt vmcnt(19)
	v_fmac_f32_e32 v76, v30, v0
	s_waitcnt vmcnt(18)
	v_fmac_f32_e32 v77, v31, v0
	s_waitcnt vmcnt(17)
	v_fmac_f32_e32 v78, v32, v0
	s_waitcnt vmcnt(16)
	v_fmac_f32_e32 v79, v33, v0
	s_waitcnt vmcnt(15)
	v_fmac_f32_e32 v80, v2, v0
	s_waitcnt vmcnt(14)
	v_fmac_f32_e32 v81, v3, v0
	s_waitcnt vmcnt(13)
	v_fmac_f32_e32 v82, v4, v0
	s_waitcnt vmcnt(12)
	v_fmac_f32_e32 v83, v5, v0
	s_waitcnt vmcnt(11)
	v_fmac_f32_e32 v84, v6, v0
	s_waitcnt vmcnt(10)
	v_fmac_f32_e32 v85, v7, v0
	s_waitcnt vmcnt(9)
	v_fmac_f32_e32 v86, v8, v0
	s_waitcnt vmcnt(8)
	v_fmac_f32_e32 v87, v9, v0
	s_waitcnt vmcnt(7)
	v_fmac_f32_e32 v88, v10, v0
	s_waitcnt vmcnt(6)
	v_fmac_f32_e32 v89, v11, v0
	s_waitcnt vmcnt(5)
	v_fmac_f32_e32 v90, v12, v0
	s_waitcnt vmcnt(4)
	v_fmac_f32_e32 v91, v13, v0
	s_waitcnt vmcnt(3)
	v_fmac_f32_e32 v92, v14, v0
	s_waitcnt vmcnt(2)
	v_fmac_f32_e32 v93, v15, v0
	s_waitcnt vmcnt(1)
	v_fmac_f32_e32 v94, v16, v0
	s_waitcnt vmcnt(0)
	v_fmac_f32_e32 v95, v17, v0
	global_store_dword v[134:135], v48, off offset:128
	global_store_dword v[50:51], v49, off offset:128
	global_store_dword v[136:137], v66, off offset:128
	global_store_dword v[52:53], v67, off offset:128
	global_store_dword v[138:139], v68, off offset:128
	global_store_dword v[140:141], v69, off offset:128
	global_store_dword v[54:55], v70, off offset:128
	global_store_dword v[142:143], v71, off offset:128
	global_store_dword v[56:57], v72, off offset:128
	global_store_dword v[144:145], v73, off offset:128
	global_store_dword v[58:59], v74, off offset:128
	global_store_dword v[146:147], v75, off offset:128
	global_store_dword v[60:61], v76, off offset:128
	global_store_dword v[148:149], v77, off offset:128
	global_store_dword v[62:63], v78, off offset:128
	global_store_dword v[150:151], v79, off offset:128
	global_store_dword v[64:65], v80, off offset:128
	global_store_dword v[152:153], v81, off offset:128
	global_store_dword v[34:35], v82, off offset:128
	global_store_dword v[154:155], v83, off offset:128
	global_store_dword v[36:37], v84, off offset:128
	global_store_dword v[156:157], v85, off offset:128
	global_store_dword v[38:39], v86, off offset:128
	global_store_dword v[158:159], v87, off offset:128
	global_store_dword v[40:41], v88, off offset:128
	global_store_dword v[160:161], v89, off offset:128
	global_store_dword v[42:43], v90, off offset:128
	global_store_dword v[162:163], v91, off offset:128
	global_store_dword v[44:45], v92, off offset:128
	global_store_dword v[164:165], v93, off offset:128
	global_store_dword v[46:47], v94, off offset:128
	global_store_dword v[166:167], v95, off offset:128
	s_cmpk_lt_i32 s4, 0x400
	s_cbranch_scc1 .LBB0_1186
	s_cmpk_ge_i32 s4, 0x600
	s_cbranch_scc1 .Lph6_done
	s_cmpk_le_i32 s59, 0x400
	s_cbranch_scc1 .Lph6_done
	v_readlane_b32 s5, v209, 2
	s_cmpk_ge_u32 s5, 0x40
	s_cbranch_scc1 .Lph6_done
	s_add_i32 s4, s5, 0x400
	s_lshl_b32 s3, s4, 7
	s_branch .LBB0_1186
.Lph6_done:
	v_readlane_b32 s72, v208, 43
	v_readlane_b32 s42, v208, 51
	v_readlane_b32 s54, v209, 14
	s_mov_b32 s62, 0x3b000
	v_readlane_b32 s73, v208, 44
	v_readlane_b32 s74, v208, 45
	v_readlane_b32 s75, v208, 46
	v_readlane_b32 s76, v208, 47
	v_readlane_b32 s77, v208, 48
	v_readlane_b32 s78, v208, 49
	v_readlane_b32 s79, v208, 50
	v_readlane_b32 s43, v208, 52
	v_readlane_b32 s55, v209, 15
	s_mov_b32 s67, 0x3a000
	v_readlane_b32 s97, v209, 2
	v_readlane_b32 s60, v208, 63
	s_mov_b32 s56, 0x10000
	s_mov_b32 s57, 0x20000
	s_mov_b32 s58, 0x30000
	s_movk_i32 s59, 0x70
	s_movk_i32 s53, 0x2000
	s_mov_b32 s52, 0xb000

.LBB0_1298:
	s_ashr_i32 s6, s5, 31
	s_lshr_b32 s6, s6, 27
	s_add_i32 s6, s5, s6
	s_ashr_i32 s34, s6, 5
	s_ashr_i32 s35, s34, 31
	v_mov_b32_e32 v36, v133
	s_lshl_b64 s[6:7], s[34:35], 18
	s_add_u32 s6, s38, s6
	v_ashrrev_i32_e32 v34, 3, v36
	v_ashrrev_i32_e32 v35, 31, v34
	s_addc_u32 s7, s39, s7
	v_lshlrev_b64 v[2:3], 11, v[34:35]
	v_lshlrev_b32_e32 v0, 4, v36
	v_lshl_add_u64 v[2:3], s[6:7], 0, v[2:3]
	v_and_b32_e32 v0, 0x70, v0
	s_lshl_b32 s6, s34, 12
	v_lshl_add_u64 v[66:67], v[2:3], 0, v[0:1]
	v_subrev_u32_e32 v2, s6, v34
	v_add_u32_e32 v2, s4, v2
	v_ashrrev_i32_e32 v3, 31, v2
	v_lshlrev_b64 v[2:3], 11, v[2:3]
	v_lshl_add_u64 v[2:3], s[0:1], 0, v[2:3]
	v_add_co_u32_e32 v70, vcc, s56, v66
	v_lshl_add_u64 v[68:69], v[2:3], 0, v[0:1]
	s_nop 0
	v_addc_co_u32_e32 v71, vcc, 0, v67, vcc
	v_add_co_u32_e32 v72, vcc, s56, v68
	v_addc_co_u32_e32 v73, vcc, 0, v69, vcc
	v_add_co_u32_e32 v74, vcc, s57, v66
	s_nop 0
	v_addc_co_u32_e32 v75, vcc, 0, v67, vcc
	v_add_co_u32_e32 v76, vcc, s57, v68
	s_nop 0
	v_addc_co_u32_e32 v77, vcc, 0, v69, vcc
	v_add_co_u32_e32 v78, vcc, s58, v66
	s_nop 0
	v_addc_co_u32_e32 v79, vcc, 0, v67, vcc
	v_add_co_u32_e32 v80, vcc, s58, v68
	v_lshlrev_b32_e32 v0, 7, v34
	s_nop 0
	v_addc_co_u32_e32 v81, vcc, 0, v69, vcc
	v_lshrrev_b32_e32 v216, 4, v133
	v_xor_b32_e32 v216, v216, v133
	v_and_b32_e32 v216, 7, v216
	v_lshlrev_b32_e32 v216, 4, v216
	v_mov_b32_e32 v217, 0x70
	v_lshrrev_b32_e32 v218, 6, v133
	v_lshlrev_b32_e32 v218, 10, v218
	s_nop 0
	v_readfirstlane_b32 s32, v218
	v_bfi_b32 v66, v217, v216, v66
	v_bfi_b32 v70, v217, v216, v70
	v_bfi_b32 v74, v217, v216, v74
	v_bfi_b32 v78, v217, v216, v78
	v_bfi_b32 v68, v217, v216, v68
	v_bfi_b32 v72, v217, v216, v72
	v_bfi_b32 v76, v217, v216, v76
	v_bfi_b32 v80, v217, v216, v80
	s_mov_b64 s[98:99], 0x80
	s_add_u32 m0, s32, 0x0
	s_nop 0
	global_load_lds_dwordx4 v[66:67], off
	s_add_u32 m0, s32, 0x1000
	s_nop 0
	global_load_lds_dwordx4 v[70:71], off
	s_add_u32 m0, s32, 0x2000
	s_nop 0
	global_load_lds_dwordx4 v[74:75], off
	s_add_u32 m0, s32, 0x3000
	s_nop 0
	global_load_lds_dwordx4 v[78:79], off
	s_add_u32 m0, s32, 0x8000
	s_nop 0
	global_load_lds_dwordx4 v[68:69], off
	s_add_u32 m0, s32, 0x9000
	s_nop 0
	global_load_lds_dwordx4 v[72:73], off
	s_add_u32 m0, s32, 0xa000
	s_nop 0
	global_load_lds_dwordx4 v[76:77], off
	s_add_u32 m0, s32, 0xb000
	s_nop 0
	global_load_lds_dwordx4 v[80:81], off
	v_lshl_add_u64 v[66:67], v[66:67], 0, s[98:99]
	v_lshl_add_u64 v[70:71], v[70:71], 0, s[98:99]
	v_lshl_add_u64 v[74:75], v[74:75], 0, s[98:99]
	v_lshl_add_u64 v[78:79], v[78:79], 0, s[98:99]
	v_lshl_add_u64 v[68:69], v[68:69], 0, s[98:99]
	v_lshl_add_u64 v[72:73], v[72:73], 0, s[98:99]
	v_lshl_add_u64 v[76:77], v[76:77], 0, s[98:99]
	v_lshl_add_u64 v[80:81], v[80:81], 0, s[98:99]
	v_lshrrev_b32_e32 v34, 1, v34
	v_xor_b32_e32 v34, v34, v36
	v_lshlrev_b32_e32 v34, 4, v34
	v_and_or_b32 v0, v34, s59, v0
	s_waitcnt vmcnt(26)
	v_and_b32_e32 v82, 31, v36
	v_bfe_u32 v83, v36, 5, 1
	v_ashrrev_i32_e32 v84, 7, v36
	v_bfe_u32 v85, v36, 6, 1
	s_waitcnt lgkmcnt(0)
	s_barrier
	s_add_u32 m0, s32, 0x4000
	s_nop 0
	global_load_lds_dwordx4 v[66:67], off
	s_add_u32 m0, s32, 0x5000
	s_nop 0
	global_load_lds_dwordx4 v[70:71], off
	s_add_u32 m0, s32, 0x6000
	s_nop 0
	global_load_lds_dwordx4 v[74:75], off
	s_add_u32 m0, s32, 0x7000
	s_nop 0
	global_load_lds_dwordx4 v[78:79], off
	s_add_u32 m0, s32, 0xc000
	s_nop 0
	global_load_lds_dwordx4 v[68:69], off
	s_add_u32 m0, s32, 0xd000
	s_nop 0
	global_load_lds_dwordx4 v[72:73], off
	s_add_u32 m0, s32, 0xe000
	s_nop 0
	global_load_lds_dwordx4 v[76:77], off
	s_add_u32 m0, s32, 0xf000
	s_nop 0
	global_load_lds_dwordx4 v[80:81], off
	s_waitcnt vmcnt(8)
	s_barrier
	v_lshrrev_b32_e32 v4, 1, v36
	v_lshlrev_b32_e32 v2, 7, v82
	v_bitop3_b32 v4, v4, v83, 7 bitop3:0x6c
	v_lshl_or_b32 v3, v84, 13, v2
	v_bfe_u32 v5, v36, 1, 3
	v_lshlrev_b32_e32 v4, 4, v4
	v_lshl_or_b32 v2, v85, 13, v2
	v_or_b32_e32 v91, v3, v4
	v_or_b32_e32 v92, v2, v4
	v_bitop3_b32 v4, v83, v5, 2 bitop3:0x36
	v_lshlrev_b32_e32 v4, 4, v4
	v_or_b32_e32 v93, v3, v4
	v_or_b32_e32 v90, v2, v4
	v_bitop3_b32 v4, v83, v5, 4 bitop3:0x36
	v_lshlrev_b32_e32 v4, 4, v4
	v_or_b32_e32 v89, v3, v4
	v_or_b32_e32 v88, v2, v4
	v_bitop3_b32 v4, v83, v5, 6 bitop3:0x36
	v_lshlrev_b32_e32 v4, 4, v4
	v_or_b32_e32 v87, v3, v4
	v_or_b32_e32 v86, v2, v4
	ds_read_b128 v[2:5], v91
	ds_read_b128 v[6:9], v92 offset:32768
	ds_read_b128 v[10:13], v91 offset:4096
	ds_read_b128 v[14:17], v92 offset:36864
	ds_read_b128 v[162:165], v93
	ds_read_b128 v[166:169], v90 offset:32768
	ds_read_b128 v[182:185], v93 offset:4096
	ds_read_b128 v[186:189], v90 offset:36864
	s_waitcnt lgkmcnt(6)
	v_mfma_f32_32x32x16_bf16 v[50:65], v[2:5], v[6:9], 0
	s_waitcnt lgkmcnt(4)
	v_mfma_f32_32x32x16_bf16 v[34:49], v[2:5], v[14:17], 0
	v_mfma_f32_32x32x16_bf16 v[18:33], v[10:13], v[6:9], 0
	v_mfma_f32_32x32x16_bf16 v[2:17], v[10:13], v[14:17], 0
	ds_read_b128 v[190:193], v89
	ds_read_b128 v[194:197], v89 offset:4096
	ds_read_b128 v[198:201], v88 offset:32768
	ds_read_b128 v[202:205], v88 offset:36864
	s_waitcnt lgkmcnt(6)
	v_mfma_f32_32x32x16_bf16 v[50:65], v[162:165], v[166:169], v[50:65]
	s_waitcnt lgkmcnt(4)
	v_mfma_f32_32x32x16_bf16 v[34:49], v[162:165], v[186:189], v[34:49]
	v_mfma_f32_32x32x16_bf16 v[18:33], v[182:185], v[166:169], v[18:33]
	v_mfma_f32_32x32x16_bf16 v[2:17], v[182:185], v[186:189], v[2:17]
	ds_read_b128 v[162:165], v87
	ds_read_b128 v[166:169], v87 offset:4096
	ds_read_b128 v[182:185], v86 offset:32768
	ds_read_b128 v[186:189], v86 offset:36864
	v_lshl_add_u64 v[66:67], v[66:67], 0, s[98:99]
	v_lshl_add_u64 v[70:71], v[70:71], 0, s[98:99]
	v_lshl_add_u64 v[74:75], v[74:75], 0, s[98:99]
	v_lshl_add_u64 v[78:79], v[78:79], 0, s[98:99]
	v_lshl_add_u64 v[68:69], v[68:69], 0, s[98:99]
	v_lshl_add_u64 v[72:73], v[72:73], 0, s[98:99]
	v_lshl_add_u64 v[76:77], v[76:77], 0, s[98:99]
	v_lshl_add_u64 v[80:81], v[80:81], 0, s[98:99]
	s_waitcnt lgkmcnt(0)
	s_barrier
	s_add_u32 m0, s32, 0x0
	v_mfma_f32_32x32x16_bf16 v[50:65], v[190:193], v[198:201], v[50:65]
	global_load_lds_dwordx4 v[66:67], off
	s_add_u32 m0, s32, 0x1000
	v_mfma_f32_32x32x16_bf16 v[34:49], v[190:193], v[202:205], v[34:49]
	global_load_lds_dwordx4 v[70:71], off
	s_add_u32 m0, s32, 0x2000
	v_mfma_f32_32x32x16_bf16 v[18:33], v[194:197], v[198:201], v[18:33]
	global_load_lds_dwordx4 v[74:75], off
	s_add_u32 m0, s32, 0x3000
	v_mfma_f32_32x32x16_bf16 v[2:17], v[194:197], v[202:205], v[2:17]
	global_load_lds_dwordx4 v[78:79], off
	s_add_u32 m0, s32, 0x8000
	v_mfma_f32_32x32x16_bf16 v[50:65], v[162:165], v[182:185], v[50:65]
	global_load_lds_dwordx4 v[68:69], off
	s_add_u32 m0, s32, 0x9000
	v_mfma_f32_32x32x16_bf16 v[34:49], v[162:165], v[186:189], v[34:49]
	global_load_lds_dwordx4 v[72:73], off
	s_add_u32 m0, s32, 0xa000
	v_mfma_f32_32x32x16_bf16 v[18:33], v[166:169], v[182:185], v[18:33]
	global_load_lds_dwordx4 v[76:77], off
	s_add_u32 m0, s32, 0xb000
	v_mfma_f32_32x32x16_bf16 v[2:17], v[166:169], v[186:189], v[2:17]
	global_load_lds_dwordx4 v[80:81], off
	s_waitcnt vmcnt(8)
	s_barrier
	ds_read_b128 v[162:165], v91 offset:16384
	ds_read_b128 v[166:169], v92 offset:49152
	ds_read_b128 v[182:185], v91 offset:20480
	ds_read_b128 v[186:189], v92 offset:53248
	ds_read_b128 v[190:193], v93 offset:16384
	ds_read_b128 v[194:197], v90 offset:49152
	ds_read_b128 v[198:201], v93 offset:20480
	ds_read_b128 v[202:205], v90 offset:53248
	s_waitcnt lgkmcnt(6)
	v_mfma_f32_32x32x16_bf16 v[50:65], v[162:165], v[166:169], v[50:65]
	s_waitcnt lgkmcnt(4)
	v_mfma_f32_32x32x16_bf16 v[34:49], v[162:165], v[186:189], v[34:49]
	v_mfma_f32_32x32x16_bf16 v[18:33], v[182:185], v[166:169], v[18:33]
	v_mfma_f32_32x32x16_bf16 v[2:17], v[182:185], v[186:189], v[2:17]
	ds_read_b128 v[162:165], v89 offset:16384
	ds_read_b128 v[166:169], v89 offset:20480
	ds_read_b128 v[182:185], v88 offset:49152
	ds_read_b128 v[186:189], v88 offset:53248
	s_waitcnt lgkmcnt(6)
	v_mfma_f32_32x32x16_bf16 v[50:65], v[190:193], v[194:197], v[50:65]
	s_waitcnt lgkmcnt(4)
	v_mfma_f32_32x32x16_bf16 v[34:49], v[190:193], v[202:205], v[34:49]
	v_mfma_f32_32x32x16_bf16 v[18:33], v[198:201], v[194:197], v[18:33]
	v_mfma_f32_32x32x16_bf16 v[2:17], v[198:201], v[202:205], v[2:17]
	ds_read_b128 v[190:193], v87 offset:16384
	ds_read_b128 v[194:197], v87 offset:20480
	ds_read_b128 v[198:201], v86 offset:49152
	ds_read_b128 v[202:205], v86 offset:53248
	v_lshl_add_u64 v[66:67], v[66:67], 0, s[98:99]
	v_lshl_add_u64 v[70:71], v[70:71], 0, s[98:99]
	v_lshl_add_u64 v[74:75], v[74:75], 0, s[98:99]
	v_lshl_add_u64 v[78:79], v[78:79], 0, s[98:99]
	v_lshl_add_u64 v[68:69], v[68:69], 0, s[98:99]
	v_lshl_add_u64 v[72:73], v[72:73], 0, s[98:99]
	v_lshl_add_u64 v[76:77], v[76:77], 0, s[98:99]
	v_lshl_add_u64 v[80:81], v[80:81], 0, s[98:99]
	s_waitcnt lgkmcnt(0)
	s_barrier
	s_add_u32 m0, s32, 0x4000
	v_mfma_f32_32x32x16_bf16 v[50:65], v[162:165], v[182:185], v[50:65]
	global_load_lds_dwordx4 v[66:67], off
	s_add_u32 m0, s32, 0x5000
	v_mfma_f32_32x32x16_bf16 v[34:49], v[162:165], v[186:189], v[34:49]
	global_load_lds_dwordx4 v[70:71], off
	s_add_u32 m0, s32, 0x6000
	v_mfma_f32_32x32x16_bf16 v[18:33], v[166:169], v[182:185], v[18:33]
	global_load_lds_dwordx4 v[74:75], off
	s_add_u32 m0, s32, 0x7000
	v_mfma_f32_32x32x16_bf16 v[2:17], v[166:169], v[186:189], v[2:17]
	global_load_lds_dwordx4 v[78:79], off
	s_add_u32 m0, s32, 0xc000
	v_mfma_f32_32x32x16_bf16 v[50:65], v[190:193], v[198:201], v[50:65]
	global_load_lds_dwordx4 v[68:69], off
	s_add_u32 m0, s32, 0xd000
	v_mfma_f32_32x32x16_bf16 v[34:49], v[190:193], v[202:205], v[34:49]
	global_load_lds_dwordx4 v[72:73], off
	s_add_u32 m0, s32, 0xe000
	v_mfma_f32_32x32x16_bf16 v[18:33], v[194:197], v[198:201], v[18:33]
	global_load_lds_dwordx4 v[76:77], off
	s_add_u32 m0, s32, 0xf000
	v_mfma_f32_32x32x16_bf16 v[2:17], v[194:197], v[202:205], v[2:17]
	global_load_lds_dwordx4 v[80:81], off
	s_waitcnt vmcnt(8)
	s_barrier
	ds_read_b128 v[162:165], v91
	ds_read_b128 v[166:169], v92 offset:32768
	ds_read_b128 v[182:185], v91 offset:4096
	ds_read_b128 v[186:189], v92 offset:36864
	ds_read_b128 v[190:193], v93
	ds_read_b128 v[194:197], v90 offset:32768
	ds_read_b128 v[198:201], v93 offset:4096
	ds_read_b128 v[202:205], v90 offset:36864
	s_waitcnt lgkmcnt(6)
	v_mfma_f32_32x32x16_bf16 v[50:65], v[162:165], v[166:169], v[50:65]
	s_waitcnt lgkmcnt(4)
	v_mfma_f32_32x32x16_bf16 v[34:49], v[162:165], v[186:189], v[34:49]
	v_mfma_f32_32x32x16_bf16 v[18:33], v[182:185], v[166:169], v[18:33]
	v_mfma_f32_32x32x16_bf16 v[2:17], v[182:185], v[186:189], v[2:17]
	ds_read_b128 v[162:165], v89
	ds_read_b128 v[166:169], v89 offset:4096
	ds_read_b128 v[182:185], v88 offset:32768
	ds_read_b128 v[186:189], v88 offset:36864
	s_waitcnt lgkmcnt(6)
	v_mfma_f32_32x32x16_bf16 v[50:65], v[190:193], v[194:197], v[50:65]
	s_waitcnt lgkmcnt(4)
	v_mfma_f32_32x32x16_bf16 v[34:49], v[190:193], v[202:205], v[34:49]
	v_mfma_f32_32x32x16_bf16 v[18:33], v[198:201], v[194:197], v[18:33]
	v_mfma_f32_32x32x16_bf16 v[2:17], v[198:201], v[202:205], v[2:17]
	ds_read_b128 v[190:193], v87
	ds_read_b128 v[194:197], v87 offset:4096
	ds_read_b128 v[198:201], v86 offset:32768
	ds_read_b128 v[202:205], v86 offset:36864
	v_lshl_add_u64 v[66:67], v[66:67], 0, s[98:99]
	v_lshl_add_u64 v[70:71], v[70:71], 0, s[98:99]
	v_lshl_add_u64 v[74:75], v[74:75], 0, s[98:99]
	v_lshl_add_u64 v[78:79], v[78:79], 0, s[98:99]
	v_lshl_add_u64 v[68:69], v[68:69], 0, s[98:99]
	v_lshl_add_u64 v[72:73], v[72:73], 0, s[98:99]
	v_lshl_add_u64 v[76:77], v[76:77], 0, s[98:99]
	v_lshl_add_u64 v[80:81], v[80:81], 0, s[98:99]
	s_waitcnt lgkmcnt(0)
	s_barrier
	s_add_u32 m0, s32, 0x0
	v_mfma_f32_32x32x16_bf16 v[50:65], v[162:165], v[182:185], v[50:65]
	global_load_lds_dwordx4 v[66:67], off
	s_add_u32 m0, s32, 0x1000
	v_mfma_f32_32x32x16_bf16 v[34:49], v[162:165], v[186:189], v[34:49]
	global_load_lds_dwordx4 v[70:71], off
	s_add_u32 m0, s32, 0x2000
	v_mfma_f32_32x32x16_bf16 v[18:33], v[166:169], v[182:185], v[18:33]
	global_load_lds_dwordx4 v[74:75], off
	s_add_u32 m0, s32, 0x3000
	v_mfma_f32_32x32x16_bf16 v[2:17], v[166:169], v[186:189], v[2:17]
	global_load_lds_dwordx4 v[78:79], off
	s_add_u32 m0, s32, 0x8000
	v_mfma_f32_32x32x16_bf16 v[50:65], v[190:193], v[198:201], v[50:65]
	global_load_lds_dwordx4 v[68:69], off
	s_add_u32 m0, s32, 0x9000
	v_mfma_f32_32x32x16_bf16 v[34:49], v[190:193], v[202:205], v[34:49]
	global_load_lds_dwordx4 v[72:73], off
	s_add_u32 m0, s32, 0xa000
	v_mfma_f32_32x32x16_bf16 v[18:33], v[194:197], v[198:201], v[18:33]
	global_load_lds_dwordx4 v[76:77], off
	s_add_u32 m0, s32, 0xb000
	v_mfma_f32_32x32x16_bf16 v[2:17], v[194:197], v[202:205], v[2:17]
	global_load_lds_dwordx4 v[80:81], off
	s_waitcnt vmcnt(8)
	s_barrier
	ds_read_b128 v[162:165], v91 offset:16384
	ds_read_b128 v[166:169], v92 offset:49152
	ds_read_b128 v[182:185], v91 offset:20480
	ds_read_b128 v[186:189], v92 offset:53248
	ds_read_b128 v[190:193], v93 offset:16384
	ds_read_b128 v[194:197], v90 offset:49152
	ds_read_b128 v[198:201], v93 offset:20480
	ds_read_b128 v[202:205], v90 offset:53248
	s_waitcnt lgkmcnt(6)
	v_mfma_f32_32x32x16_bf16 v[50:65], v[162:165], v[166:169], v[50:65]
	s_waitcnt lgkmcnt(4)
	v_mfma_f32_32x32x16_bf16 v[34:49], v[162:165], v[186:189], v[34:49]
	v_mfma_f32_32x32x16_bf16 v[18:33], v[182:185], v[166:169], v[18:33]
	v_mfma_f32_32x32x16_bf16 v[2:17], v[182:185], v[186:189], v[2:17]
	ds_read_b128 v[162:165], v89 offset:16384
	ds_read_b128 v[166:169], v89 offset:20480
	ds_read_b128 v[182:185], v88 offset:49152
	ds_read_b128 v[186:189], v88 offset:53248
	s_waitcnt lgkmcnt(6)
	v_mfma_f32_32x32x16_bf16 v[50:65], v[190:193], v[194:197], v[50:65]
	s_waitcnt lgkmcnt(4)
	v_mfma_f32_32x32x16_bf16 v[34:49], v[190:193], v[202:205], v[34:49]
	v_mfma_f32_32x32x16_bf16 v[18:33], v[198:201], v[194:197], v[18:33]
	v_mfma_f32_32x32x16_bf16 v[2:17], v[198:201], v[202:205], v[2:17]
	ds_read_b128 v[190:193], v87 offset:16384
	ds_read_b128 v[194:197], v87 offset:20480
	ds_read_b128 v[198:201], v86 offset:49152
	ds_read_b128 v[202:205], v86 offset:53248
	v_lshl_add_u64 v[66:67], v[66:67], 0, s[98:99]
	v_lshl_add_u64 v[70:71], v[70:71], 0, s[98:99]
	v_lshl_add_u64 v[74:75], v[74:75], 0, s[98:99]
	v_lshl_add_u64 v[78:79], v[78:79], 0, s[98:99]
	v_lshl_add_u64 v[68:69], v[68:69], 0, s[98:99]
	v_lshl_add_u64 v[72:73], v[72:73], 0, s[98:99]
	v_lshl_add_u64 v[76:77], v[76:77], 0, s[98:99]
	v_lshl_add_u64 v[80:81], v[80:81], 0, s[98:99]
	s_waitcnt lgkmcnt(0)
	s_barrier
	s_add_u32 m0, s32, 0x4000
	v_mfma_f32_32x32x16_bf16 v[50:65], v[162:165], v[182:185], v[50:65]
	global_load_lds_dwordx4 v[66:67], off
	s_add_u32 m0, s32, 0x5000
	v_mfma_f32_32x32x16_bf16 v[34:49], v[162:165], v[186:189], v[34:49]
	global_load_lds_dwordx4 v[70:71], off
	s_add_u32 m0, s32, 0x6000
	v_mfma_f32_32x32x16_bf16 v[18:33], v[166:169], v[182:185], v[18:33]
	global_load_lds_dwordx4 v[74:75], off
	s_add_u32 m0, s32, 0x7000
	v_mfma_f32_32x32x16_bf16 v[2:17], v[166:169], v[186:189], v[2:17]
	global_load_lds_dwordx4 v[78:79], off
	s_add_u32 m0, s32, 0xc000
	v_mfma_f32_32x32x16_bf16 v[50:65], v[190:193], v[198:201], v[50:65]
	global_load_lds_dwordx4 v[68:69], off
	s_add_u32 m0, s32, 0xd000
	v_mfma_f32_32x32x16_bf16 v[34:49], v[190:193], v[202:205], v[34:49]
	global_load_lds_dwordx4 v[72:73], off
	s_add_u32 m0, s32, 0xe000
	v_mfma_f32_32x32x16_bf16 v[18:33], v[194:197], v[198:201], v[18:33]
	global_load_lds_dwordx4 v[76:77], off
	s_add_u32 m0, s32, 0xf000
	v_mfma_f32_32x32x16_bf16 v[2:17], v[194:197], v[202:205], v[2:17]
	global_load_lds_dwordx4 v[80:81], off
	s_waitcnt vmcnt(8)
	s_barrier
	ds_read_b128 v[162:165], v91
	ds_read_b128 v[166:169], v92 offset:32768
	ds_read_b128 v[182:185], v91 offset:4096
	ds_read_b128 v[186:189], v92 offset:36864
	ds_read_b128 v[190:193], v93
	ds_read_b128 v[194:197], v90 offset:32768
	ds_read_b128 v[198:201], v93 offset:4096
	ds_read_b128 v[202:205], v90 offset:36864
	s_waitcnt lgkmcnt(6)
	v_mfma_f32_32x32x16_bf16 v[50:65], v[162:165], v[166:169], v[50:65]
	s_waitcnt lgkmcnt(4)
	v_mfma_f32_32x32x16_bf16 v[34:49], v[162:165], v[186:189], v[34:49]
	v_mfma_f32_32x32x16_bf16 v[18:33], v[182:185], v[166:169], v[18:33]
	v_mfma_f32_32x32x16_bf16 v[2:17], v[182:185], v[186:189], v[2:17]
	ds_read_b128 v[162:165], v89
	ds_read_b128 v[166:169], v89 offset:4096
	ds_read_b128 v[182:185], v88 offset:32768
	ds_read_b128 v[186:189], v88 offset:36864
	s_waitcnt lgkmcnt(6)
	v_mfma_f32_32x32x16_bf16 v[50:65], v[190:193], v[194:197], v[50:65]
	s_waitcnt lgkmcnt(4)
	v_mfma_f32_32x32x16_bf16 v[34:49], v[190:193], v[202:205], v[34:49]
	v_mfma_f32_32x32x16_bf16 v[18:33], v[198:201], v[194:197], v[18:33]
	v_mfma_f32_32x32x16_bf16 v[2:17], v[198:201], v[202:205], v[2:17]
	ds_read_b128 v[190:193], v87
	ds_read_b128 v[194:197], v87 offset:4096
	ds_read_b128 v[198:201], v86 offset:32768
	ds_read_b128 v[202:205], v86 offset:36864
	v_lshl_add_u64 v[66:67], v[66:67], 0, s[98:99]
	v_lshl_add_u64 v[70:71], v[70:71], 0, s[98:99]
	v_lshl_add_u64 v[74:75], v[74:75], 0, s[98:99]
	v_lshl_add_u64 v[78:79], v[78:79], 0, s[98:99]
	v_lshl_add_u64 v[68:69], v[68:69], 0, s[98:99]
	v_lshl_add_u64 v[72:73], v[72:73], 0, s[98:99]
	v_lshl_add_u64 v[76:77], v[76:77], 0, s[98:99]
	v_lshl_add_u64 v[80:81], v[80:81], 0, s[98:99]
	s_waitcnt lgkmcnt(0)
	s_barrier
	s_add_u32 m0, s32, 0x0
	v_mfma_f32_32x32x16_bf16 v[50:65], v[162:165], v[182:185], v[50:65]
	global_load_lds_dwordx4 v[66:67], off
	s_add_u32 m0, s32, 0x1000
	v_mfma_f32_32x32x16_bf16 v[34:49], v[162:165], v[186:189], v[34:49]
	global_load_lds_dwordx4 v[70:71], off
	s_add_u32 m0, s32, 0x2000
	v_mfma_f32_32x32x16_bf16 v[18:33], v[166:169], v[182:185], v[18:33]
	global_load_lds_dwordx4 v[74:75], off
	s_add_u32 m0, s32, 0x3000
	v_mfma_f32_32x32x16_bf16 v[2:17], v[166:169], v[186:189], v[2:17]
	global_load_lds_dwordx4 v[78:79], off
	s_add_u32 m0, s32, 0x8000
	v_mfma_f32_32x32x16_bf16 v[50:65], v[190:193], v[198:201], v[50:65]
	global_load_lds_dwordx4 v[68:69], off
	s_add_u32 m0, s32, 0x9000
	v_mfma_f32_32x32x16_bf16 v[34:49], v[190:193], v[202:205], v[34:49]
	global_load_lds_dwordx4 v[72:73], off
	s_add_u32 m0, s32, 0xa000
	v_mfma_f32_32x32x16_bf16 v[18:33], v[194:197], v[198:201], v[18:33]
	global_load_lds_dwordx4 v[76:77], off
	s_add_u32 m0, s32, 0xb000
	v_mfma_f32_32x32x16_bf16 v[2:17], v[194:197], v[202:205], v[2:17]
	global_load_lds_dwordx4 v[80:81], off
	s_waitcnt vmcnt(8)
	s_barrier
	ds_read_b128 v[162:165], v91 offset:16384
	ds_read_b128 v[166:169], v92 offset:49152
	ds_read_b128 v[182:185], v91 offset:20480
	ds_read_b128 v[186:189], v92 offset:53248
	ds_read_b128 v[190:193], v93 offset:16384
	ds_read_b128 v[194:197], v90 offset:49152
	ds_read_b128 v[198:201], v93 offset:20480
	ds_read_b128 v[202:205], v90 offset:53248
	s_waitcnt lgkmcnt(6)
	v_mfma_f32_32x32x16_bf16 v[50:65], v[162:165], v[166:169], v[50:65]
	s_waitcnt lgkmcnt(4)
	v_mfma_f32_32x32x16_bf16 v[34:49], v[162:165], v[186:189], v[34:49]
	v_mfma_f32_32x32x16_bf16 v[18:33], v[182:185], v[166:169], v[18:33]
	v_mfma_f32_32x32x16_bf16 v[2:17], v[182:185], v[186:189], v[2:17]
	ds_read_b128 v[162:165], v89 offset:16384
	ds_read_b128 v[166:169], v89 offset:20480
	ds_read_b128 v[182:185], v88 offset:49152
	ds_read_b128 v[186:189], v88 offset:53248
	s_waitcnt lgkmcnt(6)
	v_mfma_f32_32x32x16_bf16 v[50:65], v[190:193], v[194:197], v[50:65]
	s_waitcnt lgkmcnt(4)
	v_mfma_f32_32x32x16_bf16 v[34:49], v[190:193], v[202:205], v[34:49]
	v_mfma_f32_32x32x16_bf16 v[18:33], v[198:201], v[194:197], v[18:33]
	v_mfma_f32_32x32x16_bf16 v[2:17], v[198:201], v[202:205], v[2:17]
	ds_read_b128 v[190:193], v87 offset:16384
	ds_read_b128 v[194:197], v87 offset:20480
	ds_read_b128 v[198:201], v86 offset:49152
	ds_read_b128 v[202:205], v86 offset:53248
	v_lshl_add_u64 v[66:67], v[66:67], 0, s[98:99]
	v_lshl_add_u64 v[70:71], v[70:71], 0, s[98:99]
	v_lshl_add_u64 v[74:75], v[74:75], 0, s[98:99]
	v_lshl_add_u64 v[78:79], v[78:79], 0, s[98:99]
	v_lshl_add_u64 v[68:69], v[68:69], 0, s[98:99]
	v_lshl_add_u64 v[72:73], v[72:73], 0, s[98:99]
	v_lshl_add_u64 v[76:77], v[76:77], 0, s[98:99]
	v_lshl_add_u64 v[80:81], v[80:81], 0, s[98:99]
	s_waitcnt lgkmcnt(0)
	s_barrier
	s_add_u32 m0, s32, 0x4000
	v_mfma_f32_32x32x16_bf16 v[50:65], v[162:165], v[182:185], v[50:65]
	global_load_lds_dwordx4 v[66:67], off
	s_add_u32 m0, s32, 0x5000
	v_mfma_f32_32x32x16_bf16 v[34:49], v[162:165], v[186:189], v[34:49]
	global_load_lds_dwordx4 v[70:71], off
	s_add_u32 m0, s32, 0x6000
	v_mfma_f32_32x32x16_bf16 v[18:33], v[166:169], v[182:185], v[18:33]
	global_load_lds_dwordx4 v[74:75], off
	s_add_u32 m0, s32, 0x7000
	v_mfma_f32_32x32x16_bf16 v[2:17], v[166:169], v[186:189], v[2:17]
	global_load_lds_dwordx4 v[78:79], off
	s_add_u32 m0, s32, 0xc000
	v_mfma_f32_32x32x16_bf16 v[50:65], v[190:193], v[198:201], v[50:65]
	global_load_lds_dwordx4 v[68:69], off
	s_add_u32 m0, s32, 0xd000
	v_mfma_f32_32x32x16_bf16 v[34:49], v[190:193], v[202:205], v[34:49]
	global_load_lds_dwordx4 v[72:73], off
	s_add_u32 m0, s32, 0xe000
	v_mfma_f32_32x32x16_bf16 v[18:33], v[194:197], v[198:201], v[18:33]
	global_load_lds_dwordx4 v[76:77], off
	s_add_u32 m0, s32, 0xf000
	v_mfma_f32_32x32x16_bf16 v[2:17], v[194:197], v[202:205], v[2:17]
	global_load_lds_dwordx4 v[80:81], off
	s_waitcnt vmcnt(8)
	s_barrier
	ds_read_b128 v[162:165], v91
	ds_read_b128 v[166:169], v92 offset:32768
	ds_read_b128 v[182:185], v91 offset:4096
	ds_read_b128 v[186:189], v92 offset:36864
	ds_read_b128 v[190:193], v93
	ds_read_b128 v[194:197], v90 offset:32768
	ds_read_b128 v[198:201], v93 offset:4096
	ds_read_b128 v[202:205], v90 offset:36864
	s_waitcnt lgkmcnt(6)
	v_mfma_f32_32x32x16_bf16 v[50:65], v[162:165], v[166:169], v[50:65]
	s_waitcnt lgkmcnt(4)
	v_mfma_f32_32x32x16_bf16 v[34:49], v[162:165], v[186:189], v[34:49]
	v_mfma_f32_32x32x16_bf16 v[18:33], v[182:185], v[166:169], v[18:33]
	v_mfma_f32_32x32x16_bf16 v[2:17], v[182:185], v[186:189], v[2:17]
	ds_read_b128 v[162:165], v89
	ds_read_b128 v[166:169], v89 offset:4096
	ds_read_b128 v[182:185], v88 offset:32768
	ds_read_b128 v[186:189], v88 offset:36864
	s_waitcnt lgkmcnt(6)
	v_mfma_f32_32x32x16_bf16 v[50:65], v[190:193], v[194:197], v[50:65]
	s_waitcnt lgkmcnt(4)
	v_mfma_f32_32x32x16_bf16 v[34:49], v[190:193], v[202:205], v[34:49]
	v_mfma_f32_32x32x16_bf16 v[18:33], v[198:201], v[194:197], v[18:33]
	v_mfma_f32_32x32x16_bf16 v[2:17], v[198:201], v[202:205], v[2:17]
	ds_read_b128 v[190:193], v87
	ds_read_b128 v[194:197], v87 offset:4096
	ds_read_b128 v[198:201], v86 offset:32768
	ds_read_b128 v[202:205], v86 offset:36864
	v_lshl_add_u64 v[66:67], v[66:67], 0, s[98:99]
	v_lshl_add_u64 v[70:71], v[70:71], 0, s[98:99]
	v_lshl_add_u64 v[74:75], v[74:75], 0, s[98:99]
	v_lshl_add_u64 v[78:79], v[78:79], 0, s[98:99]
	v_lshl_add_u64 v[68:69], v[68:69], 0, s[98:99]
	v_lshl_add_u64 v[72:73], v[72:73], 0, s[98:99]
	v_lshl_add_u64 v[76:77], v[76:77], 0, s[98:99]
	v_lshl_add_u64 v[80:81], v[80:81], 0, s[98:99]
	s_waitcnt lgkmcnt(0)
	s_barrier
	s_add_u32 m0, s32, 0x0
	v_mfma_f32_32x32x16_bf16 v[50:65], v[162:165], v[182:185], v[50:65]
	global_load_lds_dwordx4 v[66:67], off
	s_add_u32 m0, s32, 0x1000
	v_mfma_f32_32x32x16_bf16 v[34:49], v[162:165], v[186:189], v[34:49]
	global_load_lds_dwordx4 v[70:71], off
	s_add_u32 m0, s32, 0x2000
	v_mfma_f32_32x32x16_bf16 v[18:33], v[166:169], v[182:185], v[18:33]
	global_load_lds_dwordx4 v[74:75], off
	s_add_u32 m0, s32, 0x3000
	v_mfma_f32_32x32x16_bf16 v[2:17], v[166:169], v[186:189], v[2:17]
	global_load_lds_dwordx4 v[78:79], off
	s_add_u32 m0, s32, 0x8000
	v_mfma_f32_32x32x16_bf16 v[50:65], v[190:193], v[198:201], v[50:65]
	global_load_lds_dwordx4 v[68:69], off
	s_add_u32 m0, s32, 0x9000
	v_mfma_f32_32x32x16_bf16 v[34:49], v[190:193], v[202:205], v[34:49]
	global_load_lds_dwordx4 v[72:73], off
	s_add_u32 m0, s32, 0xa000
	v_mfma_f32_32x32x16_bf16 v[18:33], v[194:197], v[198:201], v[18:33]
	global_load_lds_dwordx4 v[76:77], off
	s_add_u32 m0, s32, 0xb000
	v_mfma_f32_32x32x16_bf16 v[2:17], v[194:197], v[202:205], v[2:17]
	global_load_lds_dwordx4 v[80:81], off
	s_waitcnt vmcnt(8)
	s_barrier
	ds_read_b128 v[162:165], v91 offset:16384
	ds_read_b128 v[166:169], v92 offset:49152
	ds_read_b128 v[182:185], v91 offset:20480
	ds_read_b128 v[186:189], v92 offset:53248
	ds_read_b128 v[190:193], v93 offset:16384
	ds_read_b128 v[194:197], v90 offset:49152
	ds_read_b128 v[198:201], v93 offset:20480
	ds_read_b128 v[202:205], v90 offset:53248
	s_waitcnt lgkmcnt(6)
	v_mfma_f32_32x32x16_bf16 v[50:65], v[162:165], v[166:169], v[50:65]
	s_waitcnt lgkmcnt(4)
	v_mfma_f32_32x32x16_bf16 v[34:49], v[162:165], v[186:189], v[34:49]
	v_mfma_f32_32x32x16_bf16 v[18:33], v[182:185], v[166:169], v[18:33]
	v_mfma_f32_32x32x16_bf16 v[2:17], v[182:185], v[186:189], v[2:17]
	ds_read_b128 v[162:165], v89 offset:16384
	ds_read_b128 v[166:169], v89 offset:20480
	ds_read_b128 v[182:185], v88 offset:49152
	ds_read_b128 v[186:189], v88 offset:53248
	s_waitcnt lgkmcnt(6)
	v_mfma_f32_32x32x16_bf16 v[50:65], v[190:193], v[194:197], v[50:65]
	s_waitcnt lgkmcnt(4)
	v_mfma_f32_32x32x16_bf16 v[34:49], v[190:193], v[202:205], v[34:49]
	v_mfma_f32_32x32x16_bf16 v[18:33], v[198:201], v[194:197], v[18:33]
	v_mfma_f32_32x32x16_bf16 v[2:17], v[198:201], v[202:205], v[2:17]
	ds_read_b128 v[190:193], v87 offset:16384
	ds_read_b128 v[194:197], v87 offset:20480
	ds_read_b128 v[198:201], v86 offset:49152
	ds_read_b128 v[202:205], v86 offset:53248
	v_lshl_add_u64 v[66:67], v[66:67], 0, s[98:99]
	v_lshl_add_u64 v[70:71], v[70:71], 0, s[98:99]
	v_lshl_add_u64 v[74:75], v[74:75], 0, s[98:99]
	v_lshl_add_u64 v[78:79], v[78:79], 0, s[98:99]
	v_lshl_add_u64 v[68:69], v[68:69], 0, s[98:99]
	v_lshl_add_u64 v[72:73], v[72:73], 0, s[98:99]
	v_lshl_add_u64 v[76:77], v[76:77], 0, s[98:99]
	v_lshl_add_u64 v[80:81], v[80:81], 0, s[98:99]
	s_waitcnt lgkmcnt(0)
	s_barrier
	s_add_u32 m0, s32, 0x4000
	v_mfma_f32_32x32x16_bf16 v[50:65], v[162:165], v[182:185], v[50:65]
	global_load_lds_dwordx4 v[66:67], off
	s_add_u32 m0, s32, 0x5000
	v_mfma_f32_32x32x16_bf16 v[34:49], v[162:165], v[186:189], v[34:49]
	global_load_lds_dwordx4 v[70:71], off
	s_add_u32 m0, s32, 0x6000
	v_mfma_f32_32x32x16_bf16 v[18:33], v[166:169], v[182:185], v[18:33]
	global_load_lds_dwordx4 v[74:75], off
	s_add_u32 m0, s32, 0x7000
	v_mfma_f32_32x32x16_bf16 v[2:17], v[166:169], v[186:189], v[2:17]
	global_load_lds_dwordx4 v[78:79], off
	s_add_u32 m0, s32, 0xc000
	v_mfma_f32_32x32x16_bf16 v[50:65], v[190:193], v[198:201], v[50:65]
	global_load_lds_dwordx4 v[68:69], off
	s_add_u32 m0, s32, 0xd000
	v_mfma_f32_32x32x16_bf16 v[34:49], v[190:193], v[202:205], v[34:49]
	global_load_lds_dwordx4 v[72:73], off
	s_add_u32 m0, s32, 0xe000
	v_mfma_f32_32x32x16_bf16 v[18:33], v[194:197], v[198:201], v[18:33]
	global_load_lds_dwordx4 v[76:77], off
	s_add_u32 m0, s32, 0xf000
	v_mfma_f32_32x32x16_bf16 v[2:17], v[194:197], v[202:205], v[2:17]
	global_load_lds_dwordx4 v[80:81], off
	s_waitcnt vmcnt(8)
	s_barrier
	ds_read_b128 v[162:165], v91
	ds_read_b128 v[166:169], v92 offset:32768
	ds_read_b128 v[182:185], v91 offset:4096
	ds_read_b128 v[186:189], v92 offset:36864
	ds_read_b128 v[190:193], v93
	ds_read_b128 v[194:197], v90 offset:32768
	ds_read_b128 v[198:201], v93 offset:4096
	ds_read_b128 v[202:205], v90 offset:36864
	s_waitcnt lgkmcnt(6)
	v_mfma_f32_32x32x16_bf16 v[50:65], v[162:165], v[166:169], v[50:65]
	s_waitcnt lgkmcnt(4)
	v_mfma_f32_32x32x16_bf16 v[34:49], v[162:165], v[186:189], v[34:49]
	v_mfma_f32_32x32x16_bf16 v[18:33], v[182:185], v[166:169], v[18:33]
	v_mfma_f32_32x32x16_bf16 v[2:17], v[182:185], v[186:189], v[2:17]
	ds_read_b128 v[162:165], v89
	ds_read_b128 v[166:169], v89 offset:4096
	ds_read_b128 v[182:185], v88 offset:32768
	ds_read_b128 v[186:189], v88 offset:36864
	s_waitcnt lgkmcnt(6)
	v_mfma_f32_32x32x16_bf16 v[50:65], v[190:193], v[194:197], v[50:65]
	s_waitcnt lgkmcnt(4)
	v_mfma_f32_32x32x16_bf16 v[34:49], v[190:193], v[202:205], v[34:49]
	v_mfma_f32_32x32x16_bf16 v[18:33], v[198:201], v[194:197], v[18:33]
	v_mfma_f32_32x32x16_bf16 v[2:17], v[198:201], v[202:205], v[2:17]
	ds_read_b128 v[190:193], v87
	ds_read_b128 v[194:197], v87 offset:4096
	ds_read_b128 v[198:201], v86 offset:32768
	ds_read_b128 v[202:205], v86 offset:36864
	v_lshl_add_u64 v[66:67], v[66:67], 0, s[98:99]
	v_lshl_add_u64 v[70:71], v[70:71], 0, s[98:99]
	v_lshl_add_u64 v[74:75], v[74:75], 0, s[98:99]
	v_lshl_add_u64 v[78:79], v[78:79], 0, s[98:99]
	v_lshl_add_u64 v[68:69], v[68:69], 0, s[98:99]
	v_lshl_add_u64 v[72:73], v[72:73], 0, s[98:99]
	v_lshl_add_u64 v[76:77], v[76:77], 0, s[98:99]
	v_lshl_add_u64 v[80:81], v[80:81], 0, s[98:99]
	s_waitcnt lgkmcnt(0)
	s_barrier
	s_add_u32 m0, s32, 0x0
	v_mfma_f32_32x32x16_bf16 v[50:65], v[162:165], v[182:185], v[50:65]
	global_load_lds_dwordx4 v[66:67], off
	s_add_u32 m0, s32, 0x1000
	v_mfma_f32_32x32x16_bf16 v[34:49], v[162:165], v[186:189], v[34:49]
	global_load_lds_dwordx4 v[70:71], off
	s_add_u32 m0, s32, 0x2000
	v_mfma_f32_32x32x16_bf16 v[18:33], v[166:169], v[182:185], v[18:33]
	global_load_lds_dwordx4 v[74:75], off
	s_add_u32 m0, s32, 0x3000
	v_mfma_f32_32x32x16_bf16 v[2:17], v[166:169], v[186:189], v[2:17]
	global_load_lds_dwordx4 v[78:79], off
	s_add_u32 m0, s32, 0x8000
	v_mfma_f32_32x32x16_bf16 v[50:65], v[190:193], v[198:201], v[50:65]
	global_load_lds_dwordx4 v[68:69], off
	s_add_u32 m0, s32, 0x9000
	v_mfma_f32_32x32x16_bf16 v[34:49], v[190:193], v[202:205], v[34:49]
	global_load_lds_dwordx4 v[72:73], off
	s_add_u32 m0, s32, 0xa000
	v_mfma_f32_32x32x16_bf16 v[18:33], v[194:197], v[198:201], v[18:33]
	global_load_lds_dwordx4 v[76:77], off
	s_add_u32 m0, s32, 0xb000
	v_mfma_f32_32x32x16_bf16 v[2:17], v[194:197], v[202:205], v[2:17]
	global_load_lds_dwordx4 v[80:81], off
	s_waitcnt vmcnt(8)
	s_barrier
	ds_read_b128 v[162:165], v91 offset:16384
	ds_read_b128 v[166:169], v92 offset:49152
	ds_read_b128 v[182:185], v91 offset:20480
	ds_read_b128 v[186:189], v92 offset:53248
	ds_read_b128 v[190:193], v93 offset:16384
	ds_read_b128 v[194:197], v90 offset:49152
	ds_read_b128 v[198:201], v93 offset:20480
	ds_read_b128 v[202:205], v90 offset:53248
	s_waitcnt lgkmcnt(6)
	v_mfma_f32_32x32x16_bf16 v[50:65], v[162:165], v[166:169], v[50:65]
	s_waitcnt lgkmcnt(4)
	v_mfma_f32_32x32x16_bf16 v[34:49], v[162:165], v[186:189], v[34:49]
	v_mfma_f32_32x32x16_bf16 v[18:33], v[182:185], v[166:169], v[18:33]
	v_mfma_f32_32x32x16_bf16 v[2:17], v[182:185], v[186:189], v[2:17]
	ds_read_b128 v[162:165], v89 offset:16384
	ds_read_b128 v[166:169], v89 offset:20480
	ds_read_b128 v[182:185], v88 offset:49152
	ds_read_b128 v[186:189], v88 offset:53248
	s_waitcnt lgkmcnt(6)
	v_mfma_f32_32x32x16_bf16 v[50:65], v[190:193], v[194:197], v[50:65]
	s_waitcnt lgkmcnt(4)
	v_mfma_f32_32x32x16_bf16 v[34:49], v[190:193], v[202:205], v[34:49]
	v_mfma_f32_32x32x16_bf16 v[18:33], v[198:201], v[194:197], v[18:33]
	v_mfma_f32_32x32x16_bf16 v[2:17], v[198:201], v[202:205], v[2:17]
	ds_read_b128 v[190:193], v87 offset:16384
	ds_read_b128 v[194:197], v87 offset:20480
	ds_read_b128 v[198:201], v86 offset:49152
	ds_read_b128 v[202:205], v86 offset:53248
	v_lshl_add_u64 v[66:67], v[66:67], 0, s[98:99]
	v_lshl_add_u64 v[70:71], v[70:71], 0, s[98:99]
	v_lshl_add_u64 v[74:75], v[74:75], 0, s[98:99]
	v_lshl_add_u64 v[78:79], v[78:79], 0, s[98:99]
	v_lshl_add_u64 v[68:69], v[68:69], 0, s[98:99]
	v_lshl_add_u64 v[72:73], v[72:73], 0, s[98:99]
	v_lshl_add_u64 v[76:77], v[76:77], 0, s[98:99]
	v_lshl_add_u64 v[80:81], v[80:81], 0, s[98:99]
	s_waitcnt lgkmcnt(0)
	s_barrier
	s_add_u32 m0, s32, 0x4000
	v_mfma_f32_32x32x16_bf16 v[50:65], v[162:165], v[182:185], v[50:65]
	global_load_lds_dwordx4 v[66:67], off
	s_add_u32 m0, s32, 0x5000
	v_mfma_f32_32x32x16_bf16 v[34:49], v[162:165], v[186:189], v[34:49]
	global_load_lds_dwordx4 v[70:71], off
	s_add_u32 m0, s32, 0x6000
	v_mfma_f32_32x32x16_bf16 v[18:33], v[166:169], v[182:185], v[18:33]
	global_load_lds_dwordx4 v[74:75], off
	s_add_u32 m0, s32, 0x7000
	v_mfma_f32_32x32x16_bf16 v[2:17], v[166:169], v[186:189], v[2:17]
	global_load_lds_dwordx4 v[78:79], off
	s_add_u32 m0, s32, 0xc000
	v_mfma_f32_32x32x16_bf16 v[50:65], v[190:193], v[198:201], v[50:65]
	global_load_lds_dwordx4 v[68:69], off
	s_add_u32 m0, s32, 0xd000
	v_mfma_f32_32x32x16_bf16 v[34:49], v[190:193], v[202:205], v[34:49]
	global_load_lds_dwordx4 v[72:73], off
	s_add_u32 m0, s32, 0xe000
	v_mfma_f32_32x32x16_bf16 v[18:33], v[194:197], v[198:201], v[18:33]
	global_load_lds_dwordx4 v[76:77], off
	s_add_u32 m0, s32, 0xf000
	v_mfma_f32_32x32x16_bf16 v[2:17], v[194:197], v[202:205], v[2:17]
	global_load_lds_dwordx4 v[80:81], off
	s_waitcnt vmcnt(8)
	s_barrier
	ds_read_b128 v[162:165], v91
	ds_read_b128 v[166:169], v92 offset:32768
	ds_read_b128 v[182:185], v91 offset:4096
	ds_read_b128 v[186:189], v92 offset:36864
	ds_read_b128 v[190:193], v93
	ds_read_b128 v[194:197], v90 offset:32768
	ds_read_b128 v[198:201], v93 offset:4096
	ds_read_b128 v[202:205], v90 offset:36864
	s_waitcnt lgkmcnt(6)
	v_mfma_f32_32x32x16_bf16 v[50:65], v[162:165], v[166:169], v[50:65]
	s_waitcnt lgkmcnt(4)
	v_mfma_f32_32x32x16_bf16 v[34:49], v[162:165], v[186:189], v[34:49]
	v_mfma_f32_32x32x16_bf16 v[18:33], v[182:185], v[166:169], v[18:33]
	v_mfma_f32_32x32x16_bf16 v[2:17], v[182:185], v[186:189], v[2:17]
	ds_read_b128 v[162:165], v89
	ds_read_b128 v[166:169], v89 offset:4096
	ds_read_b128 v[182:185], v88 offset:32768
	ds_read_b128 v[186:189], v88 offset:36864
	s_waitcnt lgkmcnt(6)
	v_mfma_f32_32x32x16_bf16 v[50:65], v[190:193], v[194:197], v[50:65]
	s_waitcnt lgkmcnt(4)
	v_mfma_f32_32x32x16_bf16 v[34:49], v[190:193], v[202:205], v[34:49]
	v_mfma_f32_32x32x16_bf16 v[18:33], v[198:201], v[194:197], v[18:33]
	v_mfma_f32_32x32x16_bf16 v[2:17], v[198:201], v[202:205], v[2:17]
	ds_read_b128 v[190:193], v87
	ds_read_b128 v[194:197], v87 offset:4096
	ds_read_b128 v[198:201], v86 offset:32768
	ds_read_b128 v[202:205], v86 offset:36864
	v_lshl_add_u64 v[66:67], v[66:67], 0, s[98:99]
	v_lshl_add_u64 v[70:71], v[70:71], 0, s[98:99]
	v_lshl_add_u64 v[74:75], v[74:75], 0, s[98:99]
	v_lshl_add_u64 v[78:79], v[78:79], 0, s[98:99]
	v_lshl_add_u64 v[68:69], v[68:69], 0, s[98:99]
	v_lshl_add_u64 v[72:73], v[72:73], 0, s[98:99]
	v_lshl_add_u64 v[76:77], v[76:77], 0, s[98:99]
	v_lshl_add_u64 v[80:81], v[80:81], 0, s[98:99]
	s_waitcnt lgkmcnt(0)
	s_barrier
	s_add_u32 m0, s32, 0x0
	v_mfma_f32_32x32x16_bf16 v[50:65], v[162:165], v[182:185], v[50:65]
	global_load_lds_dwordx4 v[66:67], off
	s_add_u32 m0, s32, 0x1000
	v_mfma_f32_32x32x16_bf16 v[34:49], v[162:165], v[186:189], v[34:49]
	global_load_lds_dwordx4 v[70:71], off
	s_add_u32 m0, s32, 0x2000
	v_mfma_f32_32x32x16_bf16 v[18:33], v[166:169], v[182:185], v[18:33]
	global_load_lds_dwordx4 v[74:75], off
	s_add_u32 m0, s32, 0x3000
	v_mfma_f32_32x32x16_bf16 v[2:17], v[166:169], v[186:189], v[2:17]
	global_load_lds_dwordx4 v[78:79], off
	s_add_u32 m0, s32, 0x8000
	v_mfma_f32_32x32x16_bf16 v[50:65], v[190:193], v[198:201], v[50:65]
	global_load_lds_dwordx4 v[68:69], off
	s_add_u32 m0, s32, 0x9000
	v_mfma_f32_32x32x16_bf16 v[34:49], v[190:193], v[202:205], v[34:49]
	global_load_lds_dwordx4 v[72:73], off
	s_add_u32 m0, s32, 0xa000
	v_mfma_f32_32x32x16_bf16 v[18:33], v[194:197], v[198:201], v[18:33]
	global_load_lds_dwordx4 v[76:77], off
	s_add_u32 m0, s32, 0xb000
	v_mfma_f32_32x32x16_bf16 v[2:17], v[194:197], v[202:205], v[2:17]
	global_load_lds_dwordx4 v[80:81], off
	s_waitcnt vmcnt(8)
	s_barrier
	ds_read_b128 v[162:165], v91 offset:16384
	ds_read_b128 v[166:169], v92 offset:49152
	ds_read_b128 v[182:185], v91 offset:20480
	ds_read_b128 v[186:189], v92 offset:53248
	ds_read_b128 v[190:193], v93 offset:16384
	ds_read_b128 v[194:197], v90 offset:49152
	ds_read_b128 v[198:201], v93 offset:20480
	ds_read_b128 v[202:205], v90 offset:53248
	s_waitcnt lgkmcnt(6)
	v_mfma_f32_32x32x16_bf16 v[50:65], v[162:165], v[166:169], v[50:65]
	s_waitcnt lgkmcnt(4)
	v_mfma_f32_32x32x16_bf16 v[34:49], v[162:165], v[186:189], v[34:49]
	v_mfma_f32_32x32x16_bf16 v[18:33], v[182:185], v[166:169], v[18:33]
	v_mfma_f32_32x32x16_bf16 v[2:17], v[182:185], v[186:189], v[2:17]
	ds_read_b128 v[162:165], v89 offset:16384
	ds_read_b128 v[166:169], v89 offset:20480
	ds_read_b128 v[182:185], v88 offset:49152
	ds_read_b128 v[186:189], v88 offset:53248
	s_waitcnt lgkmcnt(6)
	v_mfma_f32_32x32x16_bf16 v[50:65], v[190:193], v[194:197], v[50:65]
	s_waitcnt lgkmcnt(4)
	v_mfma_f32_32x32x16_bf16 v[34:49], v[190:193], v[202:205], v[34:49]
	v_mfma_f32_32x32x16_bf16 v[18:33], v[198:201], v[194:197], v[18:33]
	v_mfma_f32_32x32x16_bf16 v[2:17], v[198:201], v[202:205], v[2:17]
	ds_read_b128 v[190:193], v87 offset:16384
	ds_read_b128 v[194:197], v87 offset:20480
	ds_read_b128 v[198:201], v86 offset:49152
	ds_read_b128 v[202:205], v86 offset:53248
	v_lshl_add_u64 v[66:67], v[66:67], 0, s[98:99]
	v_lshl_add_u64 v[70:71], v[70:71], 0, s[98:99]
	v_lshl_add_u64 v[74:75], v[74:75], 0, s[98:99]
	v_lshl_add_u64 v[78:79], v[78:79], 0, s[98:99]
	v_lshl_add_u64 v[68:69], v[68:69], 0, s[98:99]
	v_lshl_add_u64 v[72:73], v[72:73], 0, s[98:99]
	v_lshl_add_u64 v[76:77], v[76:77], 0, s[98:99]
	v_lshl_add_u64 v[80:81], v[80:81], 0, s[98:99]
	s_waitcnt lgkmcnt(0)
	s_barrier
	s_add_u32 m0, s32, 0x4000
	v_mfma_f32_32x32x16_bf16 v[50:65], v[162:165], v[182:185], v[50:65]
	global_load_lds_dwordx4 v[66:67], off
	s_add_u32 m0, s32, 0x5000
	v_mfma_f32_32x32x16_bf16 v[34:49], v[162:165], v[186:189], v[34:49]
	global_load_lds_dwordx4 v[70:71], off
	s_add_u32 m0, s32, 0x6000
	v_mfma_f32_32x32x16_bf16 v[18:33], v[166:169], v[182:185], v[18:33]
	global_load_lds_dwordx4 v[74:75], off
	s_add_u32 m0, s32, 0x7000
	v_mfma_f32_32x32x16_bf16 v[2:17], v[166:169], v[186:189], v[2:17]
	global_load_lds_dwordx4 v[78:79], off
	s_add_u32 m0, s32, 0xc000
	v_mfma_f32_32x32x16_bf16 v[50:65], v[190:193], v[198:201], v[50:65]
	global_load_lds_dwordx4 v[68:69], off
	s_add_u32 m0, s32, 0xd000
	v_mfma_f32_32x32x16_bf16 v[34:49], v[190:193], v[202:205], v[34:49]
	global_load_lds_dwordx4 v[72:73], off
	s_add_u32 m0, s32, 0xe000
	v_mfma_f32_32x32x16_bf16 v[18:33], v[194:197], v[198:201], v[18:33]
	global_load_lds_dwordx4 v[76:77], off
	s_add_u32 m0, s32, 0xf000
	v_mfma_f32_32x32x16_bf16 v[2:17], v[194:197], v[202:205], v[2:17]
	global_load_lds_dwordx4 v[80:81], off
	s_waitcnt vmcnt(8)
	s_barrier
	ds_read_b128 v[162:165], v91
	ds_read_b128 v[166:169], v92 offset:32768
	ds_read_b128 v[182:185], v91 offset:4096
	ds_read_b128 v[186:189], v92 offset:36864
	ds_read_b128 v[190:193], v93
	ds_read_b128 v[194:197], v90 offset:32768
	ds_read_b128 v[198:201], v93 offset:4096
	ds_read_b128 v[202:205], v90 offset:36864
	s_waitcnt lgkmcnt(6)
	v_mfma_f32_32x32x16_bf16 v[50:65], v[162:165], v[166:169], v[50:65]
	s_waitcnt lgkmcnt(4)
	v_mfma_f32_32x32x16_bf16 v[34:49], v[162:165], v[186:189], v[34:49]
	v_mfma_f32_32x32x16_bf16 v[18:33], v[182:185], v[166:169], v[18:33]
	v_mfma_f32_32x32x16_bf16 v[2:17], v[182:185], v[186:189], v[2:17]
	ds_read_b128 v[162:165], v89
	ds_read_b128 v[166:169], v89 offset:4096
	ds_read_b128 v[182:185], v88 offset:32768
	ds_read_b128 v[186:189], v88 offset:36864
	s_waitcnt lgkmcnt(6)
	v_mfma_f32_32x32x16_bf16 v[50:65], v[190:193], v[194:197], v[50:65]
	s_waitcnt lgkmcnt(4)
	v_mfma_f32_32x32x16_bf16 v[34:49], v[190:193], v[202:205], v[34:49]
	v_mfma_f32_32x32x16_bf16 v[18:33], v[198:201], v[194:197], v[18:33]
	v_mfma_f32_32x32x16_bf16 v[2:17], v[198:201], v[202:205], v[2:17]
	ds_read_b128 v[190:193], v87
	ds_read_b128 v[194:197], v87 offset:4096
	ds_read_b128 v[198:201], v86 offset:32768
	ds_read_b128 v[202:205], v86 offset:36864
	v_lshl_add_u64 v[66:67], v[66:67], 0, s[98:99]
	v_lshl_add_u64 v[70:71], v[70:71], 0, s[98:99]
	v_lshl_add_u64 v[74:75], v[74:75], 0, s[98:99]
	v_lshl_add_u64 v[78:79], v[78:79], 0, s[98:99]
	v_lshl_add_u64 v[68:69], v[68:69], 0, s[98:99]
	v_lshl_add_u64 v[72:73], v[72:73], 0, s[98:99]
	v_lshl_add_u64 v[76:77], v[76:77], 0, s[98:99]
	v_lshl_add_u64 v[80:81], v[80:81], 0, s[98:99]
	s_waitcnt lgkmcnt(0)
	s_barrier
	s_add_u32 m0, s32, 0x0
	s_nop 0
	global_load_lds_dwordx4 v[66:67], off
	s_add_u32 m0, s32, 0x1000
	s_nop 0
	global_load_lds_dwordx4 v[70:71], off
	s_add_u32 m0, s32, 0x2000
	s_nop 0
	global_load_lds_dwordx4 v[74:75], off
	s_add_u32 m0, s32, 0x3000
	s_nop 0
	global_load_lds_dwordx4 v[78:79], off
	s_add_u32 m0, s32, 0x8000
	s_nop 0
	global_load_lds_dwordx4 v[68:69], off
	s_add_u32 m0, s32, 0x9000
	s_nop 0
	global_load_lds_dwordx4 v[72:73], off
	s_add_u32 m0, s32, 0xa000
	s_nop 0
	global_load_lds_dwordx4 v[76:77], off
	s_add_u32 m0, s32, 0xb000
	s_nop 0
	global_load_lds_dwordx4 v[80:81], off
	s_waitcnt vmcnt(8)
	s_barrier
	s_nop 0
	s_nop 0
	s_nop 0
	s_nop 0
	s_nop 0
	s_nop 0
	s_nop 0
	v_mfma_f32_32x32x16_bf16 v[50:65], v[162:165], v[182:185], v[50:65]
	v_mfma_f32_32x32x16_bf16 v[34:49], v[162:165], v[186:189], v[34:49]
	v_mfma_f32_32x32x16_bf16 v[18:33], v[166:169], v[182:185], v[18:33]
	v_mfma_f32_32x32x16_bf16 v[2:17], v[166:169], v[186:189], v[2:17]
	ds_read_b128 v[110:113], v91 offset:16384
	ds_read_b128 v[114:117], v91 offset:20480
	ds_read_b128 v[118:121], v92 offset:49152
	ds_read_b128 v[122:125], v92 offset:53248
	ds_read_b128 v[162:165], v93 offset:16384
	ds_read_b128 v[166:169], v93 offset:20480
	ds_read_b128 v[182:185], v90 offset:49152
	ds_read_b128 v[186:189], v90 offset:53248
	v_mfma_f32_32x32x16_bf16 v[50:65], v[190:193], v[198:201], v[50:65]
	v_mfma_f32_32x32x16_bf16 v[34:49], v[190:193], v[202:205], v[34:49]
	v_mfma_f32_32x32x16_bf16 v[18:33], v[194:197], v[198:201], v[18:33]
	v_mfma_f32_32x32x16_bf16 v[2:17], v[194:197], v[202:205], v[2:17]
	s_waitcnt lgkmcnt(5)
	v_mfma_f32_32x32x16_bf16 v[50:65], v[110:113], v[118:121], v[50:65]
	s_waitcnt lgkmcnt(4)
	v_mfma_f32_32x32x16_bf16 v[34:49], v[110:113], v[122:125], v[34:49]
	v_mfma_f32_32x32x16_bf16 v[18:33], v[114:117], v[118:121], v[18:33]
	v_mfma_f32_32x32x16_bf16 v[2:17], v[114:117], v[122:125], v[2:17]
	ds_read_b128 v[110:113], v89 offset:16384
	ds_read_b128 v[114:117], v89 offset:20480
	ds_read_b128 v[118:121], v88 offset:49152
	ds_read_b128 v[122:125], v88 offset:53248
	s_waitcnt lgkmcnt(5)
	v_mfma_f32_32x32x16_bf16 v[50:65], v[162:165], v[182:185], v[50:65]
	s_waitcnt lgkmcnt(4)
	v_mfma_f32_32x32x16_bf16 v[34:49], v[162:165], v[186:189], v[34:49]
	v_mfma_f32_32x32x16_bf16 v[18:33], v[166:169], v[182:185], v[18:33]
	v_mfma_f32_32x32x16_bf16 v[2:17], v[166:169], v[186:189], v[2:17]
	ds_read_b128 v[162:165], v87 offset:16384
	ds_read_b128 v[166:169], v87 offset:20480
	ds_read_b128 v[182:185], v86 offset:49152
	ds_read_b128 v[186:189], v86 offset:53248
	s_waitcnt lgkmcnt(5)
	v_mfma_f32_32x32x16_bf16 v[50:65], v[110:113], v[118:121], v[50:65]
	v_lshl_add_u64 v[66:67], v[66:67], 0, s[98:99]
	v_lshl_add_u64 v[70:71], v[70:71], 0, s[98:99]
	v_lshl_add_u64 v[74:75], v[74:75], 0, s[98:99]
	v_lshl_add_u64 v[78:79], v[78:79], 0, s[98:99]
	v_lshl_add_u64 v[68:69], v[68:69], 0, s[98:99]
	v_lshl_add_u64 v[72:73], v[72:73], 0, s[98:99]
	v_lshl_add_u64 v[76:77], v[76:77], 0, s[98:99]
	v_lshl_add_u64 v[80:81], v[80:81], 0, s[98:99]
	s_waitcnt lgkmcnt(0)
	s_barrier
	s_add_u32 m0, s32, 0x4000
	s_nop 0
	global_load_lds_dwordx4 v[66:67], off
	s_add_u32 m0, s32, 0x5000
	s_nop 0
	global_load_lds_dwordx4 v[70:71], off
	s_add_u32 m0, s32, 0x6000
	s_nop 0
	global_load_lds_dwordx4 v[74:75], off
	s_add_u32 m0, s32, 0x7000
	s_nop 0
	global_load_lds_dwordx4 v[78:79], off
	s_add_u32 m0, s32, 0xc000
	s_nop 0
	global_load_lds_dwordx4 v[68:69], off
	s_add_u32 m0, s32, 0xd000
	s_nop 0
	global_load_lds_dwordx4 v[72:73], off
	s_add_u32 m0, s32, 0xe000
	s_nop 0
	global_load_lds_dwordx4 v[76:77], off
	s_add_u32 m0, s32, 0xf000
	s_nop 0
	global_load_lds_dwordx4 v[80:81], off
	s_waitcnt vmcnt(8)
	s_barrier
	v_mfma_f32_32x32x16_bf16 v[34:49], v[110:113], v[122:125], v[34:49]
	v_mfma_f32_32x32x16_bf16 v[18:33], v[114:117], v[118:121], v[18:33]
	v_mfma_f32_32x32x16_bf16 v[2:17], v[114:117], v[122:125], v[2:17]
	ds_read_b128 v[110:113], v91
	ds_read_b128 v[114:117], v91 offset:4096
	ds_read_b128 v[118:121], v92 offset:32768
	ds_read_b128 v[122:125], v92 offset:36864
	ds_read_b128 v[126:129], v93
	ds_read_b128 v[134:137], v93 offset:4096
	ds_read_b128 v[138:141], v90 offset:32768
	ds_read_b128 v[142:145], v90 offset:36864
	v_mfma_f32_32x32x16_bf16 v[50:65], v[162:165], v[182:185], v[50:65]
	v_mfma_f32_32x32x16_bf16 v[34:49], v[162:165], v[186:189], v[34:49]
	v_mfma_f32_32x32x16_bf16 v[18:33], v[166:169], v[182:185], v[18:33]
	v_mfma_f32_32x32x16_bf16 v[2:17], v[166:169], v[186:189], v[2:17]
	s_waitcnt lgkmcnt(5)
	v_mfma_f32_32x32x16_bf16 v[50:65], v[110:113], v[118:121], v[50:65]
	s_waitcnt lgkmcnt(4)
	v_mfma_f32_32x32x16_bf16 v[34:49], v[110:113], v[122:125], v[34:49]
	v_mfma_f32_32x32x16_bf16 v[18:33], v[114:117], v[118:121], v[18:33]
	v_mfma_f32_32x32x16_bf16 v[2:17], v[114:117], v[122:125], v[2:17]
	ds_read_b128 v[110:113], v89
	ds_read_b128 v[114:117], v89 offset:4096
	ds_read_b128 v[118:121], v88 offset:32768
	ds_read_b128 v[122:125], v88 offset:36864
	s_waitcnt lgkmcnt(5)
	v_mfma_f32_32x32x16_bf16 v[50:65], v[126:129], v[138:141], v[50:65]
	s_waitcnt lgkmcnt(4)
	v_mfma_f32_32x32x16_bf16 v[34:49], v[126:129], v[142:145], v[34:49]
	v_mfma_f32_32x32x16_bf16 v[18:33], v[134:137], v[138:141], v[18:33]
	v_mfma_f32_32x32x16_bf16 v[2:17], v[134:137], v[142:145], v[2:17]
	ds_read_b128 v[126:129], v87
	ds_read_b128 v[134:137], v87 offset:4096
	ds_read_b128 v[138:141], v86 offset:32768
	ds_read_b128 v[142:145], v86 offset:36864
	s_waitcnt vmcnt(0)
	s_waitcnt lgkmcnt(0)
	s_barrier
	ds_read_b128 v[66:69], v91 offset:16384
	ds_read_b128 v[70:73], v91 offset:20480
	ds_read_b128 v[74:77], v92 offset:49152
	ds_read_b128 v[78:81], v92 offset:53248
	ds_read_b128 v[94:97], v93 offset:16384
	ds_read_b128 v[98:101], v93 offset:20480
	ds_read_b128 v[102:105], v90 offset:49152
	ds_read_b128 v[90:93], v90 offset:53248
	v_mfma_f32_32x32x16_bf16 v[50:65], v[110:113], v[118:121], v[50:65]
	v_mfma_f32_32x32x16_bf16 v[34:49], v[110:113], v[122:125], v[34:49]
	v_mfma_f32_32x32x16_bf16 v[18:33], v[114:117], v[118:121], v[18:33]
	v_mfma_f32_32x32x16_bf16 v[2:17], v[114:117], v[122:125], v[2:17]
	v_mfma_f32_32x32x16_bf16 v[50:65], v[126:129], v[138:141], v[50:65]
	v_mfma_f32_32x32x16_bf16 v[34:49], v[126:129], v[142:145], v[34:49]
	v_mfma_f32_32x32x16_bf16 v[18:33], v[134:137], v[138:141], v[18:33]
	v_mfma_f32_32x32x16_bf16 v[2:17], v[134:137], v[142:145], v[2:17]
	s_waitcnt lgkmcnt(5)
	v_mfma_f32_32x32x16_bf16 v[50:65], v[66:69], v[74:77], v[50:65]
	s_waitcnt lgkmcnt(4)
	v_mfma_f32_32x32x16_bf16 v[34:49], v[66:69], v[78:81], v[34:49]
	v_mfma_f32_32x32x16_bf16 v[18:33], v[70:73], v[74:77], v[18:33]
	v_mfma_f32_32x32x16_bf16 v[2:17], v[70:73], v[78:81], v[2:17]
	ds_read_b128 v[66:69], v89 offset:16384
	ds_read_b128 v[70:73], v89 offset:20480
	ds_read_b128 v[74:77], v88 offset:49152
	ds_read_b128 v[78:81], v88 offset:53248
	s_waitcnt lgkmcnt(5)
	v_mfma_f32_32x32x16_bf16 v[50:65], v[94:97], v[102:105], v[50:65]
	s_waitcnt lgkmcnt(4)
	v_mfma_f32_32x32x16_bf16 v[34:49], v[94:97], v[90:93], v[34:49]
	v_mfma_f32_32x32x16_bf16 v[18:33], v[98:101], v[102:105], v[18:33]
	v_mfma_f32_32x32x16_bf16 v[2:17], v[98:101], v[90:93], v[2:17]
	ds_read_b128 v[88:91], v87 offset:16384
	ds_read_b128 v[92:95], v87 offset:20480
	ds_read_b128 v[96:99], v86 offset:49152
	ds_read_b128 v[100:103], v86 offset:53248
	s_waitcnt lgkmcnt(5)
	v_mfma_f32_32x32x16_bf16 v[50:65], v[66:69], v[74:77], v[50:65]
	v_lshlrev_b32_e32 v0, 6, v85
	v_lshlrev_b32_e32 v84, 6, v84
	v_subrev_u32_e32 v0, s6, v0
	v_add_u32_e32 v0, s4, v0
	v_ashrrev_i32_e32 v0, 6, v0
	v_lshlrev_b32_e32 v85, 2, v83
	s_waitcnt lgkmcnt(0)
	v_mfma_f32_32x32x16_bf16 v[50:65], v[88:91], v[96:99], v[50:65]
	s_barrier
	v_or_b32_e32 v83, 2, v84
	v_or_b32_e32 v86, 3, v84
	v_or_b32_e32 v87, 8, v85
	s_add_i32 s5, s5, s66
	s_add_i32 s4, s4, s3
	v_mfma_f32_32x32x16_bf16 v[34:49], v[66:69], v[78:81], v[34:49]
	v_lshl_add_u32 v66, s34, 7, v84
	v_ashrrev_i32_e32 v66, 1, v66
	v_and_b32_e32 v66, 0xffffffc0, v66
	v_add_u32_e32 v66, v66, v0
	v_ashrrev_i32_e32 v67, 31, v66
	v_lshlrev_b64 v[66:67], 14, v[66:67]
	v_lshl_add_u64 v[66:67], s[50:51], 0, v[66:67]
	v_lshlrev_b32_e32 v0, 1, v82
	v_lshl_add_u64 v[66:67], v[66:67], 0, v[0:1]
	v_max_f32_e32 v0, v50, v50
	v_max_f32_e32 v0, 0, v0
	v_or_b32_e32 v68, v85, v84
	v_mul_f32_e32 v0, v0, v0
	v_cvt_pk_bf16_f32 v50, v0, s0
	v_lshlrev_b32_e32 v0, 7, v68
	v_and_b32_e32 v0, 0x2200, v0
	v_lshl_add_u64 v[68:69], v[66:67], 0, v[0:1]
	v_or_b32_e32 v82, 1, v84
	global_store_short v[68:69], v50, off
	v_or_b32_e32 v0, v85, v82
	v_max_f32_e32 v50, v51, v51
	v_max_f32_e32 v50, 0, v50
	v_lshlrev_b32_e32 v0, 7, v0
	v_mul_f32_e32 v50, v50, v50
	v_and_b32_e32 v0, 0x2280, v0
	v_mfma_f32_32x32x16_bf16 v[18:33], v[70:73], v[74:77], v[18:33]
	v_max_f32_e32 v52, v52, v52
	v_max_f32_e32 v52, 0, v52
	v_mul_f32_e32 v52, v52, v52
	v_cvt_pk_bf16_f32 v52, v52, s0
	v_max_f32_e32 v54, v54, v54
	v_max_f32_e32 v54, 0, v54
	v_mul_f32_e32 v54, v54, v54
	v_mfma_f32_32x32x16_bf16 v[2:17], v[70:73], v[78:81], v[2:17]
	v_cvt_pk_bf16_f32 v70, v50, s0
	v_lshl_add_u64 v[50:51], v[66:67], 0, v[0:1]
	v_or_b32_e32 v0, v85, v83
	v_lshlrev_b32_e32 v0, 7, v0
	v_and_b32_e32 v0, 0x2300, v0
	global_store_short v[50:51], v70, off
	v_lshl_add_u64 v[70:71], v[66:67], 0, v[0:1]
	global_store_short v[70:71], v52, off
	v_or_b32_e32 v0, v85, v86
	v_max_f32_e32 v52, v53, v53
	v_max_f32_e32 v52, 0, v52
	v_lshlrev_b32_e32 v0, 7, v0
	v_mul_f32_e32 v52, v52, v52
	v_and_b32_e32 v0, 0x2380, v0
	v_cvt_pk_bf16_f32 v72, v52, s0
	v_lshl_add_u64 v[52:53], v[66:67], 0, v[0:1]
	v_or_b32_e32 v0, v87, v84
	v_lshlrev_b32_e32 v0, 7, v0
	v_and_b32_e32 v0, 0x2600, v0
	global_store_short v[52:53], v72, off
	v_cvt_pk_bf16_f32 v54, v54, s0
	v_lshl_add_u64 v[72:73], v[66:67], 0, v[0:1]
	global_store_short v[72:73], v54, off
	v_or_b32_e32 v0, v87, v82
	v_max_f32_e32 v54, v55, v55
	v_max_f32_e32 v54, 0, v54
	v_lshlrev_b32_e32 v0, 7, v0
	v_mul_f32_e32 v54, v54, v54
	v_and_b32_e32 v0, 0x2680, v0
	v_cvt_pk_bf16_f32 v74, v54, s0
	v_lshl_add_u64 v[54:55], v[66:67], 0, v[0:1]
	v_or_b32_e32 v0, v87, v83
	v_max_f32_e32 v56, v56, v56
	v_max_f32_e32 v56, 0, v56
	v_lshlrev_b32_e32 v0, 7, v0
	v_mul_f32_e32 v56, v56, v56
	v_and_b32_e32 v0, 0x2700, v0
	global_store_short v[54:55], v74, off
	v_cvt_pk_bf16_f32 v56, v56, s0
	v_lshl_add_u64 v[74:75], v[66:67], 0, v[0:1]
	global_store_short v[74:75], v56, off
	v_or_b32_e32 v0, v87, v86
	v_max_f32_e32 v56, v57, v57
	v_max_f32_e32 v56, 0, v56
	v_lshlrev_b32_e32 v0, 7, v0
	v_mfma_f32_32x32x16_bf16 v[34:49], v[88:91], v[100:103], v[34:49]
	v_mul_f32_e32 v56, v56, v56
	v_and_b32_e32 v0, 0x2780, v0
	v_or_b32_e32 v88, 16, v85
	v_cvt_pk_bf16_f32 v76, v56, s0
	v_lshl_add_u64 v[56:57], v[66:67], 0, v[0:1]
	v_or_b32_e32 v0, v88, v84
	v_max_f32_e32 v58, v58, v58
	v_max_f32_e32 v58, 0, v58
	v_lshlrev_b32_e32 v0, 7, v0
	v_mul_f32_e32 v58, v58, v58
	v_and_b32_e32 v0, 0x2a00, v0
	global_store_short v[56:57], v76, off
	v_cvt_pk_bf16_f32 v58, v58, s0
	v_lshl_add_u64 v[76:77], v[66:67], 0, v[0:1]
	global_store_short v[76:77], v58, off
	v_or_b32_e32 v0, v88, v82
	v_max_f32_e32 v58, v59, v59
	v_max_f32_e32 v58, 0, v58
	v_lshlrev_b32_e32 v0, 7, v0
	v_mul_f32_e32 v58, v58, v58
	v_and_b32_e32 v0, 0x2a80, v0
	v_cvt_pk_bf16_f32 v78, v58, s0
	v_lshl_add_u64 v[58:59], v[66:67], 0, v[0:1]
	v_or_b32_e32 v0, v88, v83
	v_max_f32_e32 v60, v60, v60
	v_max_f32_e32 v60, 0, v60
	v_lshlrev_b32_e32 v0, 7, v0
	v_mul_f32_e32 v60, v60, v60
	v_and_b32_e32 v0, 0x2b00, v0
	global_store_short v[58:59], v78, off
	v_cvt_pk_bf16_f32 v60, v60, s0
	v_lshl_add_u64 v[78:79], v[66:67], 0, v[0:1]
	global_store_short v[78:79], v60, off
	v_or_b32_e32 v0, v88, v86
	v_max_f32_e32 v60, v61, v61
	v_max_f32_e32 v60, 0, v60
	v_lshlrev_b32_e32 v0, 7, v0
	v_mul_f32_e32 v60, v60, v60
	v_and_b32_e32 v0, 0x2b80, v0
	v_or_b32_e32 v89, 24, v85
	v_cvt_pk_bf16_f32 v80, v60, s0
	v_lshl_add_u64 v[60:61], v[66:67], 0, v[0:1]
	v_or_b32_e32 v0, v89, v84
	v_max_f32_e32 v62, v62, v62
	v_max_f32_e32 v62, 0, v62
	v_lshlrev_b32_e32 v0, 7, v0
	v_mul_f32_e32 v62, v62, v62
	v_and_b32_e32 v0, 0x2e00, v0
	global_store_short v[60:61], v80, off
	v_cvt_pk_bf16_f32 v62, v62, s0
	v_lshl_add_u64 v[80:81], v[66:67], 0, v[0:1]
	global_store_short v[80:81], v62, off
	v_or_b32_e32 v0, v89, v82
	v_max_f32_e32 v62, v63, v63
	v_max_f32_e32 v62, 0, v62
	v_lshlrev_b32_e32 v0, 7, v0
	v_mul_f32_e32 v62, v62, v62
	v_and_b32_e32 v0, 0x2e80, v0
	v_cvt_pk_bf16_f32 v82, v62, s0
	v_lshl_add_u64 v[62:63], v[66:67], 0, v[0:1]
	v_or_b32_e32 v0, v89, v83
	v_max_f32_e32 v64, v64, v64
	v_max_f32_e32 v64, 0, v64
	v_lshlrev_b32_e32 v0, 7, v0
	v_mul_f32_e32 v64, v64, v64
	v_and_b32_e32 v0, 0x2f00, v0
	global_store_short v[62:63], v82, off
	v_cvt_pk_bf16_f32 v64, v64, s0
	v_lshl_add_u64 v[82:83], v[66:67], 0, v[0:1]
	global_store_short v[82:83], v64, off
	v_or_b32_e32 v0, v89, v86
	v_max_f32_e32 v64, v65, v65
	v_max_f32_e32 v64, 0, v64
	v_lshlrev_b32_e32 v0, 7, v0
	v_mul_f32_e32 v64, v64, v64
	v_and_b32_e32 v0, 0x2f80, v0
	v_cvt_pk_bf16_f32 v86, v64, s0
	v_lshl_add_u64 v[64:65], v[66:67], 0, v[0:1]
	v_max_f32_e32 v0, v34, v34
	v_max_f32_e32 v0, 0, v0
	v_mul_f32_e32 v0, v0, v0
	v_cvt_pk_bf16_f32 v0, v0, s0
	global_store_short v[64:65], v86, off
	global_store_short v[68:69], v0, off offset:64
	v_max_f32_e32 v0, v35, v35
	v_max_f32_e32 v0, 0, v0
	v_mul_f32_e32 v0, v0, v0
	v_cvt_pk_bf16_f32 v0, v0, s0
	global_store_short v[50:51], v0, off offset:64
	v_max_f32_e32 v0, v36, v36
	v_max_f32_e32 v0, 0, v0
	v_mul_f32_e32 v0, v0, v0
	v_cvt_pk_bf16_f32 v0, v0, s0
	global_store_short v[70:71], v0, off offset:64
	v_max_f32_e32 v0, v37, v37
	v_max_f32_e32 v0, 0, v0
	v_mul_f32_e32 v0, v0, v0
	v_cvt_pk_bf16_f32 v0, v0, s0
	global_store_short v[52:53], v0, off offset:64
	v_max_f32_e32 v0, v38, v38
	v_max_f32_e32 v0, 0, v0
	v_mul_f32_e32 v0, v0, v0
	v_cvt_pk_bf16_f32 v0, v0, s0
	global_store_short v[72:73], v0, off offset:64
	v_max_f32_e32 v0, v39, v39
	v_max_f32_e32 v0, 0, v0
	v_mul_f32_e32 v0, v0, v0
	v_cvt_pk_bf16_f32 v0, v0, s0
	global_store_short v[54:55], v0, off offset:64
	v_max_f32_e32 v0, v40, v40
	v_max_f32_e32 v0, 0, v0
	v_mul_f32_e32 v0, v0, v0
	v_cvt_pk_bf16_f32 v0, v0, s0
	global_store_short v[74:75], v0, off offset:64
	v_max_f32_e32 v0, v41, v41
	v_max_f32_e32 v0, 0, v0
	v_mul_f32_e32 v0, v0, v0
	v_cvt_pk_bf16_f32 v0, v0, s0
	global_store_short v[56:57], v0, off offset:64
	v_max_f32_e32 v0, v42, v42
	v_max_f32_e32 v0, 0, v0
	v_mul_f32_e32 v0, v0, v0
	v_cvt_pk_bf16_f32 v0, v0, s0
	global_store_short v[76:77], v0, off offset:64
	v_max_f32_e32 v0, v43, v43
	v_max_f32_e32 v0, 0, v0
	v_mul_f32_e32 v0, v0, v0
	v_cvt_pk_bf16_f32 v0, v0, s0
	global_store_short v[58:59], v0, off offset:64
	v_max_f32_e32 v0, v44, v44
	v_max_f32_e32 v0, 0, v0
	v_mul_f32_e32 v0, v0, v0
	v_cvt_pk_bf16_f32 v0, v0, s0
	global_store_short v[78:79], v0, off offset:64
	v_max_f32_e32 v0, v45, v45
	v_max_f32_e32 v0, 0, v0
	v_mul_f32_e32 v0, v0, v0
	v_cvt_pk_bf16_f32 v0, v0, s0
	global_store_short v[60:61], v0, off offset:64
	v_max_f32_e32 v0, v46, v46
	v_max_f32_e32 v0, 0, v0
	v_mul_f32_e32 v0, v0, v0
	v_cvt_pk_bf16_f32 v0, v0, s0
	global_store_short v[80:81], v0, off offset:64
	v_max_f32_e32 v0, v47, v47
	v_max_f32_e32 v0, 0, v0
	v_mul_f32_e32 v0, v0, v0
	v_cvt_pk_bf16_f32 v0, v0, s0
	v_mfma_f32_32x32x16_bf16 v[18:33], v[92:95], v[96:99], v[18:33]
	global_store_short v[62:63], v0, off offset:64
	v_max_f32_e32 v0, v48, v48
	v_max_f32_e32 v0, 0, v0
	v_mul_f32_e32 v0, v0, v0
	v_cvt_pk_bf16_f32 v0, v0, s0
	global_store_short v[82:83], v0, off offset:64
	v_max_f32_e32 v0, v49, v49
	v_max_f32_e32 v0, 0, v0
	v_mul_f32_e32 v0, v0, v0
	v_cvt_pk_bf16_f32 v0, v0, s0
	v_or_b32_e32 v46, 32, v84
	global_store_short v[64:65], v0, off offset:64
	v_or_b32_e32 v0, v85, v46
	v_max_f32_e32 v18, v18, v18
	v_max_f32_e32 v18, 0, v18
	v_lshlrev_b32_e32 v0, 7, v0
	v_mul_f32_e32 v18, v18, v18
	v_and_b32_e32 v0, 0x3200, v0
	v_cvt_pk_bf16_f32 v18, v18, s0
	v_lshl_add_u64 v[34:35], v[66:67], 0, v[0:1]
	v_or_b32_e32 v48, 33, v84
	global_store_short v[34:35], v18, off
	v_or_b32_e32 v0, v85, v48
	v_max_f32_e32 v18, v19, v19
	v_max_f32_e32 v18, 0, v18
	v_lshlrev_b32_e32 v0, 7, v0
	v_mul_f32_e32 v18, v18, v18
	v_and_b32_e32 v0, 0x3280, v0
	v_or_b32_e32 v49, 34, v84
	v_cvt_pk_bf16_f32 v36, v18, s0
	v_lshl_add_u64 v[18:19], v[66:67], 0, v[0:1]
	v_or_b32_e32 v0, v85, v49
	v_max_f32_e32 v20, v20, v20
	v_max_f32_e32 v20, 0, v20
	v_lshlrev_b32_e32 v0, 7, v0
	v_mul_f32_e32 v20, v20, v20
	v_and_b32_e32 v0, 0x3300, v0
	global_store_short v[18:19], v36, off
	v_cvt_pk_bf16_f32 v20, v20, s0
	v_lshl_add_u64 v[36:37], v[66:67], 0, v[0:1]
	v_or_b32_e32 v50, 35, v84
	global_store_short v[36:37], v20, off
	v_or_b32_e32 v0, v85, v50
	v_max_f32_e32 v20, v21, v21
	v_max_f32_e32 v20, 0, v20
	v_lshlrev_b32_e32 v0, 7, v0
	v_mul_f32_e32 v20, v20, v20
	v_and_b32_e32 v0, 0x3380, v0
	v_cvt_pk_bf16_f32 v38, v20, s0
	v_lshl_add_u64 v[20:21], v[66:67], 0, v[0:1]
	v_or_b32_e32 v0, v87, v46
	v_max_f32_e32 v22, v22, v22
	v_max_f32_e32 v22, 0, v22
	v_lshlrev_b32_e32 v0, 7, v0
	v_mul_f32_e32 v22, v22, v22
	v_and_b32_e32 v0, 0x3600, v0
	global_store_short v[20:21], v38, off
	v_cvt_pk_bf16_f32 v22, v22, s0
	v_lshl_add_u64 v[38:39], v[66:67], 0, v[0:1]
	global_store_short v[38:39], v22, off
	v_or_b32_e32 v0, v87, v48
	v_max_f32_e32 v22, v23, v23
	v_max_f32_e32 v22, 0, v22
	v_lshlrev_b32_e32 v0, 7, v0
	v_mul_f32_e32 v22, v22, v22
	v_and_b32_e32 v0, 0x3680, v0
	v_cvt_pk_bf16_f32 v40, v22, s0
	v_lshl_add_u64 v[22:23], v[66:67], 0, v[0:1]
	v_or_b32_e32 v0, v87, v49
	v_max_f32_e32 v24, v24, v24
	v_max_f32_e32 v24, 0, v24
	v_lshlrev_b32_e32 v0, 7, v0
	v_mul_f32_e32 v24, v24, v24
	v_and_b32_e32 v0, 0x3700, v0
	global_store_short v[22:23], v40, off
	v_cvt_pk_bf16_f32 v24, v24, s0
	v_lshl_add_u64 v[40:41], v[66:67], 0, v[0:1]
	global_store_short v[40:41], v24, off
	v_or_b32_e32 v0, v87, v50
	v_max_f32_e32 v24, v25, v25
	v_max_f32_e32 v24, 0, v24
	v_lshlrev_b32_e32 v0, 7, v0
	v_mul_f32_e32 v24, v24, v24
	v_and_b32_e32 v0, 0x3780, v0
	v_cvt_pk_bf16_f32 v42, v24, s0
	v_lshl_add_u64 v[24:25], v[66:67], 0, v[0:1]
	v_or_b32_e32 v0, v88, v46
	v_max_f32_e32 v26, v26, v26
	v_max_f32_e32 v26, 0, v26
	v_lshlrev_b32_e32 v0, 7, v0
	v_mul_f32_e32 v26, v26, v26
	v_and_b32_e32 v0, 0x3a00, v0
	global_store_short v[24:25], v42, off
	v_cvt_pk_bf16_f32 v26, v26, s0
	v_lshl_add_u64 v[42:43], v[66:67], 0, v[0:1]
	global_store_short v[42:43], v26, off
	v_or_b32_e32 v0, v88, v48
	v_max_f32_e32 v26, v27, v27
	v_max_f32_e32 v26, 0, v26
	v_lshlrev_b32_e32 v0, 7, v0
	v_mul_f32_e32 v26, v26, v26
	v_and_b32_e32 v0, 0x3a80, v0
	v_cvt_pk_bf16_f32 v44, v26, s0
	v_lshl_add_u64 v[26:27], v[66:67], 0, v[0:1]
	v_or_b32_e32 v0, v88, v49
	v_max_f32_e32 v28, v28, v28
	v_max_f32_e32 v28, 0, v28
	v_lshlrev_b32_e32 v0, 7, v0
	v_mul_f32_e32 v28, v28, v28
	v_and_b32_e32 v0, 0x3b00, v0
	global_store_short v[26:27], v44, off
	v_cvt_pk_bf16_f32 v28, v28, s0
	v_lshl_add_u64 v[44:45], v[66:67], 0, v[0:1]
	global_store_short v[44:45], v28, off
	v_or_b32_e32 v0, v88, v50
	v_max_f32_e32 v28, v29, v29
	v_max_f32_e32 v28, 0, v28
	v_lshlrev_b32_e32 v0, 7, v0
	v_mul_f32_e32 v28, v28, v28
	v_and_b32_e32 v0, 0x3b80, v0
	v_cvt_pk_bf16_f32 v47, v28, s0
	v_lshl_add_u64 v[28:29], v[66:67], 0, v[0:1]
	v_or_b32_e32 v0, v89, v46
	v_max_f32_e32 v30, v30, v30
	v_max_f32_e32 v30, 0, v30
	v_lshlrev_b32_e32 v0, 7, v0
	v_mul_f32_e32 v30, v30, v30
	v_and_b32_e32 v0, 0x3e00, v0
	global_store_short v[28:29], v47, off
	v_cvt_pk_bf16_f32 v30, v30, s0
	v_lshl_add_u64 v[46:47], v[66:67], 0, v[0:1]
	global_store_short v[46:47], v30, off
	v_or_b32_e32 v0, v89, v48
	v_max_f32_e32 v30, v31, v31
	v_max_f32_e32 v30, 0, v30
	v_lshlrev_b32_e32 v0, 7, v0
	v_mfma_f32_32x32x16_bf16 v[2:17], v[92:95], v[100:103], v[2:17]
	v_mul_f32_e32 v30, v30, v30
	v_and_b32_e32 v0, 0x3e80, v0
	v_cvt_pk_bf16_f32 v48, v30, s0
	v_lshl_add_u64 v[30:31], v[66:67], 0, v[0:1]
	v_or_b32_e32 v0, v89, v49
	v_max_f32_e32 v32, v32, v32
	v_max_f32_e32 v32, 0, v32
	v_lshlrev_b32_e32 v0, 7, v0
	v_mul_f32_e32 v32, v32, v32
	v_and_b32_e32 v0, 0x3f00, v0
	global_store_short v[30:31], v48, off
	v_cvt_pk_bf16_f32 v32, v32, s0
	v_lshl_add_u64 v[48:49], v[66:67], 0, v[0:1]
	global_store_short v[48:49], v32, off
	v_or_b32_e32 v0, v89, v50
	v_max_f32_e32 v32, v33, v33
	v_max_f32_e32 v32, 0, v32
	v_lshlrev_b32_e32 v0, 7, v0
	v_mul_f32_e32 v32, v32, v32
	v_and_b32_e32 v0, 0x3f80, v0
	v_cvt_pk_bf16_f32 v50, v32, s0
	v_lshl_add_u64 v[32:33], v[66:67], 0, v[0:1]
	v_max_f32_e32 v0, v2, v2
	v_max_f32_e32 v0, 0, v0
	v_mul_f32_e32 v0, v0, v0
	v_cvt_pk_bf16_f32 v0, v0, s0
	global_store_short v[32:33], v50, off
	global_store_short v[34:35], v0, off offset:64
	v_max_f32_e32 v0, v3, v3
	v_max_f32_e32 v0, 0, v0
	v_mul_f32_e32 v0, v0, v0
	v_cvt_pk_bf16_f32 v0, v0, s0
	global_store_short v[18:19], v0, off offset:64
	v_max_f32_e32 v0, v4, v4
	v_max_f32_e32 v0, 0, v0
	v_mul_f32_e32 v0, v0, v0
	v_cvt_pk_bf16_f32 v0, v0, s0
	global_store_short v[36:37], v0, off offset:64
	v_max_f32_e32 v0, v5, v5
	v_max_f32_e32 v0, 0, v0
	v_mul_f32_e32 v0, v0, v0
	v_cvt_pk_bf16_f32 v0, v0, s0
	global_store_short v[20:21], v0, off offset:64
	v_max_f32_e32 v0, v6, v6
	v_max_f32_e32 v0, 0, v0
	v_mul_f32_e32 v0, v0, v0
	v_cvt_pk_bf16_f32 v0, v0, s0
	global_store_short v[38:39], v0, off offset:64
	v_max_f32_e32 v0, v7, v7
	v_max_f32_e32 v0, 0, v0
	v_mul_f32_e32 v0, v0, v0
	v_cvt_pk_bf16_f32 v0, v0, s0
	global_store_short v[22:23], v0, off offset:64
	v_max_f32_e32 v0, v8, v8
	v_max_f32_e32 v0, 0, v0
	v_mul_f32_e32 v0, v0, v0
	v_cvt_pk_bf16_f32 v0, v0, s0
	global_store_short v[40:41], v0, off offset:64
	v_max_f32_e32 v0, v9, v9
	v_max_f32_e32 v0, 0, v0
	v_mul_f32_e32 v0, v0, v0
	v_cvt_pk_bf16_f32 v0, v0, s0
	global_store_short v[24:25], v0, off offset:64
	v_max_f32_e32 v0, v10, v10
	v_max_f32_e32 v0, 0, v0
	v_mul_f32_e32 v0, v0, v0
	v_cvt_pk_bf16_f32 v0, v0, s0
	global_store_short v[42:43], v0, off offset:64
	v_max_f32_e32 v0, v11, v11
	v_max_f32_e32 v0, 0, v0
	v_mul_f32_e32 v0, v0, v0
	v_cvt_pk_bf16_f32 v0, v0, s0
	global_store_short v[26:27], v0, off offset:64
	v_max_f32_e32 v0, v12, v12
	v_max_f32_e32 v0, 0, v0
	v_mul_f32_e32 v0, v0, v0
	v_cvt_pk_bf16_f32 v0, v0, s0
	global_store_short v[44:45], v0, off offset:64
	v_max_f32_e32 v0, v13, v13
	v_max_f32_e32 v0, 0, v0
	v_mul_f32_e32 v0, v0, v0
	v_cvt_pk_bf16_f32 v0, v0, s0
	global_store_short v[28:29], v0, off offset:64
	v_max_f32_e32 v0, v14, v14
	v_max_f32_e32 v0, 0, v0
	v_mul_f32_e32 v0, v0, v0
	v_cvt_pk_bf16_f32 v0, v0, s0
	global_store_short v[46:47], v0, off offset:64
	v_max_f32_e32 v0, v15, v15
	v_max_f32_e32 v0, 0, v0
	v_mul_f32_e32 v0, v0, v0
	v_cvt_pk_bf16_f32 v0, v0, s0
	global_store_short v[30:31], v0, off offset:64
	v_max_f32_e32 v0, v16, v16
	v_max_f32_e32 v0, 0, v0
	v_mul_f32_e32 v0, v0, v0
	v_cvt_pk_bf16_f32 v0, v0, s0
	global_store_short v[48:49], v0, off offset:64
	v_max_f32_e32 v0, v17, v17
	v_max_f32_e32 v0, 0, v0
	v_mul_f32_e32 v0, v0, v0
	v_cvt_pk_bf16_f32 v0, v0, s0
	s_cmp_lt_i32 s5, s2
	global_store_short v[32:33], v0, off offset:64
	s_cmpk_lt_i32 s5, 0x1000
	s_cbranch_scc1 .LBB0_1298
	s_cmpk_ge_i32 s5, 0x1200
	s_cbranch_scc1 .Lph8_done
	s_cmpk_le_i32 s2, 0x1000
	s_cbranch_scc1 .Lph8_done
	v_readlane_b32 s6, v209, 2
	s_cmpk_ge_u32 s6, 0x100
	s_cbranch_scc1 .Lph8_done
	s_and_b32 s7, s6, 7
	s_lshl_b32 s7, s7, 2
	s_lshr_b32 s6, s6, 3
	s_and_b32 s5, s6, 3
	s_or_b32 s7, s7, s5
	s_lshr_b32 s6, s6, 2
	s_lshl_b32 s6, s6, 5
	s_or_b32 s5, s6, s7
	s_addk_i32 s5, 0x1000
	s_lshl_b32 s4, s5, 7
	s_branch .LBB0_1298
.Lph8_done:
	s_mov_b32 s10, 0x8000
	s_mov_b32 s34, 0xa000
	s_mov_b32 s35, 0x2b000
	s_mov_b64 s[42:43], s[8:9]

.LBB0_1356:
	s_cmp_gt_u32 s3, 60
	s_cbranch_scc1 .Ldma9_skip_b
	s_add_u32 m0, s32, 0x4000
	s_nop 0
	global_load_lds_dwordx4 v[216:217], off
	s_add_u32 m0, s32, 0x5000
	v_lshl_add_u64 v[216:217], v[234:235], 2, v[216:217]
	global_load_lds_dwordx4 v[218:219], off
	s_add_u32 m0, s32, 0x6000
	v_lshl_add_u64 v[218:219], v[234:235], 2, v[218:219]
	global_load_lds_dwordx4 v[220:221], off
	s_add_u32 m0, s32, 0x7000
	v_lshl_add_u64 v[220:221], v[234:235], 2, v[220:221]
	global_load_lds_dwordx4 v[222:223], off
	s_add_u32 m0, s32, 0xc000
	v_lshl_add_u64 v[222:223], v[234:235], 2, v[222:223]
	global_load_lds_dwordx4 v[224:225], off
	s_add_u32 m0, s32, 0xd000
	v_lshl_add_u64 v[224:225], 32, 2, v[224:225]
	global_load_lds_dwordx4 v[226:227], off
	s_add_u32 m0, s32, 0xe000
	v_lshl_add_u64 v[226:227], 32, 2, v[226:227]
	global_load_lds_dwordx4 v[228:229], off
	s_add_u32 m0, s32, 0xf000
	v_lshl_add_u64 v[228:229], 32, 2, v[228:229]
	global_load_lds_dwordx4 v[230:231], off
	v_lshl_add_u64 v[230:231], 32, 2, v[230:231]
	s_waitcnt vmcnt(8)
	s_branch .Ldma9_join_b

.Ldma9_join_b:
	s_barrier
	s_add_i32 s3, s3, 2
	v_lshl_add_u64 v[134:135], v[134:135], 0, s[28:29]
	s_andn2_b64 vcc, exec, s[4:5]
	v_lshl_add_u64 v[136:137], v[136:137], 0, s[30:31]
	s_cbranch_vccz .LBB0_1354
.LBB0_1357:
	v_add_u32_e32 v153, v147, v148
	v_add_u32_e32 v155, v147, v150
	v_add_u32_e32 v154, v149, v148
	ds_read_b128 v[138:141], v153
	ds_read_b128 v[158:161], v153 offset:4096
	ds_read_b128 v[162:165], v154 offset:32768
	ds_read_b128 v[166:169], v154 offset:36864
	v_add_u32_e32 v156, v149, v150
	ds_read_b128 v[182:185], v155
	ds_read_b128 v[186:189], v155 offset:4096
	ds_read_b128 v[190:193], v156 offset:32768
	ds_read_b128 v[194:197], v156 offset:36864
	s_waitcnt lgkmcnt(5)
	v_mfma_f32_32x32x16_bf16 v[50:65], v[138:141], v[162:165], v[50:65]
	s_waitcnt lgkmcnt(4)
	v_mfma_f32_32x32x16_bf16 v[18:33], v[138:141], v[166:169], v[18:33]
	v_mfma_f32_32x32x16_bf16 v[34:49], v[158:161], v[162:165], v[34:49]
	v_mfma_f32_32x32x16_bf16 v[2:17], v[158:161], v[166:169], v[2:17]
	v_add_u32_e32 v157, v147, v151
	v_add_u32_e32 v158, v149, v151
	ds_read_b128 v[138:141], v157
	ds_read_b128 v[162:165], v157 offset:4096
	ds_read_b128 v[166:169], v158 offset:32768
	ds_read_b128 v[198:201], v158 offset:36864
	s_waitcnt lgkmcnt(5)
	v_mfma_f32_32x32x16_bf16 v[50:65], v[182:185], v[190:193], v[50:65]
	s_waitcnt lgkmcnt(4)
	v_mfma_f32_32x32x16_bf16 v[18:33], v[182:185], v[194:197], v[18:33]
	v_mfma_f32_32x32x16_bf16 v[34:49], v[186:189], v[190:193], v[34:49]
	v_mfma_f32_32x32x16_bf16 v[2:17], v[186:189], v[194:197], v[2:17]
	v_add_u32_e32 v159, v147, v152
	v_add_u32_e32 v160, v149, v152
	ds_read_b128 v[182:185], v159
	ds_read_b128 v[186:189], v159 offset:4096
	ds_read_b128 v[190:193], v160 offset:32768
	ds_read_b128 v[194:197], v160 offset:36864
	s_waitcnt lgkmcnt(5)
	v_mfma_f32_32x32x16_bf16 v[50:65], v[138:141], v[166:169], v[50:65]
	s_cmp_gt_u32 s3, 60
	s_waitcnt lgkmcnt(0)
	s_barrier
	v_mfma_f32_32x32x16_bf16 v[18:33], v[138:141], v[198:201], v[18:33]
	v_lshl_add_u64 v[140:141], v[134:135], 0, v[0:1]
	v_lshl_add_u64 v[138:139], v[136:137], 0, v[0:1]
	v_mfma_f32_32x32x16_bf16 v[34:49], v[162:165], v[166:169], v[34:49]
	v_mfma_f32_32x32x16_bf16 v[2:17], v[162:165], v[198:201], v[2:17]
	v_mfma_f32_32x32x16_bf16 v[50:65], v[182:185], v[190:193], v[50:65]
	v_mfma_f32_32x32x16_bf16 v[18:33], v[182:185], v[194:197], v[18:33]
	v_mfma_f32_32x32x16_bf16 v[34:49], v[186:189], v[190:193], v[34:49]
	v_mfma_f32_32x32x16_bf16 v[2:17], v[186:189], v[194:197], v[2:17]
	s_cbranch_scc1 .LBB0_1359
	v_add_co_u32_e32 v66, vcc, 0xc000, v140
	s_nop 1
	v_addc_co_u32_e32 v67, vcc, 0, v141, vcc
	v_add_co_u32_e32 v70, vcc, 0xd000, v140
	s_nop 1
	v_addc_co_u32_e32 v71, vcc, 0, v141, vcc
	v_add_co_u32_e32 v74, vcc, 0x40000, v138
	s_nop 0
	v_addc_co_u32_e32 v75, vcc, 0, v139, vcc
	v_add_co_u32_e32 v78, vcc, 0xe000, v140
	s_nop 0
	v_addc_co_u32_e32 v79, vcc, 0, v141, vcc
	v_add_co_u32_e32 v94, vcc, 0x80000, v138
	s_nop 0
	v_addc_co_u32_e32 v95, vcc, 0, v139, vcc
	v_add_co_u32_e32 v98, vcc, 0xf000, v140
	s_nop 0
	v_addc_co_u32_e32 v99, vcc, 0, v141, vcc
	v_add_co_u32_e32 v110, vcc, 0xc0000, v138
	s_nop 0
	v_addc_co_u32_e32 v111, vcc, 0, v139, vcc
	s_nop 0
.LBB0_1359:
	s_cmp_gt_u32 s3, 60
	s_cbranch_scc1 .Ldma9_skip_a
	s_add_u32 m0, s32, 0x0
	s_nop 0
	global_load_lds_dwordx4 v[216:217], off
	s_add_u32 m0, s32, 0x1000
	v_lshl_add_u64 v[216:217], v[234:235], 2, v[216:217]
	global_load_lds_dwordx4 v[218:219], off
	s_add_u32 m0, s32, 0x2000
	v_lshl_add_u64 v[218:219], v[234:235], 2, v[218:219]
	global_load_lds_dwordx4 v[220:221], off
	s_add_u32 m0, s32, 0x3000
	v_lshl_add_u64 v[220:221], v[234:235], 2, v[220:221]
	global_load_lds_dwordx4 v[222:223], off
	s_add_u32 m0, s32, 0x8000
	v_lshl_add_u64 v[222:223], v[234:235], 2, v[222:223]
	global_load_lds_dwordx4 v[224:225], off
	s_add_u32 m0, s32, 0x9000
	v_lshl_add_u64 v[224:225], 32, 2, v[224:225]
	global_load_lds_dwordx4 v[226:227], off
	s_add_u32 m0, s32, 0xa000
	v_lshl_add_u64 v[226:227], 32, 2, v[226:227]
	global_load_lds_dwordx4 v[228:229], off
	s_add_u32 m0, s32, 0xb000
	v_lshl_add_u64 v[228:229], 32, 2, v[228:229]
	global_load_lds_dwordx4 v[230:231], off
	v_lshl_add_u64 v[230:231], 32, 2, v[230:231]
	s_waitcnt vmcnt(8)
	s_branch .Ldma9_join_a

.Ldma9_join_a:
	s_barrier
	ds_read_b128 v[162:165], v153 offset:16384
	ds_read_b128 v[166:169], v153 offset:20480
	ds_read_b128 v[182:185], v154 offset:49152
	ds_read_b128 v[186:189], v154 offset:53248
	ds_read_b128 v[190:193], v155 offset:16384
	ds_read_b128 v[194:197], v155 offset:20480
	ds_read_b128 v[198:201], v156 offset:49152
	ds_read_b128 v[202:205], v156 offset:53248
	s_waitcnt lgkmcnt(5)
	v_mfma_f32_32x32x16_bf16 v[50:65], v[162:165], v[182:185], v[50:65]
	s_waitcnt lgkmcnt(4)
	v_mfma_f32_32x32x16_bf16 v[18:33], v[162:165], v[186:189], v[18:33]
	v_mfma_f32_32x32x16_bf16 v[34:49], v[166:169], v[182:185], v[34:49]
	v_mfma_f32_32x32x16_bf16 v[2:17], v[166:169], v[186:189], v[2:17]
	ds_read_b128 v[162:165], v157 offset:16384
	ds_read_b128 v[154:157], v157 offset:20480
	ds_read_b128 v[166:169], v158 offset:49152
	ds_read_b128 v[182:185], v158 offset:53248
	s_waitcnt lgkmcnt(5)
	v_mfma_f32_32x32x16_bf16 v[50:65], v[190:193], v[198:201], v[50:65]
	s_waitcnt lgkmcnt(4)
	v_mfma_f32_32x32x16_bf16 v[18:33], v[190:193], v[202:205], v[18:33]
	v_mfma_f32_32x32x16_bf16 v[34:49], v[194:197], v[198:201], v[34:49]
	v_mfma_f32_32x32x16_bf16 v[2:17], v[194:197], v[202:205], v[2:17]
	ds_read_b128 v[186:189], v159 offset:16384
	ds_read_b128 v[190:193], v159 offset:20480
	ds_read_b128 v[194:197], v160 offset:49152
	ds_read_b128 v[158:161], v160 offset:53248
	s_waitcnt lgkmcnt(5)
	v_mfma_f32_32x32x16_bf16 v[50:65], v[162:165], v[166:169], v[50:65]
	s_cmp_gt_u32 s3, 61
	s_cselect_b64 s[4:5], -1, 0
	s_and_b64 vcc, exec, s[4:5]
	s_waitcnt lgkmcnt(4)
	v_mfma_f32_32x32x16_bf16 v[18:33], v[162:165], v[182:185], v[18:33]
	v_mfma_f32_32x32x16_bf16 v[34:49], v[154:157], v[166:169], v[34:49]
	v_mfma_f32_32x32x16_bf16 v[2:17], v[154:157], v[182:185], v[2:17]
	s_waitcnt lgkmcnt(1)
	v_mfma_f32_32x32x16_bf16 v[50:65], v[186:189], v[194:197], v[50:65]
	s_waitcnt lgkmcnt(0)
	v_mfma_f32_32x32x16_bf16 v[18:33], v[186:189], v[158:161], v[18:33]
	v_mfma_f32_32x32x16_bf16 v[34:49], v[190:193], v[194:197], v[34:49]
	v_mfma_f32_32x32x16_bf16 v[2:17], v[190:193], v[158:161], v[2:17]
	s_cbranch_vccnz .LBB0_1361
.LBB0_1361:
	s_cmp_gt_u32 s3, 59
	s_waitcnt lgkmcnt(0)
	s_barrier
	s_cbranch_scc1 .LBB0_1356
	v_add_co_u32_e32 v82, vcc, 0x10000, v140
	s_nop 1
	v_addc_co_u32_e32 v83, vcc, 0, v141, vcc
	v_add_co_u32_e32 v84, vcc, 0x11000, v140
	s_nop 1
	v_addc_co_u32_e32 v85, vcc, 0, v141, vcc
	v_add_co_u32_e32 v90, vcc, 0x40000, v138
	s_nop 0
	v_addc_co_u32_e32 v91, vcc, 0, v139, vcc
	v_add_co_u32_e32 v102, vcc, 0x12000, v140
	s_nop 0
	v_addc_co_u32_e32 v103, vcc, 0, v141, vcc
	v_add_co_u32_e32 v114, vcc, 0x80000, v138
	s_nop 0
	v_addc_co_u32_e32 v115, vcc, 0, v139, vcc
	v_add_co_u32_e32 v118, vcc, 0x13000, v140
	s_nop 0
	v_addc_co_u32_e32 v119, vcc, 0, v141, vcc
	v_add_co_u32_e32 v126, vcc, 0xc0000, v138
	s_nop 0
	v_addc_co_u32_e32 v127, vcc, 0, v139, vcc
	s_nop 0
	s_branch .LBB0_1356
